# LDS-DMA loads in all GEMM K-loops use SGPR-base + 32-bit VGPR offset (SALU for the +K-tile bases): removes ~11 64-bit VALU adds per 2 K-tiles from the load segments that contended with the partner wav
# speedup vs baseline: 1.0014x; 1.0014x over previous
; #define PG8_STAGE(bufoff, gbase, voff) do { _Pragma("unroll") for (int _i = 0; _i < 2; ++_i) \
;         __builtin_amdgcn_global_load_lds((const unsigned*)((const char*)(gbase) + (voff)[_i]), (PG8_LAS unsigned*)(lds + (bufoff) + ldsw + _i * 8192), 16, 0, 0); } while (0)
; #define PG8_LDA(dst, b, h) do { _Pragma("unroll") for (int m = 0; m < 4; ++m) _Pragma("unroll") for (int k = 0; k < 2; ++k) dst[m][k] = *(const PG8_LAS bf16x8*)(lds + PG8_SA(b, h) + aoff + m * 2048 + k * 1024); } while (0)
; #define PG8_LDB(dst, b, h) do { _Pragma("unroll") for (int n = 0; n < 2; ++n) _Pragma("unroll") for (int k = 0; k < 2; ++k) dst[n][k] = *(const PG8_LAS bf16x8*)(lds + PG8_SB(b, h) + boff + n * 2048 + k * 1024); } while (0)
; #define PG8_WAIT_V(n) asm volatile("s_waitcnt vmcnt(" #n ")" ::: "memory")
; #define PG8_WAIT_L(n) asm volatile("s_waitcnt lgkmcnt(" #n ")" ::: "memory")
; #define PG8_BAR __builtin_amdgcn_s_barrier()
; #define PG8_SCHED __builtin_amdgcn_sched_barrier(0)
;     ...
;             const char* a1 = cA + (size_t)(t + 1) * kstep;
;             const char* a2 = last ? nA : cA + (size_t)(t + 2) * kstep; const char* b2 = last ? nB : cB + (size_t)(t + 2) * kstep;
;             const char* a3 = a2 + kstep; const char* b3 = b2 + kstep;
;             if (last && has_next) S.a_ready(nxt);
;             if constexpr (SP2) {
;             PG8_LDB(B0, 0, 0); PG8_LDB(B1, 0, 1); PG8_SCHED; PG8_LDA(At, 0, 0); PG8_STAGE(PG8_SA(1, 1), a1 + hstepA, voffA);
;             PG8_WAIT_V(8); PG8_WAIT_L(0); PG8_BAR; PG8_MMA(0, 0, At, B0); PG8_MMA(0, 1, At, B1); PG8_BAR; PG8_SCHED;
;             PG8_LDA(At, 0, 1); PG8_STAGE(PG8_SB(0, 0), b2, voffB); PG8_STAGE(PG8_SB(0, 1), b2 + hstepB, voffB); PG8_STAGE(PG8_SA(0, 0), a2, voffA);
;             PG8_WAIT_V(8); PG8_WAIT_L(0); PG8_BAR; PG8_MMA(1, 0, At, B0); PG8_MMA(1, 1, At, B1); PG8_BAR; PG8_SCHED;
.LBB0_538:
	s_add_u32 s63, s64, 0xfffc0080
	s_addc_u32 s66, s65, -1
	s_add_i32 s68, 0, 0x10000
	s_cmp_eq_u32 s57, 12
	s_cselect_b32 s75, s6, s66
	s_cselect_b32 s74, s15, s63
	v_add_u32_e32 v157, s68, v153
	s_cselect_b32 s67, s34, s55
	s_cselect_b32 s66, s35, s45
	s_add_i32 s63, 0, 0x14000
	ds_read_b128 v[142:145], v157
	ds_read_b128 v[146:149], v157 offset:1024
	ds_read_b128 v[158:161], v157 offset:2048
	ds_read_b128 v[186:189], v157 offset:3072
	v_add_u32_e32 v157, s63, v153
	ds_read_b128 v[190:193], v157
	ds_read_b128 v[194:197], v157 offset:1024
	ds_read_b128 v[198:201], v157 offset:2048
	ds_read_b128 v[202:205], v157 offset:3072
	s_add_i32 m0, s81, 0xc000
	ds_read_b128 v[206:209], v156
	ds_read_b128 v[210:213], v156 offset:1024
	ds_read_b128 v[214:217], v156 offset:2048
	ds_read_b128 v[218:221], v156 offset:3072
	ds_read_b128 v[222:225], v156 offset:4096
	ds_read_b128 v[234:237], v156 offset:5120
	ds_read_b128 v[238:241], v156 offset:6144
	ds_read_b128 v[242:245], v156 offset:7168
	global_load_lds_dwordx4 v138, s[64:65]
	s_add_i32 m0, s81, 0xe000
	s_nop 0
	global_load_lds_dwordx4 v140, s[64:65]
	s_waitcnt vmcnt(8)
	s_waitcnt lgkmcnt(0)
	s_barrier
	s_setprio 1
	v_mfma_i32_16x16x64_i8 v[128:131], v[142:145], v[206:209], v[128:131]
	v_mfma_i32_16x16x64_i8 v[120:123], v[158:161], v[206:209], v[120:123]
	v_mfma_i32_16x16x64_i8 v[112:115], v[142:145], v[214:217], v[112:115]
	v_mfma_i32_16x16x64_i8 v[104:107], v[158:161], v[214:217], v[104:107]
	v_mfma_i32_16x16x64_i8 v[96:99], v[142:145], v[222:225], v[96:99]
	v_mfma_i32_16x16x64_i8 v[88:91], v[158:161], v[222:225], v[88:91]
	v_mfma_i32_16x16x64_i8 v[80:83], v[142:145], v[238:241], v[80:83]
	v_mfma_i32_16x16x64_i8 v[72:75], v[158:161], v[238:241], v[72:75]
	v_mfma_i32_16x16x64_i8 v[128:131], v[146:149], v[210:213], v[128:131]
	v_mfma_i32_16x16x64_i8 v[120:123], v[186:189], v[210:213], v[120:123]
	v_mfma_i32_16x16x64_i8 v[112:115], v[146:149], v[218:221], v[112:115]
	v_mfma_i32_16x16x64_i8 v[104:107], v[186:189], v[218:221], v[104:107]
	v_mfma_i32_16x16x64_i8 v[96:99], v[146:149], v[234:237], v[96:99]
	v_mfma_i32_16x16x64_i8 v[88:91], v[186:189], v[234:237], v[88:91]
	v_mfma_i32_16x16x64_i8 v[80:83], v[146:149], v[242:245], v[80:83]
	v_mfma_i32_16x16x64_i8 v[72:75], v[186:189], v[242:245], v[72:75]
	v_mfma_i32_16x16x64_i8 v[124:127], v[190:193], v[206:209], v[124:127]
	v_mfma_i32_16x16x64_i8 v[116:119], v[198:201], v[206:209], v[116:119]
	v_mfma_i32_16x16x64_i8 v[108:111], v[190:193], v[214:217], v[108:111]
	v_mfma_i32_16x16x64_i8 v[100:103], v[198:201], v[214:217], v[100:103]
	v_mfma_i32_16x16x64_i8 v[92:95], v[190:193], v[222:225], v[92:95]
	v_mfma_i32_16x16x64_i8 v[84:87], v[198:201], v[222:225], v[84:87]
	v_mfma_i32_16x16x64_i8 v[76:79], v[190:193], v[238:241], v[76:79]
	v_mfma_i32_16x16x64_i8 v[68:71], v[198:201], v[238:241], v[68:71]
	v_mfma_i32_16x16x64_i8 v[124:127], v[194:197], v[210:213], v[124:127]
	v_mfma_i32_16x16x64_i8 v[116:119], v[202:205], v[210:213], v[116:119]
	v_mfma_i32_16x16x64_i8 v[108:111], v[194:197], v[218:221], v[108:111]
	v_mfma_i32_16x16x64_i8 v[100:103], v[202:205], v[218:221], v[100:103]
	v_mfma_i32_16x16x64_i8 v[92:95], v[194:197], v[234:237], v[92:95]
	v_mfma_i32_16x16x64_i8 v[84:87], v[202:205], v[234:237], v[84:87]
	v_mfma_i32_16x16x64_i8 v[76:79], v[194:197], v[242:245], v[76:79]
	v_mfma_i32_16x16x64_i8 v[68:71], v[202:205], v[242:245], v[68:71]
	s_setprio 0
	s_barrier
	s_add_i32 s68, s68, s10
	s_mov_b32 m0, s68
	ds_read_b128 v[206:209], v156 offset:16384
	ds_read_b128 v[210:213], v156 offset:17408
	ds_read_b128 v[214:217], v156 offset:18432
	ds_read_b128 v[218:221], v156 offset:19456
	ds_read_b128 v[222:225], v156 offset:20480
	ds_read_b128 v[234:237], v156 offset:21504
	ds_read_b128 v[238:241], v156 offset:22528
	ds_read_b128 v[242:245], v156 offset:23552
	global_load_lds_dwordx4 v34, s[66:67]
	s_add_i32 m0, s68, 0x2000
	s_add_u32 s70, s66, 0x40000
	v_lshl_add_u64 v[226:227], s[66:67], 0, v[136:137]
	s_addc_u32 s71, s67, 0
	s_add_i32 s63, s63, s10
	global_load_lds_dwordx4 v136, s[66:67]
	s_mov_b32 m0, s63
	v_lshl_add_u64 v[248:249], s[74:75], 0, v[134:135]
	global_load_lds_dwordx4 v34, s[70:71]
	s_add_i32 m0, s63, 0x2000
	s_nop 0
	global_load_lds_dwordx4 v136, s[70:71]
	v_lshl_add_u64 v[246:247], s[74:75], 0, v[132:133]
	s_mov_b32 m0, s81
	s_nop 0
	global_load_lds_dwordx4 v132, s[74:75]
	s_mov_b32 m0, s82
	s_nop 0
	global_load_lds_dwordx4 v134, s[74:75]
	s_waitcnt vmcnt(8)
	s_waitcnt lgkmcnt(0)
	s_barrier
	s_setprio 1
	v_mfma_i32_16x16x64_i8 v[64:67], v[142:145], v[206:209], v[64:67]
	v_mfma_i32_16x16x64_i8 v[56:59], v[158:161], v[206:209], v[56:59]
	v_mfma_i32_16x16x64_i8 v[48:51], v[142:145], v[214:217], v[48:51]
	v_mfma_i32_16x16x64_i8 v[40:43], v[158:161], v[214:217], v[40:43]
	v_mfma_i32_16x16x64_i8 v[30:33], v[142:145], v[222:225], v[30:33]
	v_mfma_i32_16x16x64_i8 v[22:25], v[158:161], v[222:225], v[22:25]
	v_mfma_i32_16x16x64_i8 v[14:17], v[142:145], v[238:241], v[14:17]
	v_mfma_i32_16x16x64_i8 v[6:9], v[158:161], v[238:241], v[6:9]
	v_mfma_i32_16x16x64_i8 v[64:67], v[146:149], v[210:213], v[64:67]
	v_mfma_i32_16x16x64_i8 v[56:59], v[186:189], v[210:213], v[56:59]
	v_mfma_i32_16x16x64_i8 v[48:51], v[146:149], v[218:221], v[48:51]
	v_mfma_i32_16x16x64_i8 v[40:43], v[186:189], v[218:221], v[40:43]
	v_mfma_i32_16x16x64_i8 v[30:33], v[146:149], v[234:237], v[30:33]
	v_mfma_i32_16x16x64_i8 v[22:25], v[186:189], v[234:237], v[22:25]
	v_mfma_i32_16x16x64_i8 v[14:17], v[146:149], v[242:245], v[14:17]
	v_mfma_i32_16x16x64_i8 v[6:9], v[186:189], v[242:245], v[6:9]
	v_mfma_i32_16x16x64_i8 v[60:63], v[190:193], v[206:209], v[60:63]
	v_mfma_i32_16x16x64_i8 v[52:55], v[198:201], v[206:209], v[52:55]
	v_mfma_i32_16x16x64_i8 v[44:47], v[190:193], v[214:217], v[44:47]
	v_mfma_i32_16x16x64_i8 v[36:39], v[198:201], v[214:217], v[36:39]
	v_mfma_i32_16x16x64_i8 v[26:29], v[190:193], v[222:225], v[26:29]
	v_mfma_i32_16x16x64_i8 v[18:21], v[198:201], v[222:225], v[18:21]
	v_mfma_i32_16x16x64_i8 v[10:13], v[190:193], v[238:241], v[10:13]
	v_mfma_i32_16x16x64_i8 v[2:5], v[198:201], v[238:241], v[2:5]
	v_mfma_i32_16x16x64_i8 v[60:63], v[194:197], v[210:213], v[60:63]
	v_mfma_i32_16x16x64_i8 v[52:55], v[202:205], v[210:213], v[52:55]
	v_mfma_i32_16x16x64_i8 v[44:47], v[194:197], v[218:221], v[44:47]
	v_mfma_i32_16x16x64_i8 v[36:39], v[202:205], v[218:221], v[36:39]
	v_mfma_i32_16x16x64_i8 v[26:29], v[194:197], v[234:237], v[26:29]
	v_mfma_i32_16x16x64_i8 v[18:21], v[202:205], v[234:237], v[18:21]
	v_mfma_i32_16x16x64_i8 v[10:13], v[194:197], v[242:245], v[10:13]
	v_mfma_i32_16x16x64_i8 v[2:5], v[202:205], v[242:245], v[2:5]
	s_setprio 0
	s_barrier
; #define PG8_STAGE(bufoff, gbase, voff) do { _Pragma("unroll") for (int _i = 0; _i < 2; ++_i) \
;         __builtin_amdgcn_global_load_lds((const unsigned*)((const char*)(gbase) + (voff)[_i]), (PG8_LAS unsigned*)(lds + (bufoff) + ldsw + _i * 8192), 16, 0, 0); } while (0)
; #define PG8_LDA(dst, b, h) do { _Pragma("unroll") for (int m = 0; m < 4; ++m) _Pragma("unroll") for (int k = 0; k < 2; ++k) dst[m][k] = *(const PG8_LAS bf16x8*)(lds + PG8_SA(b, h) + aoff + m * 2048 + k * 1024); } while (0)
; #define PG8_LDB(dst, b, h) do { _Pragma("unroll") for (int n = 0; n < 2; ++n) _Pragma("unroll") for (int k = 0; k < 2; ++k) dst[n][k] = *(const PG8_LAS bf16x8*)(lds + PG8_SB(b, h) + boff + n * 2048 + k * 1024); } while (0)
; #define PG8_WAIT_V(n) asm volatile("s_waitcnt vmcnt(" #n ")" ::: "memory")
; #define PG8_WAIT_L(n) asm volatile("s_waitcnt lgkmcnt(" #n ")" ::: "memory")
; #define PG8_BAR __builtin_amdgcn_s_barrier()
; #define PG8_SCHED __builtin_amdgcn_sched_barrier(0)
;     ...
;             PG8_LDB(B0, 1, 0); PG8_LDB(B1, 1, 1); PG8_SCHED; PG8_LDA(At, 1, 0); PG8_STAGE(PG8_SA(0, 1), a2 + hstepA, voffA);
;             PG8_WAIT_V(8); PG8_WAIT_L(0); PG8_BAR; PG8_MMA(0, 0, At, B0); PG8_MMA(0, 1, At, B1); PG8_BAR; PG8_SCHED;
	s_add_i32 s63, 0, 0x18000
	v_add_u32_e32 v157, s63, v153
	s_add_i32 s68, 0, 0x1c000
	ds_read_b128 v[142:145], v157
	ds_read_b128 v[146:149], v157 offset:1024
	ds_read_b128 v[158:161], v157 offset:2048
	ds_read_b128 v[186:189], v157 offset:3072
	v_add_u32_e32 v157, s68, v153
	ds_read_b128 v[190:193], v157
	ds_read_b128 v[194:197], v157 offset:1024
	ds_read_b128 v[198:201], v157 offset:2048
	ds_read_b128 v[202:205], v157 offset:3072
	s_add_u32 s70, s74, 0x40000
	s_addc_u32 s71, s75, 0
	s_mov_b32 m0, s83
	ds_read_b128 v[206:209], v156 offset:32768
	ds_read_b128 v[210:213], v156 offset:33792
	ds_read_b128 v[214:217], v156 offset:34816
	ds_read_b128 v[218:221], v156 offset:35840
	ds_read_b128 v[222:225], v156 offset:36864
	ds_read_b128 v[234:237], v156 offset:37888
	ds_read_b128 v[238:241], v156 offset:38912
	ds_read_b128 v[242:245], v156 offset:39936
	global_load_lds_dwordx4 v132, s[70:71]
	v_lshl_add_u64 v[250:251], s[70:71], 0, v[134:135]
	s_mov_b32 m0, s84
	s_nop 0
	global_load_lds_dwordx4 v134, s[70:71]
	s_waitcnt vmcnt(8)
	s_waitcnt lgkmcnt(0)
	s_barrier
	s_setprio 1
	v_mfma_i32_16x16x64_i8 v[128:131], v[142:145], v[206:209], v[128:131]
	v_mfma_i32_16x16x64_i8 v[120:123], v[158:161], v[206:209], v[120:123]
	v_mfma_i32_16x16x64_i8 v[112:115], v[142:145], v[214:217], v[112:115]
	v_mfma_i32_16x16x64_i8 v[104:107], v[158:161], v[214:217], v[104:107]
	v_mfma_i32_16x16x64_i8 v[96:99], v[142:145], v[222:225], v[96:99]
	v_mfma_i32_16x16x64_i8 v[88:91], v[158:161], v[222:225], v[88:91]
	v_mfma_i32_16x16x64_i8 v[80:83], v[142:145], v[238:241], v[80:83]
	v_mfma_i32_16x16x64_i8 v[72:75], v[158:161], v[238:241], v[72:75]
	v_mfma_i32_16x16x64_i8 v[128:131], v[146:149], v[210:213], v[128:131]
	v_mfma_i32_16x16x64_i8 v[120:123], v[186:189], v[210:213], v[120:123]
	v_mfma_i32_16x16x64_i8 v[112:115], v[146:149], v[218:221], v[112:115]
	v_mfma_i32_16x16x64_i8 v[104:107], v[186:189], v[218:221], v[104:107]
	v_mfma_i32_16x16x64_i8 v[96:99], v[146:149], v[234:237], v[96:99]
	v_mfma_i32_16x16x64_i8 v[88:91], v[186:189], v[234:237], v[88:91]
	v_mfma_i32_16x16x64_i8 v[80:83], v[146:149], v[242:245], v[80:83]
	v_mfma_i32_16x16x64_i8 v[72:75], v[186:189], v[242:245], v[72:75]
	v_mfma_i32_16x16x64_i8 v[124:127], v[190:193], v[206:209], v[124:127]
	v_mfma_i32_16x16x64_i8 v[116:119], v[198:201], v[206:209], v[116:119]
	v_mfma_i32_16x16x64_i8 v[108:111], v[190:193], v[214:217], v[108:111]
	v_mfma_i32_16x16x64_i8 v[100:103], v[198:201], v[214:217], v[100:103]
	v_mfma_i32_16x16x64_i8 v[92:95], v[190:193], v[222:225], v[92:95]
	v_mfma_i32_16x16x64_i8 v[84:87], v[198:201], v[222:225], v[84:87]
	v_mfma_i32_16x16x64_i8 v[76:79], v[190:193], v[238:241], v[76:79]
	v_mfma_i32_16x16x64_i8 v[68:71], v[198:201], v[238:241], v[68:71]
	v_mfma_i32_16x16x64_i8 v[124:127], v[194:197], v[210:213], v[124:127]
	v_mfma_i32_16x16x64_i8 v[116:119], v[202:205], v[210:213], v[116:119]
	v_mfma_i32_16x16x64_i8 v[108:111], v[194:197], v[218:221], v[108:111]
	v_mfma_i32_16x16x64_i8 v[100:103], v[202:205], v[218:221], v[100:103]
	v_mfma_i32_16x16x64_i8 v[92:95], v[194:197], v[234:237], v[92:95]
	v_mfma_i32_16x16x64_i8 v[84:87], v[202:205], v[234:237], v[84:87]
	v_mfma_i32_16x16x64_i8 v[76:79], v[194:197], v[242:245], v[76:79]
	v_mfma_i32_16x16x64_i8 v[68:71], v[202:205], v[242:245], v[68:71]
	s_setprio 0
	s_barrier
; #define PG8_STAGE(bufoff, gbase, voff) do { _Pragma("unroll") for (int _i = 0; _i < 2; ++_i) \
;         __builtin_amdgcn_global_load_lds((const unsigned*)((const char*)(gbase) + (voff)[_i]), (PG8_LAS unsigned*)(lds + (bufoff) + ldsw + _i * 8192), 16, 0, 0); } while (0)
; #define PG8_LDA(dst, b, h) do { _Pragma("unroll") for (int m = 0; m < 4; ++m) _Pragma("unroll") for (int k = 0; k < 2; ++k) dst[m][k] = *(const PG8_LAS bf16x8*)(lds + PG8_SA(b, h) + aoff + m * 2048 + k * 1024); } while (0)
; #define PG8_WAIT_V(n) asm volatile("s_waitcnt vmcnt(" #n ")" ::: "memory")
; #define PG8_WAIT_L(n) asm volatile("s_waitcnt lgkmcnt(" #n ")" ::: "memory")
;     __device__ __forceinline__ void operator()(const f32x4 (&acc)[2][2][4][2], const Unit& u, int wr, int wc, int fr, int fq) const {
;     ...
;                 float r[8]; const float scr_ = rs ? rs[row0 + ai * HALF + m * 16] * sc : sc;
;     ...
;         for (int t = 0; t < nt; t += 2) {
;             const bool last = (t == nt - 2);
;             const char* a1 = cA + (size_t)(t + 1) * kstep;
;             const char* a2 = last ? nA : cA + (size_t)(t + 2) * kstep; const char* b2 = last ? nB : cB + (size_t)(t + 2) * kstep;
;             const char* a3 = a2 + kstep; const char* b3 = b2 + kstep;
;             if (last && has_next) S.a_ready(nxt);
;             if constexpr (SP2) {
;             PG8_LDB(B0, 0, 0); PG8_LDB(B1, 0, 1); PG8_SCHED; PG8_LDA(At, 0, 0); PG8_STAGE(PG8_SA(1, 1), a1 + hstepA, voffA);
;             PG8_WAIT_V(8); PG8_WAIT_L(0); PG8_BAR; PG8_MMA(0, 0, At, B0); PG8_MMA(0, 1, At, B1); PG8_BAR; PG8_SCHED;
;             PG8_LDA(At, 0, 1); PG8_STAGE(PG8_SB(0, 0), b2, voffB); PG8_STAGE(PG8_SB(0, 1), b2 + hstepB, voffB); PG8_STAGE(PG8_SA(0, 0), a2, voffA);
;             PG8_WAIT_V(8); PG8_WAIT_L(0); PG8_BAR; PG8_MMA(1, 0, At, B0); PG8_MMA(1, 1, At, B1); PG8_BAR; PG8_SCHED;
;             PG8_LDB(B0, 1, 0); PG8_LDB(B1, 1, 1); PG8_SCHED; PG8_LDA(At, 1, 0); PG8_STAGE(PG8_SA(0, 1), a2 + hstepA, voffA);
;             PG8_WAIT_V(8); PG8_WAIT_L(0); PG8_BAR; PG8_MMA(0, 0, At, B0); PG8_MMA(0, 1, At, B1); PG8_BAR; PG8_SCHED;
;             PG8_LDA(At, 1, 1); PG8_STAGE(PG8_SB(1, 0), b3, voffB); PG8_STAGE(PG8_SB(1, 1), b3 + hstepB, voffB); PG8_STAGE(PG8_SA(1, 0), a3, voffA);
;             PG8_WAIT_V(8); PG8_WAIT_L(0); PG8_BAR; PG8_MMA(1, 0, At, B0); PG8_MMA(1, 1, At, B1); PG8_BAR; PG8_SCHED;
	s_add_i32 s63, s63, s10
	s_mov_b32 m0, s63
	ds_read_b128 v[206:209], v156 offset:49152
	ds_read_b128 v[210:213], v156 offset:50176
	ds_read_b128 v[214:217], v156 offset:51200
	ds_read_b128 v[218:221], v156 offset:52224
	ds_read_b128 v[222:225], v156 offset:53248
	ds_read_b128 v[234:237], v156 offset:54272
	ds_read_b128 v[238:241], v156 offset:55296
	ds_read_b128 v[242:245], v156 offset:56320
	s_add_u32 s98, s66, 0x80
	s_addc_u32 s99, s67, 0
	global_load_lds_dwordx4 v34, s[98:99]
	s_add_i32 m0, s63, 0x2000
	s_add_u32 s66, s66, 0x40080
	s_addc_u32 s67, s67, 0
	s_add_i32 s63, s68, s10
	s_add_u32 s98, s66, 0xfffc0000
	s_addc_u32 s99, s67, -1
	global_load_lds_dwordx4 v136, s[98:99]
	s_mov_b32 m0, s63
	s_nop 0
	global_load_lds_dwordx4 v34, s[66:67]
	s_add_i32 m0, s63, 0x2000
	s_nop 0
	global_load_lds_dwordx4 v136, s[66:67]
	s_mov_b32 m0, s86
	s_nop 0
	s_add_u32 s98, s74, 0x80
	s_addc_u32 s99, s75, 0
	global_load_lds_dwordx4 v132, s[98:99]
	v_lshl_add_u64 v[162:163], v[248:249], 0, s[22:23]
	s_mov_b32 m0, s87
	s_nop 0
	s_add_u32 s98, s74, 0x80
	s_addc_u32 s99, s75, 0
	global_load_lds_dwordx4 v134, s[98:99]
	s_waitcnt vmcnt(8)
	s_waitcnt lgkmcnt(0)
	s_barrier
	s_setprio 1
	v_mfma_i32_16x16x64_i8 v[64:67], v[142:145], v[206:209], v[64:67]
	v_mfma_i32_16x16x64_i8 v[56:59], v[158:161], v[206:209], v[56:59]
	v_mfma_i32_16x16x64_i8 v[48:51], v[142:145], v[214:217], v[48:51]
	v_mfma_i32_16x16x64_i8 v[40:43], v[158:161], v[214:217], v[40:43]
	v_mfma_i32_16x16x64_i8 v[30:33], v[142:145], v[222:225], v[30:33]
	v_mfma_i32_16x16x64_i8 v[22:25], v[158:161], v[222:225], v[22:25]
	v_mfma_i32_16x16x64_i8 v[14:17], v[142:145], v[238:241], v[14:17]
	v_mfma_i32_16x16x64_i8 v[6:9], v[158:161], v[238:241], v[6:9]
	v_mfma_i32_16x16x64_i8 v[64:67], v[146:149], v[210:213], v[64:67]
	v_mfma_i32_16x16x64_i8 v[56:59], v[186:189], v[210:213], v[56:59]
	v_mfma_i32_16x16x64_i8 v[48:51], v[146:149], v[218:221], v[48:51]
	v_mfma_i32_16x16x64_i8 v[40:43], v[186:189], v[218:221], v[40:43]
	v_mfma_i32_16x16x64_i8 v[30:33], v[146:149], v[234:237], v[30:33]
	v_mfma_i32_16x16x64_i8 v[22:25], v[186:189], v[234:237], v[22:25]
	v_mfma_i32_16x16x64_i8 v[14:17], v[146:149], v[242:245], v[14:17]
	v_mfma_i32_16x16x64_i8 v[6:9], v[186:189], v[242:245], v[6:9]
	v_mfma_i32_16x16x64_i8 v[60:63], v[190:193], v[206:209], v[60:63]
	v_mfma_i32_16x16x64_i8 v[52:55], v[198:201], v[206:209], v[52:55]
	v_mfma_i32_16x16x64_i8 v[44:47], v[190:193], v[214:217], v[44:47]
	v_mfma_i32_16x16x64_i8 v[36:39], v[198:201], v[214:217], v[36:39]
	v_mfma_i32_16x16x64_i8 v[26:29], v[190:193], v[222:225], v[26:29]
	v_mfma_i32_16x16x64_i8 v[18:21], v[198:201], v[222:225], v[18:21]
	v_mfma_i32_16x16x64_i8 v[10:13], v[190:193], v[238:241], v[10:13]
	v_mfma_i32_16x16x64_i8 v[2:5], v[198:201], v[238:241], v[2:5]
	v_mfma_i32_16x16x64_i8 v[60:63], v[194:197], v[210:213], v[60:63]
	v_mfma_i32_16x16x64_i8 v[52:55], v[202:205], v[210:213], v[52:55]
	v_mfma_i32_16x16x64_i8 v[44:47], v[194:197], v[218:221], v[44:47]
	v_mfma_i32_16x16x64_i8 v[36:39], v[202:205], v[218:221], v[36:39]
	v_mfma_i32_16x16x64_i8 v[26:29], v[194:197], v[234:237], v[26:29]
	v_mfma_i32_16x16x64_i8 v[18:21], v[202:205], v[234:237], v[18:21]
	v_mfma_i32_16x16x64_i8 v[10:13], v[194:197], v[242:245], v[10:13]
	v_mfma_i32_16x16x64_i8 v[2:5], v[202:205], v[242:245], v[2:5]
	s_setprio 0
	s_barrier
	s_add_i32 s57, s57, 2
	s_add_u32 s64, s64, 0x100
	s_addc_u32 s65, s65, 0
	s_add_u32 s45, s45, 0x100
	s_addc_u32 s55, s55, 0
	s_cmp_gt_u32 s57, 13
	s_cbranch_scc0 .LBB0_538
	v_lshl_add_u32 v144, s62, 8, v152
	v_ashrrev_i32_e32 v145, 31, v144
	v_lshl_add_u64 v[146:147], v[144:145], 2, s[50:51]
	global_load_dword v186, v[146:147], off
	global_load_dword v187, v[146:147], off offset:64
	global_load_dword v188, v[146:147], off offset:128
	global_load_dword v189, v[146:147], off offset:192
	global_load_dword v190, v[146:147], off offset:512
	global_load_dword v191, v[146:147], off offset:576
	global_load_dword v192, v[146:147], off offset:640
	global_load_dword v193, v[146:147], off offset:704
	s_and_b64 vcc, exec, s[52:53]
	s_cbranch_vccz .LBB0_541
	s_barrier

; #define PG8_STAGE(bufoff, gbase, voff) do { _Pragma("unroll") for (int _i = 0; _i < 2; ++_i) \
;         __builtin_amdgcn_global_load_lds((const unsigned*)((const char*)(gbase) + (voff)[_i]), (PG8_LAS unsigned*)(lds + (bufoff) + ldsw + _i * 8192), 16, 0, 0); } while (0)
; #define PG8_LDA(dst, b, h) do { _Pragma("unroll") for (int m = 0; m < 4; ++m) _Pragma("unroll") for (int k = 0; k < 2; ++k) dst[m][k] = *(const PG8_LAS bf16x8*)(lds + PG8_SA(b, h) + aoff + m * 2048 + k * 1024); } while (0)
; #define PG8_LDB(dst, b, h) do { _Pragma("unroll") for (int n = 0; n < 2; ++n) _Pragma("unroll") for (int k = 0; k < 2; ++k) dst[n][k] = *(const PG8_LAS bf16x8*)(lds + PG8_SB(b, h) + boff + n * 2048 + k * 1024); } while (0)
; #define PG8_WAIT_V(n) asm volatile("s_waitcnt vmcnt(" #n ")" ::: "memory")
; #define PG8_WAIT_L(n) asm volatile("s_waitcnt lgkmcnt(" #n ")" ::: "memory")
; #define PG8_BAR __builtin_amdgcn_s_barrier()
; #define PG8_SCHED __builtin_amdgcn_sched_barrier(0)
;     ...
;             const char* a1 = cA + (size_t)(t + 1) * kstep;
;             const char* a2 = last ? nA : cA + (size_t)(t + 2) * kstep; const char* b2 = last ? nB : cB + (size_t)(t + 2) * kstep;
;             const char* a3 = a2 + kstep; const char* b3 = b2 + kstep;
;             if (last && has_next) S.a_ready(nxt);
;             if constexpr (SP2) {
;             PG8_LDB(B0, 0, 0); PG8_LDB(B1, 0, 1); PG8_SCHED; PG8_LDA(At, 0, 0); PG8_STAGE(PG8_SA(1, 1), a1 + hstepA, voffA);
;             PG8_WAIT_V(8); PG8_WAIT_L(0); PG8_BAR; PG8_MMA(0, 0, At, B0); PG8_MMA(0, 1, At, B1); PG8_BAR; PG8_SCHED;
;             PG8_LDA(At, 0, 1); PG8_STAGE(PG8_SB(0, 0), b2, voffB); PG8_STAGE(PG8_SB(0, 1), b2 + hstepB, voffB); PG8_STAGE(PG8_SA(0, 0), a2, voffA);
;             PG8_WAIT_V(8); PG8_WAIT_L(0); PG8_BAR; PG8_MMA(1, 0, At, B0); PG8_MMA(1, 1, At, B1); PG8_BAR; PG8_SCHED;
.LBB0_608:
	s_add_u32 s52, s50, 0xfff80080
	s_addc_u32 s53, s51, -1
	s_add_i32 s63, 0, 0x10000
	s_cmp_eq_u32 s62, 28
	s_cselect_b32 s55, s37, s53
	s_cselect_b32 s54, s58, s52
	v_add_u32_e32 v142, s63, v145
	s_cselect_b32 s53, s31, s61
	s_cselect_b32 s52, s59, s60
	s_add_i32 s66, 0, 0x14000
	ds_read_b128 v[148:151], v142
	ds_read_b128 v[152:155], v142 offset:1024
	ds_read_b128 v[156:159], v142 offset:2048
	ds_read_b128 v[160:163], v142 offset:3072
	v_add_u32_e32 v142, s66, v145
	ds_read_b128 v[186:189], v142
	ds_read_b128 v[190:193], v142 offset:1024
	ds_read_b128 v[194:197], v142 offset:2048
	ds_read_b128 v[198:201], v142 offset:3072
	s_add_i32 m0, s12, 0xc000
	ds_read_b128 v[202:205], v147
	ds_read_b128 v[206:209], v147 offset:1024
	ds_read_b128 v[210:213], v147 offset:2048
	ds_read_b128 v[214:217], v147 offset:3072
	ds_read_b128 v[218:221], v147 offset:4096
	ds_read_b128 v[222:225], v147 offset:5120
	ds_read_b128 v[234:237], v147 offset:6144
	ds_read_b128 v[238:241], v147 offset:7168
	global_load_lds_dwordx4 v138, s[50:51]
	s_add_i32 m0, s12, 0xe000
	s_nop 0
	global_load_lds_dwordx4 v140, s[50:51]
	s_waitcnt vmcnt(8)
	s_waitcnt lgkmcnt(0)
	s_barrier
	s_setprio 1
	v_mfma_f32_16x16x32_bf16 v[128:131], v[148:151], v[202:205], v[128:131]
	v_mfma_f32_16x16x32_bf16 v[124:127], v[156:159], v[202:205], v[124:127]
	v_mfma_f32_16x16x32_bf16 v[112:115], v[148:151], v[210:213], v[112:115]
	v_mfma_f32_16x16x32_bf16 v[108:111], v[156:159], v[210:213], v[108:111]
	v_mfma_f32_16x16x32_bf16 v[96:99], v[148:151], v[218:221], v[96:99]
	v_mfma_f32_16x16x32_bf16 v[92:95], v[156:159], v[218:221], v[92:95]
	v_mfma_f32_16x16x32_bf16 v[80:83], v[148:151], v[234:237], v[80:83]
	v_mfma_f32_16x16x32_bf16 v[76:79], v[156:159], v[234:237], v[76:79]
	v_mfma_f32_16x16x32_bf16 v[128:131], v[152:155], v[206:209], v[128:131]
	v_mfma_f32_16x16x32_bf16 v[124:127], v[160:163], v[206:209], v[124:127]
	v_mfma_f32_16x16x32_bf16 v[112:115], v[152:155], v[214:217], v[112:115]
	v_mfma_f32_16x16x32_bf16 v[108:111], v[160:163], v[214:217], v[108:111]
	v_mfma_f32_16x16x32_bf16 v[96:99], v[152:155], v[222:225], v[96:99]
	v_mfma_f32_16x16x32_bf16 v[92:95], v[160:163], v[222:225], v[92:95]
	v_mfma_f32_16x16x32_bf16 v[80:83], v[152:155], v[238:241], v[80:83]
	v_mfma_f32_16x16x32_bf16 v[76:79], v[160:163], v[238:241], v[76:79]
	v_mfma_f32_16x16x32_bf16 v[120:123], v[186:189], v[202:205], v[120:123]
	v_mfma_f32_16x16x32_bf16 v[116:119], v[194:197], v[202:205], v[116:119]
	v_mfma_f32_16x16x32_bf16 v[104:107], v[186:189], v[210:213], v[104:107]
	v_mfma_f32_16x16x32_bf16 v[100:103], v[194:197], v[210:213], v[100:103]
	v_mfma_f32_16x16x32_bf16 v[88:91], v[186:189], v[218:221], v[88:91]
	v_mfma_f32_16x16x32_bf16 v[84:87], v[194:197], v[218:221], v[84:87]
	v_mfma_f32_16x16x32_bf16 v[72:75], v[186:189], v[234:237], v[72:75]
	v_mfma_f32_16x16x32_bf16 v[68:71], v[194:197], v[234:237], v[68:71]
	v_mfma_f32_16x16x32_bf16 v[120:123], v[190:193], v[206:209], v[120:123]
	v_mfma_f32_16x16x32_bf16 v[116:119], v[198:201], v[206:209], v[116:119]
	v_mfma_f32_16x16x32_bf16 v[104:107], v[190:193], v[214:217], v[104:107]
	v_mfma_f32_16x16x32_bf16 v[100:103], v[198:201], v[214:217], v[100:103]
	v_mfma_f32_16x16x32_bf16 v[88:91], v[190:193], v[222:225], v[88:91]
	v_mfma_f32_16x16x32_bf16 v[84:87], v[198:201], v[222:225], v[84:87]
	v_mfma_f32_16x16x32_bf16 v[72:75], v[190:193], v[238:241], v[72:75]
	v_mfma_f32_16x16x32_bf16 v[68:71], v[198:201], v[238:241], v[68:71]
	s_setprio 0
	s_barrier
	s_add_i32 s63, s63, s6
	s_mov_b32 m0, s63
	ds_read_b128 v[202:205], v147 offset:16384
	ds_read_b128 v[206:209], v147 offset:17408
	ds_read_b128 v[210:213], v147 offset:18432
	ds_read_b128 v[214:217], v147 offset:19456
	ds_read_b128 v[218:221], v147 offset:20480
	ds_read_b128 v[222:225], v147 offset:21504
	ds_read_b128 v[234:237], v147 offset:22528
	ds_read_b128 v[238:241], v147 offset:23552
	global_load_lds_dwordx4 v34, s[52:53]
	s_add_i32 m0, s63, 0x2000
	s_add_u32 s64, s52, 0x80000
	v_lshl_add_u64 v[226:227], s[52:53], 0, v[132:133]
	s_addc_u32 s65, s53, 0
	s_add_i32 s63, s66, s6
	global_load_lds_dwordx4 v132, s[52:53]
	s_mov_b32 m0, s63
	v_lshl_add_u64 v[244:245], s[54:55], 0, v[134:135]
	global_load_lds_dwordx4 v34, s[64:65]
	s_add_i32 m0, s63, 0x2000
	s_nop 0
	global_load_lds_dwordx4 v132, s[64:65]
	v_lshl_add_u64 v[242:243], s[54:55], 0, v[136:137]
	s_mov_b32 m0, s12
	s_nop 0
	global_load_lds_dwordx4 v136, s[54:55]
	s_mov_b32 m0, s13
	s_nop 0
	global_load_lds_dwordx4 v134, s[54:55]
	s_waitcnt vmcnt(8)
	s_waitcnt lgkmcnt(0)
	s_barrier
; #define PG8_STAGE(bufoff, gbase, voff) do { _Pragma("unroll") for (int _i = 0; _i < 2; ++_i) \
;         __builtin_amdgcn_global_load_lds((const unsigned*)((const char*)(gbase) + (voff)[_i]), (PG8_LAS unsigned*)(lds + (bufoff) + ldsw + _i * 8192), 16, 0, 0); } while (0)
; #define PG8_LDA(dst, b, h) do { _Pragma("unroll") for (int m = 0; m < 4; ++m) _Pragma("unroll") for (int k = 0; k < 2; ++k) dst[m][k] = *(const PG8_LAS bf16x8*)(lds + PG8_SA(b, h) + aoff + m * 2048 + k * 1024); } while (0)
; #define PG8_LDB(dst, b, h) do { _Pragma("unroll") for (int n = 0; n < 2; ++n) _Pragma("unroll") for (int k = 0; k < 2; ++k) dst[n][k] = *(const PG8_LAS bf16x8*)(lds + PG8_SB(b, h) + boff + n * 2048 + k * 1024); } while (0)
; #define PG8_WAIT_V(n) asm volatile("s_waitcnt vmcnt(" #n ")" ::: "memory")
; #define PG8_WAIT_L(n) asm volatile("s_waitcnt lgkmcnt(" #n ")" ::: "memory")
; #define PG8_BAR __builtin_amdgcn_s_barrier()
; #define PG8_SCHED __builtin_amdgcn_sched_barrier(0)
;     ...
;             PG8_WAIT_V(8); PG8_WAIT_L(0); PG8_BAR; PG8_MMA(1, 0, At, B0); PG8_MMA(1, 1, At, B1); PG8_BAR; PG8_SCHED;
;             PG8_LDB(B0, 1, 0); PG8_LDB(B1, 1, 1); PG8_SCHED; PG8_LDA(At, 1, 0); PG8_STAGE(PG8_SA(0, 1), a2 + hstepA, voffA);
;             PG8_WAIT_V(8); PG8_WAIT_L(0); PG8_BAR; PG8_MMA(0, 0, At, B0); PG8_MMA(0, 1, At, B1); PG8_BAR; PG8_SCHED;
	s_setprio 1
	v_mfma_f32_16x16x32_bf16 v[64:67], v[148:151], v[202:205], v[64:67]
	v_mfma_f32_16x16x32_bf16 v[60:63], v[156:159], v[202:205], v[60:63]
	v_mfma_f32_16x16x32_bf16 v[48:51], v[148:151], v[210:213], v[48:51]
	v_mfma_f32_16x16x32_bf16 v[44:47], v[156:159], v[210:213], v[44:47]
	v_mfma_f32_16x16x32_bf16 v[30:33], v[148:151], v[218:221], v[30:33]
	v_mfma_f32_16x16x32_bf16 v[26:29], v[156:159], v[218:221], v[26:29]
	v_mfma_f32_16x16x32_bf16 v[14:17], v[148:151], v[234:237], v[14:17]
	v_mfma_f32_16x16x32_bf16 v[10:13], v[156:159], v[234:237], v[10:13]
	v_mfma_f32_16x16x32_bf16 v[64:67], v[152:155], v[206:209], v[64:67]
	v_mfma_f32_16x16x32_bf16 v[60:63], v[160:163], v[206:209], v[60:63]
	v_mfma_f32_16x16x32_bf16 v[48:51], v[152:155], v[214:217], v[48:51]
	v_mfma_f32_16x16x32_bf16 v[44:47], v[160:163], v[214:217], v[44:47]
	v_mfma_f32_16x16x32_bf16 v[30:33], v[152:155], v[222:225], v[30:33]
	v_mfma_f32_16x16x32_bf16 v[26:29], v[160:163], v[222:225], v[26:29]
	v_mfma_f32_16x16x32_bf16 v[14:17], v[152:155], v[238:241], v[14:17]
	v_mfma_f32_16x16x32_bf16 v[10:13], v[160:163], v[238:241], v[10:13]
	v_mfma_f32_16x16x32_bf16 v[56:59], v[186:189], v[202:205], v[56:59]
	v_mfma_f32_16x16x32_bf16 v[52:55], v[194:197], v[202:205], v[52:55]
	v_mfma_f32_16x16x32_bf16 v[40:43], v[186:189], v[210:213], v[40:43]
	v_mfma_f32_16x16x32_bf16 v[36:39], v[194:197], v[210:213], v[36:39]
	v_mfma_f32_16x16x32_bf16 v[22:25], v[186:189], v[218:221], v[22:25]
	v_mfma_f32_16x16x32_bf16 v[18:21], v[194:197], v[218:221], v[18:21]
	v_mfma_f32_16x16x32_bf16 v[6:9], v[186:189], v[234:237], v[6:9]
	v_mfma_f32_16x16x32_bf16 v[2:5], v[194:197], v[234:237], v[2:5]
	v_mfma_f32_16x16x32_bf16 v[56:59], v[190:193], v[206:209], v[56:59]
	v_mfma_f32_16x16x32_bf16 v[52:55], v[198:201], v[206:209], v[52:55]
	v_mfma_f32_16x16x32_bf16 v[40:43], v[190:193], v[214:217], v[40:43]
	v_mfma_f32_16x16x32_bf16 v[36:39], v[198:201], v[214:217], v[36:39]
	v_mfma_f32_16x16x32_bf16 v[22:25], v[190:193], v[222:225], v[22:25]
	v_mfma_f32_16x16x32_bf16 v[18:21], v[198:201], v[222:225], v[18:21]
	v_mfma_f32_16x16x32_bf16 v[6:9], v[190:193], v[238:241], v[6:9]
	v_mfma_f32_16x16x32_bf16 v[2:5], v[198:201], v[238:241], v[2:5]
	s_setprio 0
	s_barrier
	s_add_i32 s63, 0, 0x18000
	s_add_i32 s64, 0, 0x1c000
	v_add_u32_e32 v160, s63, v145
	v_add_u32_e32 v198, s64, v145
	ds_read_b128 v[148:151], v160
	ds_read_b128 v[152:155], v160 offset:1024
	ds_read_b128 v[156:159], v160 offset:2048
	ds_read_b128 v[160:163], v160 offset:3072
	ds_read_b128 v[186:189], v198
	ds_read_b128 v[190:193], v198 offset:1024
	ds_read_b128 v[194:197], v198 offset:2048
	ds_read_b128 v[198:201], v198 offset:3072
	s_add_u32 s54, s54, 0x80000
	s_addc_u32 s55, s55, 0
	s_mov_b32 m0, s15
	ds_read_b128 v[202:205], v147 offset:32768
	ds_read_b128 v[206:209], v147 offset:33792
	ds_read_b128 v[210:213], v147 offset:34816
	ds_read_b128 v[214:217], v147 offset:35840
	ds_read_b128 v[218:221], v147 offset:36864
	ds_read_b128 v[222:225], v147 offset:37888
	ds_read_b128 v[234:237], v147 offset:38912
	ds_read_b128 v[238:241], v147 offset:39936
	global_load_lds_dwordx4 v136, s[54:55]
	v_lshl_add_u64 v[246:247], s[54:55], 0, v[134:135]
	s_mov_b32 m0, s34
	s_nop 0
	global_load_lds_dwordx4 v134, s[54:55]
	s_waitcnt vmcnt(8)
	s_waitcnt lgkmcnt(0)
	s_barrier
	s_setprio 1
	v_mfma_f32_16x16x32_bf16 v[128:131], v[148:151], v[202:205], v[128:131]
	v_mfma_f32_16x16x32_bf16 v[124:127], v[156:159], v[202:205], v[124:127]
	v_mfma_f32_16x16x32_bf16 v[112:115], v[148:151], v[210:213], v[112:115]
	v_mfma_f32_16x16x32_bf16 v[108:111], v[156:159], v[210:213], v[108:111]
	v_mfma_f32_16x16x32_bf16 v[96:99], v[148:151], v[218:221], v[96:99]
	v_mfma_f32_16x16x32_bf16 v[92:95], v[156:159], v[218:221], v[92:95]
	v_mfma_f32_16x16x32_bf16 v[80:83], v[148:151], v[234:237], v[80:83]
	v_mfma_f32_16x16x32_bf16 v[76:79], v[156:159], v[234:237], v[76:79]
	v_mfma_f32_16x16x32_bf16 v[128:131], v[152:155], v[206:209], v[128:131]
	v_mfma_f32_16x16x32_bf16 v[124:127], v[160:163], v[206:209], v[124:127]
	v_mfma_f32_16x16x32_bf16 v[112:115], v[152:155], v[214:217], v[112:115]
	v_mfma_f32_16x16x32_bf16 v[108:111], v[160:163], v[214:217], v[108:111]
	v_mfma_f32_16x16x32_bf16 v[96:99], v[152:155], v[222:225], v[96:99]
	v_mfma_f32_16x16x32_bf16 v[92:95], v[160:163], v[222:225], v[92:95]
	v_mfma_f32_16x16x32_bf16 v[80:83], v[152:155], v[238:241], v[80:83]
	v_mfma_f32_16x16x32_bf16 v[76:79], v[160:163], v[238:241], v[76:79]
	v_mfma_f32_16x16x32_bf16 v[120:123], v[186:189], v[202:205], v[120:123]
	v_mfma_f32_16x16x32_bf16 v[116:119], v[194:197], v[202:205], v[116:119]
	v_mfma_f32_16x16x32_bf16 v[104:107], v[186:189], v[210:213], v[104:107]
	v_mfma_f32_16x16x32_bf16 v[100:103], v[194:197], v[210:213], v[100:103]
	v_mfma_f32_16x16x32_bf16 v[88:91], v[186:189], v[218:221], v[88:91]
	v_mfma_f32_16x16x32_bf16 v[84:87], v[194:197], v[218:221], v[84:87]
	v_mfma_f32_16x16x32_bf16 v[72:75], v[186:189], v[234:237], v[72:75]
	v_mfma_f32_16x16x32_bf16 v[68:71], v[194:197], v[234:237], v[68:71]
	v_mfma_f32_16x16x32_bf16 v[120:123], v[190:193], v[206:209], v[120:123]
	v_mfma_f32_16x16x32_bf16 v[116:119], v[198:201], v[206:209], v[116:119]
	v_mfma_f32_16x16x32_bf16 v[104:107], v[190:193], v[214:217], v[104:107]
	v_mfma_f32_16x16x32_bf16 v[100:103], v[198:201], v[214:217], v[100:103]
	v_mfma_f32_16x16x32_bf16 v[88:91], v[190:193], v[222:225], v[88:91]
	v_mfma_f32_16x16x32_bf16 v[84:87], v[198:201], v[222:225], v[84:87]
	v_mfma_f32_16x16x32_bf16 v[72:75], v[190:193], v[238:241], v[72:75]
	v_mfma_f32_16x16x32_bf16 v[68:71], v[198:201], v[238:241], v[68:71]
	s_setprio 0
	s_barrier
; #define PG8_STAGE(bufoff, gbase, voff) do { _Pragma("unroll") for (int _i = 0; _i < 2; ++_i) \
;         __builtin_amdgcn_global_load_lds((const unsigned*)((const char*)(gbase) + (voff)[_i]), (PG8_LAS unsigned*)(lds + (bufoff) + ldsw + _i * 8192), 16, 0, 0); } while (0)
; #define PG8_LDA(dst, b, h) do { _Pragma("unroll") for (int m = 0; m < 4; ++m) _Pragma("unroll") for (int k = 0; k < 2; ++k) dst[m][k] = *(const PG8_LAS bf16x8*)(lds + PG8_SA(b, h) + aoff + m * 2048 + k * 1024); } while (0)
; #define PG8_WAIT_V(n) asm volatile("s_waitcnt vmcnt(" #n ")" ::: "memory")
; #define PG8_WAIT_L(n) asm volatile("s_waitcnt lgkmcnt(" #n ")" ::: "memory")
; #define PG8_BAR __builtin_amdgcn_s_barrier()
; #define PG8_SCHED __builtin_amdgcn_sched_barrier(0)
;     ...
;         for (int t = 0; t < nt; t += 2) {
;             const bool last = (t == nt - 2);
;             const char* a1 = cA + (size_t)(t + 1) * kstep;
;             const char* a2 = last ? nA : cA + (size_t)(t + 2) * kstep; const char* b2 = last ? nB : cB + (size_t)(t + 2) * kstep;
;             const char* a3 = a2 + kstep; const char* b3 = b2 + kstep;
;     ...
;             PG8_LDA(At, 1, 1); PG8_STAGE(PG8_SB(1, 0), b3, voffB); PG8_STAGE(PG8_SB(1, 1), b3 + hstepB, voffB); PG8_STAGE(PG8_SA(1, 0), a3, voffA);
;             PG8_WAIT_V(8); PG8_WAIT_L(0); PG8_BAR; PG8_MMA(1, 0, At, B0); PG8_MMA(1, 1, At, B1); PG8_BAR; PG8_SCHED;
	s_add_i32 s54, s63, s6
	s_mov_b32 m0, s54
	ds_read_b128 v[202:205], v147 offset:49152
	ds_read_b128 v[206:209], v147 offset:50176
	ds_read_b128 v[210:213], v147 offset:51200
	ds_read_b128 v[214:217], v147 offset:52224
	ds_read_b128 v[218:221], v147 offset:53248
	ds_read_b128 v[222:225], v147 offset:54272
	ds_read_b128 v[234:237], v147 offset:55296
	ds_read_b128 v[238:241], v147 offset:56320
	s_add_u32 s98, s52, 0x80
	s_addc_u32 s99, s53, 0
	global_load_lds_dwordx4 v34, s[98:99]
	s_add_i32 m0, s54, 0x2000
	s_add_u32 s52, s52, 0x80080
	s_addc_u32 s53, s53, 0
	s_add_i32 s54, s64, s6
	s_add_u32 s98, s52, 0xfff80000
	s_addc_u32 s99, s53, -1
	global_load_lds_dwordx4 v132, s[98:99]
	s_mov_b32 m0, s54
	s_nop 0
	global_load_lds_dwordx4 v34, s[52:53]
	s_add_i32 m0, s54, 0x2000
	s_nop 0
	global_load_lds_dwordx4 v132, s[52:53]
	v_lshl_add_u64 v[142:143], v[242:243], 0, s[22:23]
	s_mov_b32 m0, s24
	s_nop 0
	global_load_lds_dwordx4 v[142:143], off
	v_lshl_add_u64 v[142:143], v[244:245], 0, s[22:23]
	s_mov_b32 m0, s35
	s_nop 0
	global_load_lds_dwordx4 v[142:143], off
	s_waitcnt vmcnt(8)
	s_waitcnt lgkmcnt(0)
	s_barrier
	s_setprio 1
	v_mfma_f32_16x16x32_bf16 v[64:67], v[148:151], v[202:205], v[64:67]
	v_mfma_f32_16x16x32_bf16 v[60:63], v[156:159], v[202:205], v[60:63]
	v_mfma_f32_16x16x32_bf16 v[48:51], v[148:151], v[210:213], v[48:51]
	v_mfma_f32_16x16x32_bf16 v[44:47], v[156:159], v[210:213], v[44:47]
	v_mfma_f32_16x16x32_bf16 v[30:33], v[148:151], v[218:221], v[30:33]
	v_mfma_f32_16x16x32_bf16 v[26:29], v[156:159], v[218:221], v[26:29]
	v_mfma_f32_16x16x32_bf16 v[14:17], v[148:151], v[234:237], v[14:17]
	v_mfma_f32_16x16x32_bf16 v[10:13], v[156:159], v[234:237], v[10:13]
	v_mfma_f32_16x16x32_bf16 v[64:67], v[152:155], v[206:209], v[64:67]
	v_mfma_f32_16x16x32_bf16 v[60:63], v[160:163], v[206:209], v[60:63]
	v_mfma_f32_16x16x32_bf16 v[48:51], v[152:155], v[214:217], v[48:51]
	v_mfma_f32_16x16x32_bf16 v[44:47], v[160:163], v[214:217], v[44:47]
	v_mfma_f32_16x16x32_bf16 v[30:33], v[152:155], v[222:225], v[30:33]
	v_mfma_f32_16x16x32_bf16 v[26:29], v[160:163], v[222:225], v[26:29]
	v_mfma_f32_16x16x32_bf16 v[14:17], v[152:155], v[238:241], v[14:17]
	v_mfma_f32_16x16x32_bf16 v[10:13], v[160:163], v[238:241], v[10:13]
	v_mfma_f32_16x16x32_bf16 v[56:59], v[186:189], v[202:205], v[56:59]
	v_mfma_f32_16x16x32_bf16 v[52:55], v[194:197], v[202:205], v[52:55]
	v_mfma_f32_16x16x32_bf16 v[40:43], v[186:189], v[210:213], v[40:43]
	v_mfma_f32_16x16x32_bf16 v[36:39], v[194:197], v[210:213], v[36:39]
	v_mfma_f32_16x16x32_bf16 v[22:25], v[186:189], v[218:221], v[22:25]
	v_mfma_f32_16x16x32_bf16 v[18:21], v[194:197], v[218:221], v[18:21]
	v_mfma_f32_16x16x32_bf16 v[6:9], v[186:189], v[234:237], v[6:9]
	v_mfma_f32_16x16x32_bf16 v[2:5], v[194:197], v[234:237], v[2:5]
	v_mfma_f32_16x16x32_bf16 v[56:59], v[190:193], v[206:209], v[56:59]
	v_mfma_f32_16x16x32_bf16 v[52:55], v[198:201], v[206:209], v[52:55]
	v_mfma_f32_16x16x32_bf16 v[40:43], v[190:193], v[214:217], v[40:43]
	v_mfma_f32_16x16x32_bf16 v[36:39], v[198:201], v[214:217], v[36:39]
	v_mfma_f32_16x16x32_bf16 v[22:25], v[190:193], v[222:225], v[22:25]
	v_mfma_f32_16x16x32_bf16 v[18:21], v[198:201], v[222:225], v[18:21]
	v_mfma_f32_16x16x32_bf16 v[6:9], v[190:193], v[238:241], v[6:9]
	v_mfma_f32_16x16x32_bf16 v[2:5], v[198:201], v[238:241], v[2:5]
	s_setprio 0
	s_barrier
	s_add_i32 s62, s62, 2
	s_add_u32 s50, s50, 0x100
	s_addc_u32 s51, s51, 0
	s_add_u32 s60, s60, 0x100
	s_addc_u32 s61, s61, 0
	s_cmp_gt_u32 s62, 29
	s_cbranch_scc0 .LBB0_608
	s_and_b64 vcc, exec, s[28:29]
	s_cbranch_vccz .LBB0_611
	s_barrier

; #define PG8_STAGE(bufoff, gbase, voff) do { _Pragma("unroll") for (int _i = 0; _i < 2; ++_i) \
;         __builtin_amdgcn_global_load_lds((const unsigned*)((const char*)(gbase) + (voff)[_i]), (PG8_LAS unsigned*)(lds + (bufoff) + ldsw + _i * 8192), 16, 0, 0); } while (0)
; #define PG8_LDA(dst, b, h) do { _Pragma("unroll") for (int m = 0; m < 4; ++m) _Pragma("unroll") for (int k = 0; k < 2; ++k) dst[m][k] = *(const PG8_LAS bf16x8*)(lds + PG8_SA(b, h) + aoff + m * 2048 + k * 1024); } while (0)
; #define PG8_LDB(dst, b, h) do { _Pragma("unroll") for (int n = 0; n < 2; ++n) _Pragma("unroll") for (int k = 0; k < 2; ++k) dst[n][k] = *(const PG8_LAS bf16x8*)(lds + PG8_SB(b, h) + boff + n * 2048 + k * 1024); } while (0)
; #define PG8_WAIT_V(n) asm volatile("s_waitcnt vmcnt(" #n ")" ::: "memory")
; #define PG8_WAIT_L(n) asm volatile("s_waitcnt lgkmcnt(" #n ")" ::: "memory")
; #define PG8_BAR __builtin_amdgcn_s_barrier()
; #define PG8_SCHED __builtin_amdgcn_sched_barrier(0)
;     ...
;             const char* a1 = cA + (size_t)(t + 1) * kstep;
;             const char* a2 = last ? nA : cA + (size_t)(t + 2) * kstep; const char* b2 = last ? nB : cB + (size_t)(t + 2) * kstep;
;             const char* a3 = a2 + kstep; const char* b3 = b2 + kstep;
;             if (last && has_next) S.a_ready(nxt);
;             if constexpr (SP2) {
;             PG8_LDB(B0, 0, 0); PG8_LDB(B1, 0, 1); PG8_SCHED; PG8_LDA(At, 0, 0); PG8_STAGE(PG8_SA(1, 1), a1 + hstepA, voffA);
;             PG8_WAIT_V(8); PG8_WAIT_L(0); PG8_BAR; PG8_MMA(0, 0, At, B0); PG8_MMA(0, 1, At, B1); PG8_BAR; PG8_SCHED;
;             PG8_LDA(At, 0, 1); PG8_STAGE(PG8_SB(0, 0), b2, voffB); PG8_STAGE(PG8_SB(0, 1), b2 + hstepB, voffB); PG8_STAGE(PG8_SA(0, 0), a2, voffA);
;             PG8_WAIT_V(8); PG8_WAIT_L(0); PG8_BAR; PG8_MMA(1, 0, At, B0); PG8_MMA(1, 1, At, B1); PG8_BAR; PG8_SCHED;
.LBB0_694:
	s_add_u32 s44, s42, 0x100
	s_addc_u32 s45, s43, 0
	s_add_i32 s67, 0, 0x10000
	s_cmpk_eq_i32 s66, 0x54
	s_cselect_b32 s53, s37, s45
	s_cselect_b32 s52, s36, s44
	s_cselect_b32 s51, s41, s65
	s_cselect_b32 s50, s40, s64
	s_add_i32 s68, 0, 0x14000
	v_add_u32_e32 v158, s67, v143
	v_add_u32_e32 v162, s68, v143
	ds_read_b128 v[146:149], v158
	ds_read_b128 v[150:153], v158 offset:1024
	ds_read_b128 v[154:157], v158 offset:2048
	ds_read_b128 v[158:161], v158 offset:3072
	ds_read_b128 v[186:189], v162
	ds_read_b128 v[190:193], v162 offset:1024
	ds_read_b128 v[194:197], v162 offset:2048
	ds_read_b128 v[198:201], v162 offset:3072
	s_add_i32 m0, s34, 0xc000
	ds_read_b128 v[202:205], v145
	ds_read_b128 v[206:209], v145 offset:1024
	ds_read_b128 v[210:213], v145 offset:2048
	ds_read_b128 v[214:217], v145 offset:3072
	ds_read_b128 v[218:221], v145 offset:4096
	ds_read_b128 v[222:225], v145 offset:5120
	ds_read_b128 v[234:237], v145 offset:6144
	ds_read_b128 v[238:241], v145 offset:7168
	global_load_lds_dwordx4 v138, s[42:43]
	s_add_i32 m0, s34, 0xe000
	s_nop 0
	global_load_lds_dwordx4 v140, s[42:43]
	s_waitcnt vmcnt(8)
	s_waitcnt lgkmcnt(0)
	s_barrier
	s_setprio 1
	v_mfma_f32_16x16x32_bf16 v[128:131], v[146:149], v[202:205], v[128:131]
	v_mfma_f32_16x16x32_bf16 v[124:127], v[154:157], v[202:205], v[124:127]
	v_mfma_f32_16x16x32_bf16 v[120:123], v[146:149], v[210:213], v[120:123]
	v_mfma_f32_16x16x32_bf16 v[116:119], v[154:157], v[210:213], v[116:119]
	v_mfma_f32_16x16x32_bf16 v[104:107], v[146:149], v[218:221], v[104:107]
	v_mfma_f32_16x16x32_bf16 v[100:103], v[154:157], v[218:221], v[100:103]
	v_mfma_f32_16x16x32_bf16 v[88:91], v[146:149], v[234:237], v[88:91]
	v_mfma_f32_16x16x32_bf16 v[84:87], v[154:157], v[234:237], v[84:87]
	v_mfma_f32_16x16x32_bf16 v[128:131], v[150:153], v[206:209], v[128:131]
	v_mfma_f32_16x16x32_bf16 v[124:127], v[158:161], v[206:209], v[124:127]
	v_mfma_f32_16x16x32_bf16 v[120:123], v[150:153], v[214:217], v[120:123]
	v_mfma_f32_16x16x32_bf16 v[116:119], v[158:161], v[214:217], v[116:119]
	v_mfma_f32_16x16x32_bf16 v[104:107], v[150:153], v[222:225], v[104:107]
	v_mfma_f32_16x16x32_bf16 v[100:103], v[158:161], v[222:225], v[100:103]
	v_mfma_f32_16x16x32_bf16 v[88:91], v[150:153], v[238:241], v[88:91]
	v_mfma_f32_16x16x32_bf16 v[84:87], v[158:161], v[238:241], v[84:87]
	v_mfma_f32_16x16x32_bf16 v[112:115], v[186:189], v[202:205], v[112:115]
	v_mfma_f32_16x16x32_bf16 v[108:111], v[194:197], v[202:205], v[108:111]
	v_mfma_f32_16x16x32_bf16 v[96:99], v[186:189], v[210:213], v[96:99]
	v_mfma_f32_16x16x32_bf16 v[92:95], v[194:197], v[210:213], v[92:95]
	v_mfma_f32_16x16x32_bf16 v[80:83], v[186:189], v[218:221], v[80:83]
	v_mfma_f32_16x16x32_bf16 v[76:79], v[194:197], v[218:221], v[76:79]
	v_mfma_f32_16x16x32_bf16 v[72:75], v[186:189], v[234:237], v[72:75]
	v_mfma_f32_16x16x32_bf16 v[68:71], v[194:197], v[234:237], v[68:71]
	v_mfma_f32_16x16x32_bf16 v[112:115], v[190:193], v[206:209], v[112:115]
	v_mfma_f32_16x16x32_bf16 v[108:111], v[198:201], v[206:209], v[108:111]
	v_mfma_f32_16x16x32_bf16 v[96:99], v[190:193], v[214:217], v[96:99]
	v_mfma_f32_16x16x32_bf16 v[92:95], v[198:201], v[214:217], v[92:95]
	v_mfma_f32_16x16x32_bf16 v[80:83], v[190:193], v[222:225], v[80:83]
	v_mfma_f32_16x16x32_bf16 v[76:79], v[198:201], v[222:225], v[76:79]
	v_mfma_f32_16x16x32_bf16 v[72:75], v[190:193], v[238:241], v[72:75]
	v_mfma_f32_16x16x32_bf16 v[68:71], v[198:201], v[238:241], v[68:71]
	s_setprio 0
	s_barrier
	s_add_i32 s42, s67, s15
	s_mov_b32 m0, s42
	ds_read_b128 v[202:205], v145 offset:16384
	ds_read_b128 v[206:209], v145 offset:17408
	ds_read_b128 v[210:213], v145 offset:18432
	ds_read_b128 v[214:217], v145 offset:19456
	ds_read_b128 v[218:221], v145 offset:20480
	ds_read_b128 v[222:225], v145 offset:21504
	ds_read_b128 v[234:237], v145 offset:22528
	ds_read_b128 v[238:241], v145 offset:23552
	global_load_lds_dwordx4 v34, s[50:51]
	s_add_i32 m0, s42, 0x2000
	s_add_u32 s42, s50, 0x160000
	v_lshl_add_u64 v[226:227], s[50:51], 0, v[136:137]
	s_addc_u32 s43, s51, 0
	s_add_i32 s67, s68, s15
	global_load_lds_dwordx4 v136, s[50:51]
	s_mov_b32 m0, s67
	v_lshl_add_u64 v[244:245], s[52:53], 0, v[134:135]
	global_load_lds_dwordx4 v34, s[42:43]
	s_add_i32 m0, s67, 0x2000
	s_nop 0
	global_load_lds_dwordx4 v136, s[42:43]
	v_lshl_add_u64 v[242:243], s[52:53], 0, v[132:133]
	s_mov_b32 m0, s34
	s_nop 0
	global_load_lds_dwordx4 v132, s[52:53]
	s_mov_b32 m0, s35
	s_nop 0
	global_load_lds_dwordx4 v134, s[52:53]
	s_waitcnt vmcnt(8)
	s_waitcnt lgkmcnt(0)
	s_barrier
; #define PG8_STAGE(bufoff, gbase, voff) do { _Pragma("unroll") for (int _i = 0; _i < 2; ++_i) \
;         __builtin_amdgcn_global_load_lds((const unsigned*)((const char*)(gbase) + (voff)[_i]), (PG8_LAS unsigned*)(lds + (bufoff) + ldsw + _i * 8192), 16, 0, 0); } while (0)
; #define PG8_LDA(dst, b, h) do { _Pragma("unroll") for (int m = 0; m < 4; ++m) _Pragma("unroll") for (int k = 0; k < 2; ++k) dst[m][k] = *(const PG8_LAS bf16x8*)(lds + PG8_SA(b, h) + aoff + m * 2048 + k * 1024); } while (0)
; #define PG8_LDB(dst, b, h) do { _Pragma("unroll") for (int n = 0; n < 2; ++n) _Pragma("unroll") for (int k = 0; k < 2; ++k) dst[n][k] = *(const PG8_LAS bf16x8*)(lds + PG8_SB(b, h) + boff + n * 2048 + k * 1024); } while (0)
; #define PG8_WAIT_V(n) asm volatile("s_waitcnt vmcnt(" #n ")" ::: "memory")
; #define PG8_WAIT_L(n) asm volatile("s_waitcnt lgkmcnt(" #n ")" ::: "memory")
; #define PG8_BAR __builtin_amdgcn_s_barrier()
; #define PG8_SCHED __builtin_amdgcn_sched_barrier(0)
;     ...
;             PG8_WAIT_V(8); PG8_WAIT_L(0); PG8_BAR; PG8_MMA(1, 0, At, B0); PG8_MMA(1, 1, At, B1); PG8_BAR; PG8_SCHED;
;             PG8_LDB(B0, 1, 0); PG8_LDB(B1, 1, 1); PG8_SCHED; PG8_LDA(At, 1, 0); PG8_STAGE(PG8_SA(0, 1), a2 + hstepA, voffA);
;             PG8_WAIT_V(8); PG8_WAIT_L(0); PG8_BAR; PG8_MMA(0, 0, At, B0); PG8_MMA(0, 1, At, B1); PG8_BAR; PG8_SCHED;
	s_setprio 1
	v_mfma_f32_16x16x32_bf16 v[64:67], v[146:149], v[202:205], v[64:67]
	v_mfma_f32_16x16x32_bf16 v[60:63], v[154:157], v[202:205], v[60:63]
	v_mfma_f32_16x16x32_bf16 v[56:59], v[146:149], v[210:213], v[56:59]
	v_mfma_f32_16x16x32_bf16 v[52:55], v[154:157], v[210:213], v[52:55]
	v_mfma_f32_16x16x32_bf16 v[40:43], v[146:149], v[218:221], v[40:43]
	v_mfma_f32_16x16x32_bf16 v[36:39], v[154:157], v[218:221], v[36:39]
	v_mfma_f32_16x16x32_bf16 v[22:25], v[146:149], v[234:237], v[22:25]
	v_mfma_f32_16x16x32_bf16 v[18:21], v[154:157], v[234:237], v[18:21]
	v_mfma_f32_16x16x32_bf16 v[64:67], v[150:153], v[206:209], v[64:67]
	v_mfma_f32_16x16x32_bf16 v[60:63], v[158:161], v[206:209], v[60:63]
	v_mfma_f32_16x16x32_bf16 v[56:59], v[150:153], v[214:217], v[56:59]
	v_mfma_f32_16x16x32_bf16 v[52:55], v[158:161], v[214:217], v[52:55]
	v_mfma_f32_16x16x32_bf16 v[40:43], v[150:153], v[222:225], v[40:43]
	v_mfma_f32_16x16x32_bf16 v[36:39], v[158:161], v[222:225], v[36:39]
	v_mfma_f32_16x16x32_bf16 v[22:25], v[150:153], v[238:241], v[22:25]
	v_mfma_f32_16x16x32_bf16 v[18:21], v[158:161], v[238:241], v[18:21]
	v_mfma_f32_16x16x32_bf16 v[48:51], v[186:189], v[202:205], v[48:51]
	v_mfma_f32_16x16x32_bf16 v[44:47], v[194:197], v[202:205], v[44:47]
	v_mfma_f32_16x16x32_bf16 v[30:33], v[186:189], v[210:213], v[30:33]
	v_mfma_f32_16x16x32_bf16 v[26:29], v[194:197], v[210:213], v[26:29]
	v_mfma_f32_16x16x32_bf16 v[14:17], v[186:189], v[218:221], v[14:17]
	v_mfma_f32_16x16x32_bf16 v[10:13], v[194:197], v[218:221], v[10:13]
	v_mfma_f32_16x16x32_bf16 v[6:9], v[186:189], v[234:237], v[6:9]
	v_mfma_f32_16x16x32_bf16 v[2:5], v[194:197], v[234:237], v[2:5]
	v_mfma_f32_16x16x32_bf16 v[48:51], v[190:193], v[206:209], v[48:51]
	v_mfma_f32_16x16x32_bf16 v[44:47], v[198:201], v[206:209], v[44:47]
	v_mfma_f32_16x16x32_bf16 v[30:33], v[190:193], v[214:217], v[30:33]
	v_mfma_f32_16x16x32_bf16 v[26:29], v[198:201], v[214:217], v[26:29]
	v_mfma_f32_16x16x32_bf16 v[14:17], v[190:193], v[222:225], v[14:17]
	v_mfma_f32_16x16x32_bf16 v[10:13], v[198:201], v[222:225], v[10:13]
	v_mfma_f32_16x16x32_bf16 v[6:9], v[190:193], v[238:241], v[6:9]
	v_mfma_f32_16x16x32_bf16 v[2:5], v[198:201], v[238:241], v[2:5]
	s_setprio 0
	s_barrier
	s_add_i32 s67, 0, 0x18000
	s_add_i32 s68, 0, 0x1c000
	v_add_u32_e32 v158, s67, v143
	v_add_u32_e32 v198, s68, v143
	ds_read_b128 v[146:149], v158
	ds_read_b128 v[150:153], v158 offset:1024
	ds_read_b128 v[154:157], v158 offset:2048
	ds_read_b128 v[158:161], v158 offset:3072
	ds_read_b128 v[186:189], v198
	ds_read_b128 v[190:193], v198 offset:1024
	ds_read_b128 v[194:197], v198 offset:2048
	ds_read_b128 v[198:201], v198 offset:3072
	s_add_u32 s42, s52, 0x160000
	s_addc_u32 s43, s53, 0
	s_mov_b32 m0, s54
	ds_read_b128 v[202:205], v145 offset:32768
	ds_read_b128 v[206:209], v145 offset:33792
	ds_read_b128 v[210:213], v145 offset:34816
	ds_read_b128 v[214:217], v145 offset:35840
	ds_read_b128 v[218:221], v145 offset:36864
	ds_read_b128 v[222:225], v145 offset:37888
	ds_read_b128 v[234:237], v145 offset:38912
	ds_read_b128 v[238:241], v145 offset:39936
	global_load_lds_dwordx4 v132, s[42:43]
	v_lshl_add_u64 v[246:247], s[42:43], 0, v[134:135]
	s_mov_b32 m0, s55
	s_nop 0
	global_load_lds_dwordx4 v134, s[42:43]
	s_waitcnt vmcnt(8)
	s_waitcnt lgkmcnt(0)
	s_barrier
	s_setprio 1
	v_mfma_f32_16x16x32_bf16 v[128:131], v[146:149], v[202:205], v[128:131]
	v_mfma_f32_16x16x32_bf16 v[124:127], v[154:157], v[202:205], v[124:127]
	v_mfma_f32_16x16x32_bf16 v[120:123], v[146:149], v[210:213], v[120:123]
	v_mfma_f32_16x16x32_bf16 v[116:119], v[154:157], v[210:213], v[116:119]
	v_mfma_f32_16x16x32_bf16 v[104:107], v[146:149], v[218:221], v[104:107]
	v_mfma_f32_16x16x32_bf16 v[100:103], v[154:157], v[218:221], v[100:103]
	v_mfma_f32_16x16x32_bf16 v[88:91], v[146:149], v[234:237], v[88:91]
	v_mfma_f32_16x16x32_bf16 v[84:87], v[154:157], v[234:237], v[84:87]
	v_mfma_f32_16x16x32_bf16 v[128:131], v[150:153], v[206:209], v[128:131]
	v_mfma_f32_16x16x32_bf16 v[124:127], v[158:161], v[206:209], v[124:127]
	v_mfma_f32_16x16x32_bf16 v[120:123], v[150:153], v[214:217], v[120:123]
	v_mfma_f32_16x16x32_bf16 v[116:119], v[158:161], v[214:217], v[116:119]
	v_mfma_f32_16x16x32_bf16 v[104:107], v[150:153], v[222:225], v[104:107]
	v_mfma_f32_16x16x32_bf16 v[100:103], v[158:161], v[222:225], v[100:103]
	v_mfma_f32_16x16x32_bf16 v[88:91], v[150:153], v[238:241], v[88:91]
	v_mfma_f32_16x16x32_bf16 v[84:87], v[158:161], v[238:241], v[84:87]
	v_mfma_f32_16x16x32_bf16 v[112:115], v[186:189], v[202:205], v[112:115]
	v_mfma_f32_16x16x32_bf16 v[108:111], v[194:197], v[202:205], v[108:111]
	v_mfma_f32_16x16x32_bf16 v[96:99], v[186:189], v[210:213], v[96:99]
	v_mfma_f32_16x16x32_bf16 v[92:95], v[194:197], v[210:213], v[92:95]
	v_mfma_f32_16x16x32_bf16 v[80:83], v[186:189], v[218:221], v[80:83]
	v_mfma_f32_16x16x32_bf16 v[76:79], v[194:197], v[218:221], v[76:79]
	v_mfma_f32_16x16x32_bf16 v[72:75], v[186:189], v[234:237], v[72:75]
	v_mfma_f32_16x16x32_bf16 v[68:71], v[194:197], v[234:237], v[68:71]
	v_mfma_f32_16x16x32_bf16 v[112:115], v[190:193], v[206:209], v[112:115]
	v_mfma_f32_16x16x32_bf16 v[108:111], v[198:201], v[206:209], v[108:111]
	v_mfma_f32_16x16x32_bf16 v[96:99], v[190:193], v[214:217], v[96:99]
	v_mfma_f32_16x16x32_bf16 v[92:95], v[198:201], v[214:217], v[92:95]
	v_mfma_f32_16x16x32_bf16 v[80:83], v[190:193], v[222:225], v[80:83]
	v_mfma_f32_16x16x32_bf16 v[76:79], v[198:201], v[222:225], v[76:79]
	v_mfma_f32_16x16x32_bf16 v[72:75], v[190:193], v[238:241], v[72:75]
	v_mfma_f32_16x16x32_bf16 v[68:71], v[198:201], v[238:241], v[68:71]
	s_setprio 0
	s_barrier
; #define PG8_STAGE(bufoff, gbase, voff) do { _Pragma("unroll") for (int _i = 0; _i < 2; ++_i) \
;         __builtin_amdgcn_global_load_lds((const unsigned*)((const char*)(gbase) + (voff)[_i]), (PG8_LAS unsigned*)(lds + (bufoff) + ldsw + _i * 8192), 16, 0, 0); } while (0)
; #define PG8_LDA(dst, b, h) do { _Pragma("unroll") for (int m = 0; m < 4; ++m) _Pragma("unroll") for (int k = 0; k < 2; ++k) dst[m][k] = *(const PG8_LAS bf16x8*)(lds + PG8_SA(b, h) + aoff + m * 2048 + k * 1024); } while (0)
; #define PG8_WAIT_V(n) asm volatile("s_waitcnt vmcnt(" #n ")" ::: "memory")
; #define PG8_WAIT_L(n) asm volatile("s_waitcnt lgkmcnt(" #n ")" ::: "memory")
; #define PG8_BAR __builtin_amdgcn_s_barrier()
; #define PG8_SCHED __builtin_amdgcn_sched_barrier(0)
;     ...
;         for (int t = 0; t < nt; t += 2) {
;             const bool last = (t == nt - 2);
;             const char* a1 = cA + (size_t)(t + 1) * kstep;
;             const char* a2 = last ? nA : cA + (size_t)(t + 2) * kstep; const char* b2 = last ? nB : cB + (size_t)(t + 2) * kstep;
;             const char* a3 = a2 + kstep; const char* b3 = b2 + kstep;
;     ...
;             PG8_LDA(At, 1, 1); PG8_STAGE(PG8_SB(1, 0), b3, voffB); PG8_STAGE(PG8_SB(1, 1), b3 + hstepB, voffB); PG8_STAGE(PG8_SA(1, 0), a3, voffA);
;             PG8_WAIT_V(8); PG8_WAIT_L(0); PG8_BAR; PG8_MMA(1, 0, At, B0); PG8_MMA(1, 1, At, B1); PG8_BAR; PG8_SCHED;
	s_add_i32 s42, s67, s15
	s_mov_b32 m0, s42
	ds_read_b128 v[202:205], v145 offset:49152
	ds_read_b128 v[206:209], v145 offset:50176
	ds_read_b128 v[210:213], v145 offset:51200
	ds_read_b128 v[214:217], v145 offset:52224
	ds_read_b128 v[218:221], v145 offset:53248
	ds_read_b128 v[222:225], v145 offset:54272
	ds_read_b128 v[234:237], v145 offset:55296
	ds_read_b128 v[238:241], v145 offset:56320
	s_add_u32 s98, s50, 0x80
	s_addc_u32 s99, s51, 0
	global_load_lds_dwordx4 v34, s[98:99]
	s_add_i32 m0, s42, 0x2000
	s_add_u32 s42, s50, 0x160080
	v_lshl_add_u64 v[162:163], v[226:227], 0, s[22:23]
	s_addc_u32 s43, s51, 0
	s_add_i32 s50, s68, s15
	global_load_lds_dwordx4 v[162:163], off
	s_mov_b32 m0, s50
	s_nop 0
	global_load_lds_dwordx4 v34, s[42:43]
	s_add_i32 m0, s50, 0x2000
	s_nop 0
	global_load_lds_dwordx4 v136, s[42:43]
	s_mov_b32 m0, s56
	s_nop 0
	s_add_u32 s98, s52, 0x80
	s_addc_u32 s99, s53, 0
	global_load_lds_dwordx4 v132, s[98:99]
	v_lshl_add_u64 v[162:163], v[244:245], 0, s[22:23]
	s_mov_b32 m0, s57
	s_nop 0
	s_add_u32 s98, s52, 0x80
	s_addc_u32 s99, s53, 0
	global_load_lds_dwordx4 v134, s[98:99]
	s_waitcnt vmcnt(8)
	s_waitcnt lgkmcnt(0)
	s_barrier
	s_setprio 1
	v_mfma_f32_16x16x32_bf16 v[64:67], v[146:149], v[202:205], v[64:67]
	v_mfma_f32_16x16x32_bf16 v[60:63], v[154:157], v[202:205], v[60:63]
	v_mfma_f32_16x16x32_bf16 v[56:59], v[146:149], v[210:213], v[56:59]
	v_mfma_f32_16x16x32_bf16 v[52:55], v[154:157], v[210:213], v[52:55]
	v_mfma_f32_16x16x32_bf16 v[40:43], v[146:149], v[218:221], v[40:43]
	v_mfma_f32_16x16x32_bf16 v[36:39], v[154:157], v[218:221], v[36:39]
	v_mfma_f32_16x16x32_bf16 v[22:25], v[146:149], v[234:237], v[22:25]
	v_mfma_f32_16x16x32_bf16 v[18:21], v[154:157], v[234:237], v[18:21]
	v_mfma_f32_16x16x32_bf16 v[64:67], v[150:153], v[206:209], v[64:67]
	v_mfma_f32_16x16x32_bf16 v[60:63], v[158:161], v[206:209], v[60:63]
	v_mfma_f32_16x16x32_bf16 v[56:59], v[150:153], v[214:217], v[56:59]
	v_mfma_f32_16x16x32_bf16 v[52:55], v[158:161], v[214:217], v[52:55]
	v_mfma_f32_16x16x32_bf16 v[40:43], v[150:153], v[222:225], v[40:43]
	v_mfma_f32_16x16x32_bf16 v[36:39], v[158:161], v[222:225], v[36:39]
	v_mfma_f32_16x16x32_bf16 v[22:25], v[150:153], v[238:241], v[22:25]
	v_mfma_f32_16x16x32_bf16 v[18:21], v[158:161], v[238:241], v[18:21]
	v_mfma_f32_16x16x32_bf16 v[48:51], v[186:189], v[202:205], v[48:51]
	v_mfma_f32_16x16x32_bf16 v[44:47], v[194:197], v[202:205], v[44:47]
	v_mfma_f32_16x16x32_bf16 v[30:33], v[186:189], v[210:213], v[30:33]
	v_mfma_f32_16x16x32_bf16 v[26:29], v[194:197], v[210:213], v[26:29]
	v_mfma_f32_16x16x32_bf16 v[14:17], v[186:189], v[218:221], v[14:17]
	v_mfma_f32_16x16x32_bf16 v[10:13], v[194:197], v[218:221], v[10:13]
	v_mfma_f32_16x16x32_bf16 v[6:9], v[186:189], v[234:237], v[6:9]
	v_mfma_f32_16x16x32_bf16 v[2:5], v[194:197], v[234:237], v[2:5]
	v_mfma_f32_16x16x32_bf16 v[48:51], v[190:193], v[206:209], v[48:51]
	v_mfma_f32_16x16x32_bf16 v[44:47], v[198:201], v[206:209], v[44:47]
	v_mfma_f32_16x16x32_bf16 v[30:33], v[190:193], v[214:217], v[30:33]
	v_mfma_f32_16x16x32_bf16 v[26:29], v[198:201], v[214:217], v[26:29]
	v_mfma_f32_16x16x32_bf16 v[14:17], v[190:193], v[222:225], v[14:17]
	v_mfma_f32_16x16x32_bf16 v[10:13], v[198:201], v[222:225], v[10:13]
	v_mfma_f32_16x16x32_bf16 v[6:9], v[190:193], v[238:241], v[6:9]
	v_mfma_f32_16x16x32_bf16 v[2:5], v[198:201], v[238:241], v[2:5]
	s_setprio 0
	s_barrier
	s_add_i32 s66, s66, 2
	s_add_u32 s64, s64, 0x100
	s_addc_u32 s65, s65, 0
	s_cmpk_gt_u32 s66, 0x55
	s_mov_b64 s[42:43], s[44:45]
	s_cbranch_scc0 .LBB0_694
	s_and_b64 vcc, exec, s[30:31]
	s_cbranch_vccz .LBB0_697
	s_barrier

; #define PG8_STAGE(bufoff, gbase, voff) do { _Pragma("unroll") for (int _i = 0; _i < 2; ++_i) \
;         __builtin_amdgcn_global_load_lds((const unsigned*)((const char*)(gbase) + (voff)[_i]), (PG8_LAS unsigned*)(lds + (bufoff) + ldsw + _i * 8192), 16, 0, 0); } while (0)
; #define PG8_LDA(dst, b, h) do { _Pragma("unroll") for (int m = 0; m < 4; ++m) _Pragma("unroll") for (int k = 0; k < 2; ++k) dst[m][k] = *(const PG8_LAS bf16x8*)(lds + PG8_SA(b, h) + aoff + m * 2048 + k * 1024); } while (0)
; #define PG8_LDB(dst, b, h) do { _Pragma("unroll") for (int n = 0; n < 2; ++n) _Pragma("unroll") for (int k = 0; k < 2; ++k) dst[n][k] = *(const PG8_LAS bf16x8*)(lds + PG8_SB(b, h) + boff + n * 2048 + k * 1024); } while (0)
; #define PG8_WAIT_V(n) asm volatile("s_waitcnt vmcnt(" #n ")" ::: "memory")
; #define PG8_WAIT_L(n) asm volatile("s_waitcnt lgkmcnt(" #n ")" ::: "memory")
; #define PG8_BAR __builtin_amdgcn_s_barrier()
; #define PG8_SCHED __builtin_amdgcn_sched_barrier(0)
;     ...
;             const char* a1 = cA + (size_t)(t + 1) * kstep;
;             const char* a2 = last ? nA : cA + (size_t)(t + 2) * kstep; const char* b2 = last ? nB : cB + (size_t)(t + 2) * kstep;
;             const char* a3 = a2 + kstep; const char* b3 = b2 + kstep;
;             if (last && has_next) S.a_ready(nxt);
;             if constexpr (SP2) {
;             PG8_LDB(B0, 0, 0); PG8_LDB(B1, 0, 1); PG8_SCHED; PG8_LDA(At, 0, 0); PG8_STAGE(PG8_SA(1, 1), a1 + hstepA, voffA);
;             PG8_WAIT_V(8); PG8_WAIT_L(0); PG8_BAR; PG8_MMA(0, 0, At, B0); PG8_MMA(0, 1, At, B1); PG8_BAR; PG8_SCHED;
;             PG8_LDA(At, 0, 1); PG8_STAGE(PG8_SB(0, 0), b2, voffB); PG8_STAGE(PG8_SB(0, 1), b2 + hstepB, voffB); PG8_STAGE(PG8_SA(0, 0), a2, voffA);
;             PG8_WAIT_V(8); PG8_WAIT_L(0); PG8_BAR; PG8_MMA(1, 0, At, B0); PG8_MMA(1, 1, At, B1); PG8_BAR; PG8_SCHED;
.LBB0_726:
	s_add_u32 s40, s42, 0x100
	s_addc_u32 s41, s43, 0
	s_add_i32 s64, 0, 0x10000
	s_cmp_eq_u32 s63, 40
	s_cselect_b32 s51, s31, s41
	s_cselect_b32 s50, s30, s40
	s_cselect_b32 s45, s37, s62
	s_cselect_b32 s44, s36, s61
	s_add_i32 s65, 0, 0x14000
	v_add_u32_e32 v2, s64, v209
	v_add_u32_e32 v6, s65, v209
	ds_read_b128 v[26:29], v2
	ds_read_b128 v[30:33], v2 offset:1024
	ds_read_b128 v[18:21], v2 offset:2048
	ds_read_b128 v[22:25], v2 offset:3072
	ds_read_b128 v[10:13], v6
	ds_read_b128 v[14:17], v6 offset:1024
	ds_read_b128 v[2:5], v6 offset:2048
	ds_read_b128 v[6:9], v6 offset:3072
	s_add_i32 m0, s21, 0xc000
	ds_read_b128 v[200:203], v211
	ds_read_b128 v[204:207], v211 offset:1024
	ds_read_b128 v[212:215], v211 offset:2048
	ds_read_b128 v[216:219], v211 offset:3072
	ds_read_b128 v[220:223], v211 offset:4096
	ds_read_b128 v[224:227], v211 offset:5120
	ds_read_b128 v[234:237], v211 offset:6144
	ds_read_b128 v[238:241], v211 offset:7168
	global_load_lds_dwordx4 v196, s[42:43]
	s_add_i32 m0, s21, 0xe000
	s_nop 0
	global_load_lds_dwordx4 v198, s[42:43]
	s_waitcnt vmcnt(8)
	s_waitcnt lgkmcnt(0)
	s_barrier
	s_setprio 1
	v_mfma_f32_16x16x128_f8f6f4 v[160:163], v[26:33], v[200:207], v[160:163]
	v_mfma_f32_16x16x128_f8f6f4 v[156:159], v[18:25], v[200:207], v[156:159]
	v_mfma_f32_16x16x128_f8f6f4 v[152:155], v[26:33], v[212:219], v[152:155]
	v_mfma_f32_16x16x128_f8f6f4 v[144:147], v[18:25], v[212:219], v[144:147]
	v_mfma_f32_16x16x128_f8f6f4 v[136:139], v[26:33], v[220:227], v[136:139]
	v_mfma_f32_16x16x128_f8f6f4 v[128:131], v[18:25], v[220:227], v[128:131]
	v_mfma_f32_16x16x128_f8f6f4 v[120:123], v[26:33], v[234:241], v[120:123]
	v_mfma_f32_16x16x128_f8f6f4 v[112:115], v[18:25], v[234:241], v[112:115]
	v_mfma_f32_16x16x128_f8f6f4 v[148:151], v[10:17], v[200:207], v[148:151]
	v_mfma_f32_16x16x128_f8f6f4 v[140:143], v[2:9], v[200:207], v[140:143]
	v_mfma_f32_16x16x128_f8f6f4 v[132:135], v[10:17], v[212:219], v[132:135]
	v_mfma_f32_16x16x128_f8f6f4 v[124:127], v[2:9], v[212:219], v[124:127]
	v_mfma_f32_16x16x128_f8f6f4 v[116:119], v[10:17], v[220:227], v[116:119]
	v_mfma_f32_16x16x128_f8f6f4 v[108:111], v[2:9], v[220:227], v[108:111]
	v_mfma_f32_16x16x128_f8f6f4 v[104:107], v[10:17], v[234:241], v[104:107]
	v_mfma_f32_16x16x128_f8f6f4 v[100:103], v[2:9], v[234:241], v[100:103]
	s_setprio 0
	s_barrier
	s_add_i32 s42, s64, s15
	s_mov_b32 m0, s42
	ds_read_b128 v[212:215], v211 offset:16384
	ds_read_b128 v[216:219], v211 offset:17408
	ds_read_b128 v[220:223], v211 offset:18432
	ds_read_b128 v[224:227], v211 offset:19456
	ds_read_b128 v[234:237], v211 offset:20480
	ds_read_b128 v[238:241], v211 offset:21504
	ds_read_b128 v[242:245], v211 offset:22528
	ds_read_b128 v[246:249], v211 offset:23552
	global_load_lds_dwordx4 v34, s[44:45]
	s_add_i32 m0, s42, 0x2000
	s_add_u32 s42, s44, 0xb0000
	v_lshl_add_u64 v[202:203], s[44:45], 0, v[190:191]
	s_addc_u32 s43, s45, 0
	s_add_i32 s64, s65, s15
	global_load_lds_dwordx4 v190, s[44:45]
	s_mov_b32 m0, s64
	s_nop 0
	global_load_lds_dwordx4 v34, s[42:43]
	s_add_i32 m0, s64, 0x2000
	s_nop 0
	global_load_lds_dwordx4 v190, s[42:43]
	s_mov_b32 m0, s21
	s_nop 0
	global_load_lds_dwordx4 v186, s[50:51]
	s_mov_b32 m0, s34
	s_nop 0
	global_load_lds_dwordx4 v188, s[50:51]
	s_waitcnt vmcnt(8)
	s_waitcnt lgkmcnt(0)
	s_barrier
	s_setprio 1
	v_mfma_f32_16x16x128_f8f6f4 v[96:99], v[26:33], v[212:219], v[96:99]
	v_mfma_f32_16x16x128_f8f6f4 v[92:95], v[18:25], v[212:219], v[92:95]
	v_mfma_f32_16x16x128_f8f6f4 v[88:91], v[26:33], v[220:227], v[88:91]
	v_mfma_f32_16x16x128_f8f6f4 v[80:83], v[18:25], v[220:227], v[80:83]
	v_mfma_f32_16x16x128_f8f6f4 v[72:75], v[26:33], v[234:241], v[72:75]
	v_mfma_f32_16x16x128_f8f6f4 v[64:67], v[18:25], v[234:241], v[64:67]
	v_mfma_f32_16x16x128_f8f6f4 v[56:59], v[26:33], v[242:249], v[56:59]
	v_mfma_f32_16x16x128_f8f6f4 v[48:51], v[18:25], v[242:249], v[48:51]
	v_mfma_f32_16x16x128_f8f6f4 v[84:87], v[10:17], v[212:219], v[84:87]
	v_mfma_f32_16x16x128_f8f6f4 v[76:79], v[2:9], v[212:219], v[76:79]
	v_mfma_f32_16x16x128_f8f6f4 v[68:71], v[10:17], v[220:227], v[68:71]
	v_mfma_f32_16x16x128_f8f6f4 v[60:63], v[2:9], v[220:227], v[60:63]
	v_mfma_f32_16x16x128_f8f6f4 v[52:55], v[10:17], v[234:241], v[52:55]
	v_mfma_f32_16x16x128_f8f6f4 v[44:47], v[2:9], v[234:241], v[44:47]
	v_mfma_f32_16x16x128_f8f6f4 v[40:43], v[10:17], v[242:249], v[40:43]
	v_mfma_f32_16x16x128_f8f6f4 v[36:39], v[2:9], v[242:249], v[36:39]
	s_setprio 0
	s_barrier
; #define PG8_STAGE(bufoff, gbase, voff) do { _Pragma("unroll") for (int _i = 0; _i < 2; ++_i) \
;         __builtin_amdgcn_global_load_lds((const unsigned*)((const char*)(gbase) + (voff)[_i]), (PG8_LAS unsigned*)(lds + (bufoff) + ldsw + _i * 8192), 16, 0, 0); } while (0)
; #define PG8_LDA(dst, b, h) do { _Pragma("unroll") for (int m = 0; m < 4; ++m) _Pragma("unroll") for (int k = 0; k < 2; ++k) dst[m][k] = *(const PG8_LAS bf16x8*)(lds + PG8_SA(b, h) + aoff + m * 2048 + k * 1024); } while (0)
; #define PG8_LDB(dst, b, h) do { _Pragma("unroll") for (int n = 0; n < 2; ++n) _Pragma("unroll") for (int k = 0; k < 2; ++k) dst[n][k] = *(const PG8_LAS bf16x8*)(lds + PG8_SB(b, h) + boff + n * 2048 + k * 1024); } while (0)
; #define PG8_WAIT_V(n) asm volatile("s_waitcnt vmcnt(" #n ")" ::: "memory")
; #define PG8_WAIT_L(n) asm volatile("s_waitcnt lgkmcnt(" #n ")" ::: "memory")
; #define PG8_BAR __builtin_amdgcn_s_barrier()
; #define PG8_SCHED __builtin_amdgcn_sched_barrier(0)
;     ...
;             PG8_WAIT_V(8); PG8_WAIT_L(0); PG8_BAR; PG8_MMA(1, 0, At, B0); PG8_MMA(1, 1, At, B1); PG8_BAR; PG8_SCHED;
;             PG8_LDB(B0, 1, 0); PG8_LDB(B1, 1, 1); PG8_SCHED; PG8_LDA(At, 1, 0); PG8_STAGE(PG8_SA(0, 1), a2 + hstepA, voffA);
;             PG8_WAIT_V(8); PG8_WAIT_L(0); PG8_BAR; PG8_MMA(0, 0, At, B0); PG8_MMA(0, 1, At, B1); PG8_BAR; PG8_SCHED;
;             PG8_LDA(At, 1, 1); PG8_STAGE(PG8_SB(1, 0), b3, voffB); PG8_STAGE(PG8_SB(1, 1), b3 + hstepB, voffB); PG8_STAGE(PG8_SA(1, 0), a3, voffA);
;             PG8_WAIT_V(8); PG8_WAIT_L(0); PG8_BAR; PG8_MMA(1, 0, At, B0); PG8_MMA(1, 1, At, B1); PG8_BAR; PG8_SCHED;
	s_add_i32 s64, 0, 0x18000
	s_add_i32 s65, 0, 0x1c000
	v_add_u32_e32 v14, s64, v209
	v_add_u32_e32 v30, s65, v209
	ds_read_b128 v[2:5], v14
	ds_read_b128 v[6:9], v14 offset:1024
	ds_read_b128 v[10:13], v14 offset:2048
	ds_read_b128 v[14:17], v14 offset:3072
	ds_read_b128 v[18:21], v30
	ds_read_b128 v[22:25], v30 offset:1024
	ds_read_b128 v[26:29], v30 offset:2048
	ds_read_b128 v[30:33], v30 offset:3072
	s_add_u32 s42, s50, 0xb0000
	s_addc_u32 s43, s51, 0
	s_mov_b32 m0, s35
	ds_read_b128 v[212:215], v211 offset:32768
	ds_read_b128 v[216:219], v211 offset:33792
	ds_read_b128 v[220:223], v211 offset:34816
	ds_read_b128 v[224:227], v211 offset:35840
	ds_read_b128 v[234:237], v211 offset:36864
	ds_read_b128 v[238:241], v211 offset:37888
	ds_read_b128 v[242:245], v211 offset:38912
	ds_read_b128 v[246:249], v211 offset:39936
	global_load_lds_dwordx4 v186, s[42:43]
	v_lshl_add_u64 v[250:251], s[42:43], 0, v[188:189]
	s_mov_b32 m0, s52
	s_nop 0
	global_load_lds_dwordx4 v188, s[42:43]
	s_waitcnt vmcnt(8)
	s_waitcnt lgkmcnt(0)
	s_barrier
	s_setprio 1
	v_mfma_f32_16x16x128_f8f6f4 v[160:163], v[2:9], v[212:219], v[160:163]
	v_mfma_f32_16x16x128_f8f6f4 v[156:159], v[10:17], v[212:219], v[156:159]
	v_mfma_f32_16x16x128_f8f6f4 v[152:155], v[2:9], v[220:227], v[152:155]
	v_mfma_f32_16x16x128_f8f6f4 v[144:147], v[10:17], v[220:227], v[144:147]
	v_mfma_f32_16x16x128_f8f6f4 v[136:139], v[2:9], v[234:241], v[136:139]
	v_mfma_f32_16x16x128_f8f6f4 v[128:131], v[10:17], v[234:241], v[128:131]
	v_mfma_f32_16x16x128_f8f6f4 v[120:123], v[2:9], v[242:249], v[120:123]
	v_mfma_f32_16x16x128_f8f6f4 v[112:115], v[10:17], v[242:249], v[112:115]
	v_mfma_f32_16x16x128_f8f6f4 v[148:151], v[18:25], v[212:219], v[148:151]
	v_mfma_f32_16x16x128_f8f6f4 v[140:143], v[26:33], v[212:219], v[140:143]
	v_mfma_f32_16x16x128_f8f6f4 v[132:135], v[18:25], v[220:227], v[132:135]
	v_mfma_f32_16x16x128_f8f6f4 v[124:127], v[26:33], v[220:227], v[124:127]
	v_mfma_f32_16x16x128_f8f6f4 v[116:119], v[18:25], v[234:241], v[116:119]
	v_mfma_f32_16x16x128_f8f6f4 v[108:111], v[26:33], v[234:241], v[108:111]
	v_mfma_f32_16x16x128_f8f6f4 v[104:107], v[18:25], v[242:249], v[104:107]
	v_mfma_f32_16x16x128_f8f6f4 v[100:103], v[26:33], v[242:249], v[100:103]
	s_setprio 0
	s_barrier
	s_add_i32 s42, s64, s15
	s_mov_b32 m0, s42
	ds_read_b128 v[212:215], v211 offset:49152
	ds_read_b128 v[216:219], v211 offset:50176
	ds_read_b128 v[220:223], v211 offset:51200
	ds_read_b128 v[224:227], v211 offset:52224
	ds_read_b128 v[234:237], v211 offset:53248
	ds_read_b128 v[238:241], v211 offset:54272
	ds_read_b128 v[242:245], v211 offset:55296
	ds_read_b128 v[246:249], v211 offset:56320
	s_add_u32 s98, s44, 0x80
	s_addc_u32 s99, s45, 0
	global_load_lds_dwordx4 v34, s[98:99]
	s_add_i32 m0, s42, 0x2000
	s_add_u32 s42, s44, 0xb0080
	v_lshl_add_u64 v[200:201], v[202:203], 0, s[22:23]
	s_addc_u32 s43, s45, 0
	s_add_i32 s44, s65, s15
	global_load_lds_dwordx4 v[200:201], off
	s_mov_b32 m0, s44
	s_nop 0
	global_load_lds_dwordx4 v34, s[42:43]
	s_add_i32 m0, s44, 0x2000
	s_nop 0
	global_load_lds_dwordx4 v190, s[42:43]
	s_mov_b32 m0, s53
	s_nop 0
	s_add_u32 s98, s50, 0x80
	s_addc_u32 s99, s51, 0
	global_load_lds_dwordx4 v186, s[98:99]
	s_mov_b32 m0, s54
	s_nop 0
	s_add_u32 s98, s50, 0x80
	s_addc_u32 s99, s51, 0
	global_load_lds_dwordx4 v188, s[98:99]
	s_waitcnt vmcnt(8)
	s_waitcnt lgkmcnt(0)
	s_barrier
	s_setprio 1
	v_mfma_f32_16x16x128_f8f6f4 v[96:99], v[2:9], v[212:219], v[96:99]
	v_mfma_f32_16x16x128_f8f6f4 v[92:95], v[10:17], v[212:219], v[92:95]
	v_mfma_f32_16x16x128_f8f6f4 v[88:91], v[2:9], v[220:227], v[88:91]
	v_mfma_f32_16x16x128_f8f6f4 v[80:83], v[10:17], v[220:227], v[80:83]
	v_mfma_f32_16x16x128_f8f6f4 v[72:75], v[2:9], v[234:241], v[72:75]
	v_mfma_f32_16x16x128_f8f6f4 v[64:67], v[10:17], v[234:241], v[64:67]
	v_mfma_f32_16x16x128_f8f6f4 v[56:59], v[2:9], v[242:249], v[56:59]
	v_mfma_f32_16x16x128_f8f6f4 v[48:51], v[10:17], v[242:249], v[48:51]
	v_mfma_f32_16x16x128_f8f6f4 v[84:87], v[18:25], v[212:219], v[84:87]
	v_mfma_f32_16x16x128_f8f6f4 v[76:79], v[26:33], v[212:219], v[76:79]
	v_mfma_f32_16x16x128_f8f6f4 v[68:71], v[18:25], v[220:227], v[68:71]
	v_mfma_f32_16x16x128_f8f6f4 v[60:63], v[26:33], v[220:227], v[60:63]
	v_mfma_f32_16x16x128_f8f6f4 v[52:55], v[18:25], v[234:241], v[52:55]
	v_mfma_f32_16x16x128_f8f6f4 v[44:47], v[26:33], v[234:241], v[44:47]
	v_mfma_f32_16x16x128_f8f6f4 v[40:43], v[18:25], v[242:249], v[40:43]
	v_mfma_f32_16x16x128_f8f6f4 v[36:39], v[26:33], v[242:249], v[36:39]
	s_setprio 0
	s_barrier
	s_add_i32 s63, s63, 2
	s_add_u32 s61, s61, 0x100
	s_addc_u32 s62, s62, 0
	s_cmp_gt_u32 s63, 41
	s_mov_b64 s[42:43], s[40:41]
	s_cbranch_scc0 .LBB0_726
	s_and_b64 vcc, exec, s[28:29]
	s_cbranch_vccz .LBB0_729
	s_barrier

; #define PG8_STAGE(bufoff, gbase, voff) do { _Pragma("unroll") for (int _i = 0; _i < 2; ++_i) \
;         __builtin_amdgcn_global_load_lds((const unsigned*)((const char*)(gbase) + (voff)[_i]), (PG8_LAS unsigned*)(lds + (bufoff) + ldsw + _i * 8192), 16, 0, 0); } while (0)
; #define PG8_LDA(dst, b, h) do { _Pragma("unroll") for (int m = 0; m < 4; ++m) _Pragma("unroll") for (int k = 0; k < 2; ++k) dst[m][k] = *(const PG8_LAS bf16x8*)(lds + PG8_SA(b, h) + aoff + m * 2048 + k * 1024); } while (0)
; #define PG8_LDB(dst, b, h) do { _Pragma("unroll") for (int n = 0; n < 2; ++n) _Pragma("unroll") for (int k = 0; k < 2; ++k) dst[n][k] = *(const PG8_LAS bf16x8*)(lds + PG8_SB(b, h) + boff + n * 2048 + k * 1024); } while (0)
; #define PG8_WAIT_V(n) asm volatile("s_waitcnt vmcnt(" #n ")" ::: "memory")
; #define PG8_WAIT_L(n) asm volatile("s_waitcnt lgkmcnt(" #n ")" ::: "memory")
; #define PG8_BAR __builtin_amdgcn_s_barrier()
; #define PG8_SCHED __builtin_amdgcn_sched_barrier(0)
;     ...
;             const char* a1 = cA + (size_t)(t + 1) * kstep;
;             const char* a2 = last ? nA : cA + (size_t)(t + 2) * kstep; const char* b2 = last ? nB : cB + (size_t)(t + 2) * kstep;
;             const char* a3 = a2 + kstep; const char* b3 = b2 + kstep;
;             if (last && has_next) S.a_ready(nxt);
;             if constexpr (SP2) {
;             PG8_LDB(B0, 0, 0); PG8_LDB(B1, 0, 1); PG8_SCHED; PG8_LDA(At, 0, 0); PG8_STAGE(PG8_SA(1, 1), a1 + hstepA, voffA);
;             PG8_WAIT_V(8); PG8_WAIT_L(0); PG8_BAR; PG8_MMA(0, 0, At, B0); PG8_MMA(0, 1, At, B1); PG8_BAR; PG8_SCHED;
;             PG8_LDA(At, 0, 1); PG8_STAGE(PG8_SB(0, 0), b2, voffB); PG8_STAGE(PG8_SB(0, 1), b2 + hstepB, voffB); PG8_STAGE(PG8_SA(0, 0), a2, voffA);
;             PG8_WAIT_V(8); PG8_WAIT_L(0); PG8_BAR; PG8_MMA(1, 0, At, B0); PG8_MMA(1, 1, At, B1); PG8_BAR; PG8_SCHED;
.LBB0_923:
	s_add_u32 s56, s52, 0xfff80080
	s_addc_u32 s57, s53, -1
	s_add_i32 s68, 0, 0x10000
	s_cmp_eq_u32 s47, 28
	s_cselect_b32 s59, s6, s57
	s_cselect_b32 s58, s15, s56
	s_cselect_b32 s57, s34, s41
	s_cselect_b32 s56, s35, s37
	s_add_i32 s76, 0, 0x14000
	s_waitcnt vmcnt(0)
	v_add_u32_e32 v160, s68, v153
	v_add_u32_e32 v198, s76, v153
	ds_read_b128 v[132:135], v160
	ds_read_b128 v[136:139], v160 offset:1024
	ds_read_b128 v[156:159], v160 offset:2048
	ds_read_b128 v[160:163], v160 offset:3072
	ds_read_b128 v[186:189], v198
	ds_read_b128 v[190:193], v198 offset:1024
	ds_read_b128 v[194:197], v198 offset:2048
	ds_read_b128 v[198:201], v198 offset:3072
	s_add_i32 m0, s10, 0xc000
	ds_read_b128 v[202:205], v155
	ds_read_b128 v[206:209], v155 offset:1024
	ds_read_b128 v[210:213], v155 offset:2048
	ds_read_b128 v[214:217], v155 offset:3072
	ds_read_b128 v[218:221], v155 offset:4096
	ds_read_b128 v[222:225], v155 offset:5120
	ds_read_b128 v[234:237], v155 offset:6144
	ds_read_b128 v[238:241], v155 offset:7168
	global_load_lds_dwordx4 v148, s[52:53]
	s_add_i32 m0, s10, 0xe000
	s_nop 0
	global_load_lds_dwordx4 v150, s[52:53]
	s_waitcnt vmcnt(8)
	s_waitcnt lgkmcnt(0)
	s_barrier
	s_setprio 1
	v_mfma_f32_16x16x32_bf16 v[128:131], v[132:135], v[202:205], v[128:131]
	v_mfma_f32_16x16x32_bf16 v[124:127], v[156:159], v[202:205], v[124:127]
	v_mfma_f32_16x16x32_bf16 v[112:115], v[132:135], v[210:213], v[112:115]
	v_mfma_f32_16x16x32_bf16 v[108:111], v[156:159], v[210:213], v[108:111]
	v_mfma_f32_16x16x32_bf16 v[96:99], v[132:135], v[218:221], v[96:99]
	v_mfma_f32_16x16x32_bf16 v[92:95], v[156:159], v[218:221], v[92:95]
	v_mfma_f32_16x16x32_bf16 v[80:83], v[132:135], v[234:237], v[80:83]
	v_mfma_f32_16x16x32_bf16 v[76:79], v[156:159], v[234:237], v[76:79]
	v_mfma_f32_16x16x32_bf16 v[128:131], v[136:139], v[206:209], v[128:131]
	v_mfma_f32_16x16x32_bf16 v[124:127], v[160:163], v[206:209], v[124:127]
	v_mfma_f32_16x16x32_bf16 v[112:115], v[136:139], v[214:217], v[112:115]
	v_mfma_f32_16x16x32_bf16 v[108:111], v[160:163], v[214:217], v[108:111]
	v_mfma_f32_16x16x32_bf16 v[96:99], v[136:139], v[222:225], v[96:99]
	v_mfma_f32_16x16x32_bf16 v[92:95], v[160:163], v[222:225], v[92:95]
	v_mfma_f32_16x16x32_bf16 v[80:83], v[136:139], v[238:241], v[80:83]
	v_mfma_f32_16x16x32_bf16 v[76:79], v[160:163], v[238:241], v[76:79]
	v_mfma_f32_16x16x32_bf16 v[120:123], v[186:189], v[202:205], v[120:123]
	v_mfma_f32_16x16x32_bf16 v[116:119], v[194:197], v[202:205], v[116:119]
	v_mfma_f32_16x16x32_bf16 v[104:107], v[186:189], v[210:213], v[104:107]
	v_mfma_f32_16x16x32_bf16 v[100:103], v[194:197], v[210:213], v[100:103]
	v_mfma_f32_16x16x32_bf16 v[88:91], v[186:189], v[218:221], v[88:91]
	v_mfma_f32_16x16x32_bf16 v[84:87], v[194:197], v[218:221], v[84:87]
	v_mfma_f32_16x16x32_bf16 v[72:75], v[186:189], v[234:237], v[72:75]
	v_mfma_f32_16x16x32_bf16 v[68:71], v[194:197], v[234:237], v[68:71]
	v_mfma_f32_16x16x32_bf16 v[120:123], v[190:193], v[206:209], v[120:123]
	v_mfma_f32_16x16x32_bf16 v[116:119], v[198:201], v[206:209], v[116:119]
	v_mfma_f32_16x16x32_bf16 v[104:107], v[190:193], v[214:217], v[104:107]
	v_mfma_f32_16x16x32_bf16 v[100:103], v[198:201], v[214:217], v[100:103]
	v_mfma_f32_16x16x32_bf16 v[88:91], v[190:193], v[222:225], v[88:91]
	v_mfma_f32_16x16x32_bf16 v[84:87], v[198:201], v[222:225], v[84:87]
	v_mfma_f32_16x16x32_bf16 v[72:75], v[190:193], v[238:241], v[72:75]
	v_mfma_f32_16x16x32_bf16 v[68:71], v[198:201], v[238:241], v[68:71]
	s_setprio 0
	s_barrier
	s_add_i32 s68, s68, s9
	s_mov_b32 m0, s68
	ds_read_b128 v[202:205], v155 offset:16384
	ds_read_b128 v[206:209], v155 offset:17408
	ds_read_b128 v[210:213], v155 offset:18432
	ds_read_b128 v[214:217], v155 offset:19456
	ds_read_b128 v[218:221], v155 offset:20480
	ds_read_b128 v[222:225], v155 offset:21504
	ds_read_b128 v[234:237], v155 offset:22528
	ds_read_b128 v[238:241], v155 offset:23552
	global_load_lds_dwordx4 v142, s[56:57]
	s_add_i32 m0, s68, 0x2000
	s_add_u32 s70, s56, 0x80000
	v_lshl_add_u64 v[242:243], s[56:57], 0, v[146:147]
	s_addc_u32 s71, s57, 0
	s_add_i32 s68, s76, s9
	global_load_lds_dwordx4 v146, s[56:57]
	s_mov_b32 m0, s68
	v_lshl_add_u64 v[246:247], s[58:59], 0, v[144:145]
	global_load_lds_dwordx4 v142, s[70:71]
	s_add_i32 m0, s68, 0x2000
	s_nop 0
	global_load_lds_dwordx4 v146, s[70:71]
	v_lshl_add_u64 v[244:245], s[58:59], 0, v[140:141]
	s_mov_b32 m0, s10
	s_nop 0
	global_load_lds_dwordx4 v140, s[58:59]
	s_mov_b32 m0, s11
	s_nop 0
	global_load_lds_dwordx4 v144, s[58:59]
	s_waitcnt vmcnt(8)
	s_waitcnt lgkmcnt(0)
	s_barrier
; #define PG8_STAGE(bufoff, gbase, voff) do { _Pragma("unroll") for (int _i = 0; _i < 2; ++_i) \
;         __builtin_amdgcn_global_load_lds((const unsigned*)((const char*)(gbase) + (voff)[_i]), (PG8_LAS unsigned*)(lds + (bufoff) + ldsw + _i * 8192), 16, 0, 0); } while (0)
; #define PG8_LDA(dst, b, h) do { _Pragma("unroll") for (int m = 0; m < 4; ++m) _Pragma("unroll") for (int k = 0; k < 2; ++k) dst[m][k] = *(const PG8_LAS bf16x8*)(lds + PG8_SA(b, h) + aoff + m * 2048 + k * 1024); } while (0)
; #define PG8_LDB(dst, b, h) do { _Pragma("unroll") for (int n = 0; n < 2; ++n) _Pragma("unroll") for (int k = 0; k < 2; ++k) dst[n][k] = *(const PG8_LAS bf16x8*)(lds + PG8_SB(b, h) + boff + n * 2048 + k * 1024); } while (0)
; #define PG8_WAIT_V(n) asm volatile("s_waitcnt vmcnt(" #n ")" ::: "memory")
; #define PG8_WAIT_L(n) asm volatile("s_waitcnt lgkmcnt(" #n ")" ::: "memory")
; #define PG8_BAR __builtin_amdgcn_s_barrier()
; #define PG8_SCHED __builtin_amdgcn_sched_barrier(0)
;     ...
;             PG8_WAIT_V(8); PG8_WAIT_L(0); PG8_BAR; PG8_MMA(1, 0, At, B0); PG8_MMA(1, 1, At, B1); PG8_BAR; PG8_SCHED;
;             PG8_LDB(B0, 1, 0); PG8_LDB(B1, 1, 1); PG8_SCHED; PG8_LDA(At, 1, 0); PG8_STAGE(PG8_SA(0, 1), a2 + hstepA, voffA);
;             PG8_WAIT_V(8); PG8_WAIT_L(0); PG8_BAR; PG8_MMA(0, 0, At, B0); PG8_MMA(0, 1, At, B1); PG8_BAR; PG8_SCHED;
	s_setprio 1
	v_mfma_f32_16x16x32_bf16 v[64:67], v[132:135], v[202:205], v[64:67]
	v_mfma_f32_16x16x32_bf16 v[60:63], v[156:159], v[202:205], v[60:63]
	v_mfma_f32_16x16x32_bf16 v[48:51], v[132:135], v[210:213], v[48:51]
	v_mfma_f32_16x16x32_bf16 v[44:47], v[156:159], v[210:213], v[44:47]
	v_mfma_f32_16x16x32_bf16 v[30:33], v[132:135], v[218:221], v[30:33]
	v_mfma_f32_16x16x32_bf16 v[26:29], v[156:159], v[218:221], v[26:29]
	v_mfma_f32_16x16x32_bf16 v[14:17], v[132:135], v[234:237], v[14:17]
	v_mfma_f32_16x16x32_bf16 v[10:13], v[156:159], v[234:237], v[10:13]
	v_mfma_f32_16x16x32_bf16 v[64:67], v[136:139], v[206:209], v[64:67]
	v_mfma_f32_16x16x32_bf16 v[60:63], v[160:163], v[206:209], v[60:63]
	v_mfma_f32_16x16x32_bf16 v[48:51], v[136:139], v[214:217], v[48:51]
	v_mfma_f32_16x16x32_bf16 v[44:47], v[160:163], v[214:217], v[44:47]
	v_mfma_f32_16x16x32_bf16 v[30:33], v[136:139], v[222:225], v[30:33]
	v_mfma_f32_16x16x32_bf16 v[26:29], v[160:163], v[222:225], v[26:29]
	v_mfma_f32_16x16x32_bf16 v[14:17], v[136:139], v[238:241], v[14:17]
	v_mfma_f32_16x16x32_bf16 v[10:13], v[160:163], v[238:241], v[10:13]
	v_mfma_f32_16x16x32_bf16 v[56:59], v[186:189], v[202:205], v[56:59]
	v_mfma_f32_16x16x32_bf16 v[52:55], v[194:197], v[202:205], v[52:55]
	v_mfma_f32_16x16x32_bf16 v[40:43], v[186:189], v[210:213], v[40:43]
	v_mfma_f32_16x16x32_bf16 v[36:39], v[194:197], v[210:213], v[36:39]
	v_mfma_f32_16x16x32_bf16 v[22:25], v[186:189], v[218:221], v[22:25]
	v_mfma_f32_16x16x32_bf16 v[18:21], v[194:197], v[218:221], v[18:21]
	v_mfma_f32_16x16x32_bf16 v[6:9], v[186:189], v[234:237], v[6:9]
	v_mfma_f32_16x16x32_bf16 v[2:5], v[194:197], v[234:237], v[2:5]
	v_mfma_f32_16x16x32_bf16 v[56:59], v[190:193], v[206:209], v[56:59]
	v_mfma_f32_16x16x32_bf16 v[52:55], v[198:201], v[206:209], v[52:55]
	v_mfma_f32_16x16x32_bf16 v[40:43], v[190:193], v[214:217], v[40:43]
	v_mfma_f32_16x16x32_bf16 v[36:39], v[198:201], v[214:217], v[36:39]
	v_mfma_f32_16x16x32_bf16 v[22:25], v[190:193], v[222:225], v[22:25]
	v_mfma_f32_16x16x32_bf16 v[18:21], v[198:201], v[222:225], v[18:21]
	v_mfma_f32_16x16x32_bf16 v[6:9], v[190:193], v[238:241], v[6:9]
	v_mfma_f32_16x16x32_bf16 v[2:5], v[198:201], v[238:241], v[2:5]
	s_setprio 0
	s_barrier
	s_add_i32 s68, 0, 0x18000
	s_add_i32 s70, 0, 0x1c000
	v_add_u32_e32 v160, s68, v153
	v_add_u32_e32 v198, s70, v153
	ds_read_b128 v[132:135], v160
	ds_read_b128 v[136:139], v160 offset:1024
	ds_read_b128 v[156:159], v160 offset:2048
	ds_read_b128 v[160:163], v160 offset:3072
	ds_read_b128 v[186:189], v198
	ds_read_b128 v[190:193], v198 offset:1024
	ds_read_b128 v[194:197], v198 offset:2048
	ds_read_b128 v[198:201], v198 offset:3072
	s_add_u32 s58, s58, 0x80000
	s_addc_u32 s59, s59, 0
	s_mov_b32 m0, s12
	ds_read_b128 v[202:205], v155 offset:32768
	ds_read_b128 v[206:209], v155 offset:33792
	ds_read_b128 v[210:213], v155 offset:34816
	ds_read_b128 v[214:217], v155 offset:35840
	ds_read_b128 v[218:221], v155 offset:36864
	ds_read_b128 v[222:225], v155 offset:37888
	ds_read_b128 v[234:237], v155 offset:38912
	ds_read_b128 v[238:241], v155 offset:39936
	global_load_lds_dwordx4 v140, s[58:59]
	v_lshl_add_u64 v[248:249], s[58:59], 0, v[144:145]
	s_mov_b32 m0, s13
	s_nop 0
	global_load_lds_dwordx4 v144, s[58:59]
	s_waitcnt vmcnt(8)
	s_waitcnt lgkmcnt(0)
	s_barrier
	s_setprio 1
	v_mfma_f32_16x16x32_bf16 v[128:131], v[132:135], v[202:205], v[128:131]
	v_mfma_f32_16x16x32_bf16 v[124:127], v[156:159], v[202:205], v[124:127]
	v_mfma_f32_16x16x32_bf16 v[112:115], v[132:135], v[210:213], v[112:115]
	v_mfma_f32_16x16x32_bf16 v[108:111], v[156:159], v[210:213], v[108:111]
	v_mfma_f32_16x16x32_bf16 v[96:99], v[132:135], v[218:221], v[96:99]
	v_mfma_f32_16x16x32_bf16 v[92:95], v[156:159], v[218:221], v[92:95]
	v_mfma_f32_16x16x32_bf16 v[80:83], v[132:135], v[234:237], v[80:83]
	v_mfma_f32_16x16x32_bf16 v[76:79], v[156:159], v[234:237], v[76:79]
	v_mfma_f32_16x16x32_bf16 v[128:131], v[136:139], v[206:209], v[128:131]
	v_mfma_f32_16x16x32_bf16 v[124:127], v[160:163], v[206:209], v[124:127]
	v_mfma_f32_16x16x32_bf16 v[112:115], v[136:139], v[214:217], v[112:115]
	v_mfma_f32_16x16x32_bf16 v[108:111], v[160:163], v[214:217], v[108:111]
	v_mfma_f32_16x16x32_bf16 v[96:99], v[136:139], v[222:225], v[96:99]
	v_mfma_f32_16x16x32_bf16 v[92:95], v[160:163], v[222:225], v[92:95]
	v_mfma_f32_16x16x32_bf16 v[80:83], v[136:139], v[238:241], v[80:83]
	v_mfma_f32_16x16x32_bf16 v[76:79], v[160:163], v[238:241], v[76:79]
	v_mfma_f32_16x16x32_bf16 v[120:123], v[186:189], v[202:205], v[120:123]
	v_mfma_f32_16x16x32_bf16 v[116:119], v[194:197], v[202:205], v[116:119]
	v_mfma_f32_16x16x32_bf16 v[104:107], v[186:189], v[210:213], v[104:107]
	v_mfma_f32_16x16x32_bf16 v[100:103], v[194:197], v[210:213], v[100:103]
	v_mfma_f32_16x16x32_bf16 v[88:91], v[186:189], v[218:221], v[88:91]
	v_mfma_f32_16x16x32_bf16 v[84:87], v[194:197], v[218:221], v[84:87]
	v_mfma_f32_16x16x32_bf16 v[72:75], v[186:189], v[234:237], v[72:75]
	v_mfma_f32_16x16x32_bf16 v[68:71], v[194:197], v[234:237], v[68:71]
	v_mfma_f32_16x16x32_bf16 v[120:123], v[190:193], v[206:209], v[120:123]
	v_mfma_f32_16x16x32_bf16 v[116:119], v[198:201], v[206:209], v[116:119]
	v_mfma_f32_16x16x32_bf16 v[104:107], v[190:193], v[214:217], v[104:107]
	v_mfma_f32_16x16x32_bf16 v[100:103], v[198:201], v[214:217], v[100:103]
	v_mfma_f32_16x16x32_bf16 v[88:91], v[190:193], v[222:225], v[88:91]
	v_mfma_f32_16x16x32_bf16 v[84:87], v[198:201], v[222:225], v[84:87]
	v_mfma_f32_16x16x32_bf16 v[72:75], v[190:193], v[238:241], v[72:75]
	v_mfma_f32_16x16x32_bf16 v[68:71], v[198:201], v[238:241], v[68:71]
	s_setprio 0
	s_barrier
; #define PG8_STAGE(bufoff, gbase, voff) do { _Pragma("unroll") for (int _i = 0; _i < 2; ++_i) \
;         __builtin_amdgcn_global_load_lds((const unsigned*)((const char*)(gbase) + (voff)[_i]), (PG8_LAS unsigned*)(lds + (bufoff) + ldsw + _i * 8192), 16, 0, 0); } while (0)
; #define PG8_LDA(dst, b, h) do { _Pragma("unroll") for (int m = 0; m < 4; ++m) _Pragma("unroll") for (int k = 0; k < 2; ++k) dst[m][k] = *(const PG8_LAS bf16x8*)(lds + PG8_SA(b, h) + aoff + m * 2048 + k * 1024); } while (0)
; #define PG8_WAIT_V(n) asm volatile("s_waitcnt vmcnt(" #n ")" ::: "memory")
; #define PG8_WAIT_L(n) asm volatile("s_waitcnt lgkmcnt(" #n ")" ::: "memory")
; #define PG8_BAR __builtin_amdgcn_s_barrier()
; #define PG8_SCHED __builtin_amdgcn_sched_barrier(0)
;     ...
;         for (int t = 0; t < nt; t += 2) {
;             const bool last = (t == nt - 2);
;             const char* a1 = cA + (size_t)(t + 1) * kstep;
;             const char* a2 = last ? nA : cA + (size_t)(t + 2) * kstep; const char* b2 = last ? nB : cB + (size_t)(t + 2) * kstep;
;             const char* a3 = a2 + kstep; const char* b3 = b2 + kstep;
;     ...
;             PG8_LDA(At, 1, 1); PG8_STAGE(PG8_SB(1, 0), b3, voffB); PG8_STAGE(PG8_SB(1, 1), b3 + hstepB, voffB); PG8_STAGE(PG8_SA(1, 0), a3, voffA);
;             PG8_WAIT_V(8); PG8_WAIT_L(0); PG8_BAR; PG8_MMA(1, 0, At, B0); PG8_MMA(1, 1, At, B1); PG8_BAR; PG8_SCHED;
	s_add_i32 s58, s68, s9
	s_mov_b32 m0, s58
	ds_read_b128 v[202:205], v155 offset:49152
	ds_read_b128 v[206:209], v155 offset:50176
	ds_read_b128 v[210:213], v155 offset:51200
	ds_read_b128 v[214:217], v155 offset:52224
	ds_read_b128 v[218:221], v155 offset:53248
	ds_read_b128 v[222:225], v155 offset:54272
	ds_read_b128 v[234:237], v155 offset:55296
	ds_read_b128 v[238:241], v155 offset:56320
	s_add_u32 s98, s56, 0x80
	s_addc_u32 s99, s57, 0
	global_load_lds_dwordx4 v142, s[98:99]
	s_add_i32 m0, s58, 0x2000
	s_add_u32 s56, s56, 0x80080
	s_addc_u32 s57, s57, 0
	s_add_i32 s58, s70, s9
	s_add_u32 s98, s56, 0xfff80000
	s_addc_u32 s99, s57, -1
	global_load_lds_dwordx4 v146, s[98:99]
	s_mov_b32 m0, s58
	s_nop 0
	global_load_lds_dwordx4 v142, s[56:57]
	s_add_i32 m0, s58, 0x2000
	s_nop 0
	global_load_lds_dwordx4 v146, s[56:57]
	v_lshl_add_u64 v[226:227], v[244:245], 0, s[22:23]
	s_mov_b32 m0, s55
	s_nop 0
	global_load_lds_dwordx4 v[226:227], off
	v_lshl_add_u64 v[226:227], v[246:247], 0, s[22:23]
	s_mov_b32 m0, s66
	s_nop 0
	global_load_lds_dwordx4 v[226:227], off
	s_waitcnt vmcnt(8)
	s_waitcnt lgkmcnt(0)
	s_barrier
	s_setprio 1
	v_mfma_f32_16x16x32_bf16 v[64:67], v[132:135], v[202:205], v[64:67]
	v_mfma_f32_16x16x32_bf16 v[60:63], v[156:159], v[202:205], v[60:63]
	v_mfma_f32_16x16x32_bf16 v[48:51], v[132:135], v[210:213], v[48:51]
	v_mfma_f32_16x16x32_bf16 v[44:47], v[156:159], v[210:213], v[44:47]
	v_mfma_f32_16x16x32_bf16 v[30:33], v[132:135], v[218:221], v[30:33]
	v_mfma_f32_16x16x32_bf16 v[26:29], v[156:159], v[218:221], v[26:29]
	v_mfma_f32_16x16x32_bf16 v[14:17], v[132:135], v[234:237], v[14:17]
	v_mfma_f32_16x16x32_bf16 v[10:13], v[156:159], v[234:237], v[10:13]
	v_mfma_f32_16x16x32_bf16 v[64:67], v[136:139], v[206:209], v[64:67]
	v_mfma_f32_16x16x32_bf16 v[60:63], v[160:163], v[206:209], v[60:63]
	v_mfma_f32_16x16x32_bf16 v[48:51], v[136:139], v[214:217], v[48:51]
	v_mfma_f32_16x16x32_bf16 v[44:47], v[160:163], v[214:217], v[44:47]
	v_mfma_f32_16x16x32_bf16 v[30:33], v[136:139], v[222:225], v[30:33]
	v_mfma_f32_16x16x32_bf16 v[26:29], v[160:163], v[222:225], v[26:29]
	v_mfma_f32_16x16x32_bf16 v[14:17], v[136:139], v[238:241], v[14:17]
	v_mfma_f32_16x16x32_bf16 v[10:13], v[160:163], v[238:241], v[10:13]
	v_mfma_f32_16x16x32_bf16 v[56:59], v[186:189], v[202:205], v[56:59]
	v_mfma_f32_16x16x32_bf16 v[52:55], v[194:197], v[202:205], v[52:55]
	v_mfma_f32_16x16x32_bf16 v[40:43], v[186:189], v[210:213], v[40:43]
	v_mfma_f32_16x16x32_bf16 v[36:39], v[194:197], v[210:213], v[36:39]
	v_mfma_f32_16x16x32_bf16 v[22:25], v[186:189], v[218:221], v[22:25]
	v_mfma_f32_16x16x32_bf16 v[18:21], v[194:197], v[218:221], v[18:21]
	v_mfma_f32_16x16x32_bf16 v[6:9], v[186:189], v[234:237], v[6:9]
	v_mfma_f32_16x16x32_bf16 v[2:5], v[194:197], v[234:237], v[2:5]
	v_mfma_f32_16x16x32_bf16 v[56:59], v[190:193], v[206:209], v[56:59]
	v_mfma_f32_16x16x32_bf16 v[52:55], v[198:201], v[206:209], v[52:55]
	v_mfma_f32_16x16x32_bf16 v[40:43], v[190:193], v[214:217], v[40:43]
	v_mfma_f32_16x16x32_bf16 v[36:39], v[198:201], v[214:217], v[36:39]
	v_mfma_f32_16x16x32_bf16 v[22:25], v[190:193], v[222:225], v[22:25]
	v_mfma_f32_16x16x32_bf16 v[18:21], v[198:201], v[222:225], v[18:21]
	v_mfma_f32_16x16x32_bf16 v[6:9], v[190:193], v[238:241], v[6:9]
	v_mfma_f32_16x16x32_bf16 v[2:5], v[198:201], v[238:241], v[2:5]
	s_setprio 0
	s_barrier
	s_add_i32 s47, s47, 2
	s_add_u32 s52, s52, 0x100
	s_addc_u32 s53, s53, 0
	s_add_u32 s37, s37, 0x100
	s_addc_u32 s41, s41, 0
	s_cmp_gt_u32 s47, 29
	s_cbranch_scc0 .LBB0_923
	s_and_b64 vcc, exec, s[30:31]
	s_cbranch_vccz .LBB0_926
	s_barrier

; #define PG8_STAGE(bufoff, gbase, voff) do { _Pragma("unroll") for (int _i = 0; _i < 2; ++_i) \
;         __builtin_amdgcn_global_load_lds((const unsigned*)((const char*)(gbase) + (voff)[_i]), (PG8_LAS unsigned*)(lds + (bufoff) + ldsw + _i * 8192), 16, 0, 0); } while (0)
; #define PG8_LDA(dst, b, h) do { _Pragma("unroll") for (int m = 0; m < 4; ++m) _Pragma("unroll") for (int k = 0; k < 2; ++k) dst[m][k] = *(const PG8_LAS bf16x8*)(lds + PG8_SA(b, h) + aoff + m * 2048 + k * 1024); } while (0)
; #define PG8_LDB(dst, b, h) do { _Pragma("unroll") for (int n = 0; n < 2; ++n) _Pragma("unroll") for (int k = 0; k < 2; ++k) dst[n][k] = *(const PG8_LAS bf16x8*)(lds + PG8_SB(b, h) + boff + n * 2048 + k * 1024); } while (0)
; #define PG8_WAIT_V(n) asm volatile("s_waitcnt vmcnt(" #n ")" ::: "memory")
; #define PG8_WAIT_L(n) asm volatile("s_waitcnt lgkmcnt(" #n ")" ::: "memory")
; #define PG8_BAR __builtin_amdgcn_s_barrier()
; #define PG8_SCHED __builtin_amdgcn_sched_barrier(0)
;     ...
;             const bool last = (t == nt - 2);
;             const char* a1 = cA + (size_t)(t + 1) * kstep;
;             const char* a2 = last ? nA : cA + (size_t)(t + 2) * kstep; const char* b2 = last ? nB : cB + (size_t)(t + 2) * kstep;
;             const char* a3 = a2 + kstep; const char* b3 = b2 + kstep;
;             if (last && has_next) S.a_ready(nxt);
;             if constexpr (SP2) {
;             PG8_LDB(B0, 0, 0); PG8_LDB(B1, 0, 1); PG8_SCHED; PG8_LDA(At, 0, 0); PG8_STAGE(PG8_SA(1, 1), a1 + hstepA, voffA);
;             PG8_WAIT_V(8); PG8_WAIT_L(0); PG8_BAR; PG8_MMA(0, 0, At, B0); PG8_MMA(0, 1, At, B1); PG8_BAR; PG8_SCHED;
;             PG8_LDA(At, 0, 1); PG8_STAGE(PG8_SB(0, 0), b2, voffB); PG8_STAGE(PG8_SB(0, 1), b2 + hstepB, voffB); PG8_STAGE(PG8_SA(0, 0), a2, voffA);
;             PG8_WAIT_V(8); PG8_WAIT_L(0); PG8_BAR; PG8_MMA(1, 0, At, B0); PG8_MMA(1, 1, At, B1); PG8_BAR; PG8_SCHED;
.LBB0_1133:
	s_add_u32 s52, s50, 0xfffc0080
	s_addc_u32 s53, s51, -1
	s_add_i32 s75, 0, 0x10000
	s_cmp_eq_u32 s74, 12
	s_cselect_b32 s55, s37, s53
	s_cselect_b32 s54, s67, s52
	s_cselect_b32 s53, s31, s71
	s_cselect_b32 s52, s68, s70
	s_add_i32 s76, 0, 0x14000
	v_add_u32_e32 v2, s75, v208
	v_add_u32_e32 v6, s76, v208
	ds_read_b128 v[26:29], v2
	ds_read_b128 v[30:33], v2 offset:1024
	ds_read_b128 v[18:21], v2 offset:2048
	ds_read_b128 v[22:25], v2 offset:3072
	ds_read_b128 v[10:13], v6
	ds_read_b128 v[14:17], v6 offset:1024
	ds_read_b128 v[2:5], v6 offset:2048
	ds_read_b128 v[6:9], v6 offset:3072
	s_add_i32 m0, s57, 0xc000
	ds_read_b128 v[198:201], v209
	ds_read_b128 v[202:205], v209 offset:1024
	ds_read_b128 v[210:213], v209 offset:2048
	ds_read_b128 v[214:217], v209 offset:3072
	ds_read_b128 v[218:221], v209 offset:4096
	ds_read_b128 v[222:225], v209 offset:5120
	ds_read_b128 v[234:237], v209 offset:6144
	ds_read_b128 v[238:241], v209 offset:7168
	global_load_lds_dwordx4 v194, s[50:51]
	s_add_i32 m0, s57, 0xe000
	s_nop 0
	global_load_lds_dwordx4 v196, s[50:51]
	s_waitcnt vmcnt(8)
	s_waitcnt lgkmcnt(0)
	s_barrier
	s_setprio 1
	v_mfma_f32_16x16x128_f8f6f4 v[160:163], v[26:33], v[198:205], v[160:163]
	v_mfma_f32_16x16x128_f8f6f4 v[156:159], v[18:25], v[198:205], v[156:159]
	v_mfma_f32_16x16x128_f8f6f4 v[144:147], v[26:33], v[210:217], v[144:147]
	v_mfma_f32_16x16x128_f8f6f4 v[140:143], v[18:25], v[210:217], v[140:143]
	v_mfma_f32_16x16x128_f8f6f4 v[128:131], v[26:33], v[218:225], v[128:131]
	v_mfma_f32_16x16x128_f8f6f4 v[124:127], v[18:25], v[218:225], v[124:127]
	v_mfma_f32_16x16x128_f8f6f4 v[112:115], v[26:33], v[234:241], v[112:115]
	v_mfma_f32_16x16x128_f8f6f4 v[108:111], v[18:25], v[234:241], v[108:111]
	v_mfma_f32_16x16x128_f8f6f4 v[152:155], v[10:17], v[198:205], v[152:155]
	v_mfma_f32_16x16x128_f8f6f4 v[148:151], v[2:9], v[198:205], v[148:151]
	v_mfma_f32_16x16x128_f8f6f4 v[136:139], v[10:17], v[210:217], v[136:139]
	v_mfma_f32_16x16x128_f8f6f4 v[132:135], v[2:9], v[210:217], v[132:135]
	v_mfma_f32_16x16x128_f8f6f4 v[120:123], v[10:17], v[218:225], v[120:123]
	v_mfma_f32_16x16x128_f8f6f4 v[116:119], v[2:9], v[218:225], v[116:119]
	v_mfma_f32_16x16x128_f8f6f4 v[104:107], v[10:17], v[234:241], v[104:107]
	v_mfma_f32_16x16x128_f8f6f4 v[100:103], v[2:9], v[234:241], v[100:103]
	s_setprio 0
	s_barrier
	s_add_i32 s75, s75, s11
	s_mov_b32 m0, s75
	ds_read_b128 v[210:213], v209 offset:16384
	ds_read_b128 v[214:217], v209 offset:17408
	ds_read_b128 v[218:221], v209 offset:18432
	ds_read_b128 v[222:225], v209 offset:19456
	ds_read_b128 v[234:237], v209 offset:20480
	ds_read_b128 v[238:241], v209 offset:21504
	ds_read_b128 v[242:245], v209 offset:22528
	ds_read_b128 v[246:249], v209 offset:23552
	global_load_lds_dwordx4 v34, s[52:53]
	s_add_i32 m0, s75, 0x2000
	s_add_u32 s78, s52, 0x40000
	s_addc_u32 s79, s53, 0
	s_add_i32 s75, s76, s11
	global_load_lds_dwordx4 v186, s[52:53]
	s_mov_b32 m0, s75
	v_lshl_add_u64 v[204:205], s[54:55], 0, v[188:189]
	global_load_lds_dwordx4 v34, s[78:79]
	s_add_i32 m0, s75, 0x2000
	s_nop 0
	global_load_lds_dwordx4 v186, s[78:79]
	v_lshl_add_u64 v[202:203], s[54:55], 0, v[190:191]
	s_mov_b32 m0, s57
	s_nop 0
	global_load_lds_dwordx4 v190, s[54:55]
	s_mov_b32 m0, s6
	s_nop 0
	global_load_lds_dwordx4 v188, s[54:55]
	s_waitcnt vmcnt(8)
	s_waitcnt lgkmcnt(0)
	s_barrier
	s_setprio 1
	v_mfma_f32_16x16x128_f8f6f4 v[96:99], v[26:33], v[210:217], v[96:99]
	v_mfma_f32_16x16x128_f8f6f4 v[92:95], v[18:25], v[210:217], v[92:95]
	v_mfma_f32_16x16x128_f8f6f4 v[80:83], v[26:33], v[218:225], v[80:83]
	v_mfma_f32_16x16x128_f8f6f4 v[76:79], v[18:25], v[218:225], v[76:79]
	v_mfma_f32_16x16x128_f8f6f4 v[64:67], v[26:33], v[234:241], v[64:67]
	v_mfma_f32_16x16x128_f8f6f4 v[60:63], v[18:25], v[234:241], v[60:63]
	v_mfma_f32_16x16x128_f8f6f4 v[48:51], v[26:33], v[242:249], v[48:51]
	v_mfma_f32_16x16x128_f8f6f4 v[44:47], v[18:25], v[242:249], v[44:47]
	v_mfma_f32_16x16x128_f8f6f4 v[88:91], v[10:17], v[210:217], v[88:91]
	v_mfma_f32_16x16x128_f8f6f4 v[84:87], v[2:9], v[210:217], v[84:87]
	v_mfma_f32_16x16x128_f8f6f4 v[72:75], v[10:17], v[218:225], v[72:75]
	v_mfma_f32_16x16x128_f8f6f4 v[68:71], v[2:9], v[218:225], v[68:71]
	v_mfma_f32_16x16x128_f8f6f4 v[56:59], v[10:17], v[234:241], v[56:59]
	v_mfma_f32_16x16x128_f8f6f4 v[52:55], v[2:9], v[234:241], v[52:55]
	v_mfma_f32_16x16x128_f8f6f4 v[40:43], v[10:17], v[242:249], v[40:43]
	v_mfma_f32_16x16x128_f8f6f4 v[36:39], v[2:9], v[242:249], v[36:39]
	s_setprio 0
	s_barrier
; #define PG8_STAGE(bufoff, gbase, voff) do { _Pragma("unroll") for (int _i = 0; _i < 2; ++_i) \
;         __builtin_amdgcn_global_load_lds((const unsigned*)((const char*)(gbase) + (voff)[_i]), (PG8_LAS unsigned*)(lds + (bufoff) + ldsw + _i * 8192), 16, 0, 0); } while (0)
; #define PG8_LDA(dst, b, h) do { _Pragma("unroll") for (int m = 0; m < 4; ++m) _Pragma("unroll") for (int k = 0; k < 2; ++k) dst[m][k] = *(const PG8_LAS bf16x8*)(lds + PG8_SA(b, h) + aoff + m * 2048 + k * 1024); } while (0)
; #define PG8_LDB(dst, b, h) do { _Pragma("unroll") for (int n = 0; n < 2; ++n) _Pragma("unroll") for (int k = 0; k < 2; ++k) dst[n][k] = *(const PG8_LAS bf16x8*)(lds + PG8_SB(b, h) + boff + n * 2048 + k * 1024); } while (0)
; #define PG8_WAIT_V(n) asm volatile("s_waitcnt vmcnt(" #n ")" ::: "memory")
; #define PG8_WAIT_L(n) asm volatile("s_waitcnt lgkmcnt(" #n ")" ::: "memory")
; #define PG8_BAR __builtin_amdgcn_s_barrier()
; #define PG8_SCHED __builtin_amdgcn_sched_barrier(0)
;     ...
;             PG8_LDB(B0, 1, 0); PG8_LDB(B1, 1, 1); PG8_SCHED; PG8_LDA(At, 1, 0); PG8_STAGE(PG8_SA(0, 1), a2 + hstepA, voffA);
;             PG8_WAIT_V(8); PG8_WAIT_L(0); PG8_BAR; PG8_MMA(0, 0, At, B0); PG8_MMA(0, 1, At, B1); PG8_BAR; PG8_SCHED;
;             PG8_LDA(At, 1, 1); PG8_STAGE(PG8_SB(1, 0), b3, voffB); PG8_STAGE(PG8_SB(1, 1), b3 + hstepB, voffB); PG8_STAGE(PG8_SA(1, 0), a3, voffA);
;             PG8_WAIT_V(8); PG8_WAIT_L(0); PG8_BAR; PG8_MMA(1, 0, At, B0); PG8_MMA(1, 1, At, B1); PG8_BAR; PG8_SCHED;
	s_add_i32 s75, 0, 0x18000
	s_add_i32 s76, 0, 0x1c000
	v_add_u32_e32 v14, s75, v208
	v_add_u32_e32 v30, s76, v208
	ds_read_b128 v[2:5], v14
	ds_read_b128 v[6:9], v14 offset:1024
	ds_read_b128 v[10:13], v14 offset:2048
	ds_read_b128 v[14:17], v14 offset:3072
	ds_read_b128 v[18:21], v30
	ds_read_b128 v[22:25], v30 offset:1024
	ds_read_b128 v[26:29], v30 offset:2048
	ds_read_b128 v[30:33], v30 offset:3072
	s_add_u32 s54, s54, 0x40000
	s_addc_u32 s55, s55, 0
	s_mov_b32 m0, s15
	ds_read_b128 v[210:213], v209 offset:32768
	ds_read_b128 v[214:217], v209 offset:33792
	ds_read_b128 v[218:221], v209 offset:34816
	ds_read_b128 v[222:225], v209 offset:35840
	ds_read_b128 v[234:237], v209 offset:36864
	ds_read_b128 v[238:241], v209 offset:37888
	ds_read_b128 v[242:245], v209 offset:38912
	ds_read_b128 v[246:249], v209 offset:39936
	global_load_lds_dwordx4 v190, s[54:55]
	v_lshl_add_u64 v[226:227], s[54:55], 0, v[188:189]
	s_mov_b32 m0, s34
	s_nop 0
	global_load_lds_dwordx4 v188, s[54:55]
	s_waitcnt vmcnt(8)
	s_waitcnt lgkmcnt(0)
	s_barrier
	s_setprio 1
	v_mfma_f32_16x16x128_f8f6f4 v[160:163], v[2:9], v[210:217], v[160:163]
	v_mfma_f32_16x16x128_f8f6f4 v[156:159], v[10:17], v[210:217], v[156:159]
	v_mfma_f32_16x16x128_f8f6f4 v[144:147], v[2:9], v[218:225], v[144:147]
	v_mfma_f32_16x16x128_f8f6f4 v[140:143], v[10:17], v[218:225], v[140:143]
	v_mfma_f32_16x16x128_f8f6f4 v[128:131], v[2:9], v[234:241], v[128:131]
	v_mfma_f32_16x16x128_f8f6f4 v[124:127], v[10:17], v[234:241], v[124:127]
	v_mfma_f32_16x16x128_f8f6f4 v[112:115], v[2:9], v[242:249], v[112:115]
	v_mfma_f32_16x16x128_f8f6f4 v[108:111], v[10:17], v[242:249], v[108:111]
	v_mfma_f32_16x16x128_f8f6f4 v[152:155], v[18:25], v[210:217], v[152:155]
	v_mfma_f32_16x16x128_f8f6f4 v[148:151], v[26:33], v[210:217], v[148:151]
	v_mfma_f32_16x16x128_f8f6f4 v[136:139], v[18:25], v[218:225], v[136:139]
	v_mfma_f32_16x16x128_f8f6f4 v[132:135], v[26:33], v[218:225], v[132:135]
	v_mfma_f32_16x16x128_f8f6f4 v[120:123], v[18:25], v[234:241], v[120:123]
	v_mfma_f32_16x16x128_f8f6f4 v[116:119], v[26:33], v[234:241], v[116:119]
	v_mfma_f32_16x16x128_f8f6f4 v[104:107], v[18:25], v[242:249], v[104:107]
	v_mfma_f32_16x16x128_f8f6f4 v[100:103], v[26:33], v[242:249], v[100:103]
	s_setprio 0
	s_barrier
	s_add_i32 s54, s75, s11
	s_mov_b32 m0, s54
	ds_read_b128 v[210:213], v209 offset:49152
	ds_read_b128 v[214:217], v209 offset:50176
	ds_read_b128 v[218:221], v209 offset:51200
	ds_read_b128 v[222:225], v209 offset:52224
	ds_read_b128 v[234:237], v209 offset:53248
	ds_read_b128 v[238:241], v209 offset:54272
	ds_read_b128 v[242:245], v209 offset:55296
	ds_read_b128 v[246:249], v209 offset:56320
	s_add_u32 s98, s52, 0x80
	s_addc_u32 s99, s53, 0
	global_load_lds_dwordx4 v34, s[98:99]
	s_add_i32 m0, s54, 0x2000
	s_add_u32 s52, s52, 0x40080
	s_addc_u32 s53, s53, 0
	s_add_i32 s54, s76, s11
	s_add_u32 s98, s52, 0xfffc0000
	s_addc_u32 s99, s53, -1
	global_load_lds_dwordx4 v186, s[98:99]
	s_mov_b32 m0, s54
	s_nop 0
	global_load_lds_dwordx4 v34, s[52:53]
	s_add_i32 m0, s54, 0x2000
	s_nop 0
	global_load_lds_dwordx4 v186, s[52:53]
	v_lshl_add_u64 v[198:199], v[202:203], 0, s[22:23]
	s_mov_b32 m0, s35
	s_nop 0
	global_load_lds_dwordx4 v[198:199], off
	v_lshl_add_u64 v[198:199], v[204:205], 0, s[22:23]
	s_mov_b32 m0, s58
	s_nop 0
	global_load_lds_dwordx4 v[198:199], off
	s_waitcnt vmcnt(8)
	s_waitcnt lgkmcnt(0)
	s_barrier
	s_setprio 1
	v_mfma_f32_16x16x128_f8f6f4 v[96:99], v[2:9], v[210:217], v[96:99]
	v_mfma_f32_16x16x128_f8f6f4 v[92:95], v[10:17], v[210:217], v[92:95]
	v_mfma_f32_16x16x128_f8f6f4 v[80:83], v[2:9], v[218:225], v[80:83]
	v_mfma_f32_16x16x128_f8f6f4 v[76:79], v[10:17], v[218:225], v[76:79]
	v_mfma_f32_16x16x128_f8f6f4 v[64:67], v[2:9], v[234:241], v[64:67]
	v_mfma_f32_16x16x128_f8f6f4 v[60:63], v[10:17], v[234:241], v[60:63]
	v_mfma_f32_16x16x128_f8f6f4 v[48:51], v[2:9], v[242:249], v[48:51]
	v_mfma_f32_16x16x128_f8f6f4 v[44:47], v[10:17], v[242:249], v[44:47]
	v_mfma_f32_16x16x128_f8f6f4 v[88:91], v[18:25], v[210:217], v[88:91]
	v_mfma_f32_16x16x128_f8f6f4 v[84:87], v[26:33], v[210:217], v[84:87]
	v_mfma_f32_16x16x128_f8f6f4 v[72:75], v[18:25], v[218:225], v[72:75]
	v_mfma_f32_16x16x128_f8f6f4 v[68:71], v[26:33], v[218:225], v[68:71]
	v_mfma_f32_16x16x128_f8f6f4 v[56:59], v[18:25], v[234:241], v[56:59]
	v_mfma_f32_16x16x128_f8f6f4 v[52:55], v[26:33], v[234:241], v[52:55]
	v_mfma_f32_16x16x128_f8f6f4 v[40:43], v[18:25], v[242:249], v[40:43]
	v_mfma_f32_16x16x128_f8f6f4 v[36:39], v[26:33], v[242:249], v[36:39]
	s_setprio 0
	s_barrier
	s_add_i32 s74, s74, 2
	s_add_u32 s50, s50, 0x100
	s_addc_u32 s51, s51, 0
	s_add_u32 s70, s70, 0x100
	s_addc_u32 s71, s71, 0
	s_cmp_gt_u32 s74, 13
	s_cbranch_scc0 .LBB0_1133
	s_and_b64 vcc, exec, s[28:29]
	s_cbranch_vccz .LBB0_1136
	s_barrier

; #define PG8_STAGE(bufoff, gbase, voff) do { _Pragma("unroll") for (int _i = 0; _i < 2; ++_i) \
;         __builtin_amdgcn_global_load_lds((const unsigned*)((const char*)(gbase) + (voff)[_i]), (PG8_LAS unsigned*)(lds + (bufoff) + ldsw + _i * 8192), 16, 0, 0); } while (0)
; #define PG8_LDA(dst, b, h) do { _Pragma("unroll") for (int m = 0; m < 4; ++m) _Pragma("unroll") for (int k = 0; k < 2; ++k) dst[m][k] = *(const PG8_LAS bf16x8*)(lds + PG8_SA(b, h) + aoff + m * 2048 + k * 1024); } while (0)
; #define PG8_LDB(dst, b, h) do { _Pragma("unroll") for (int n = 0; n < 2; ++n) _Pragma("unroll") for (int k = 0; k < 2; ++k) dst[n][k] = *(const PG8_LAS bf16x8*)(lds + PG8_SB(b, h) + boff + n * 2048 + k * 1024); } while (0)
; #define PG8_WAIT_V(n) asm volatile("s_waitcnt vmcnt(" #n ")" ::: "memory")
; #define PG8_WAIT_L(n) asm volatile("s_waitcnt lgkmcnt(" #n ")" ::: "memory")
; #define PG8_BAR __builtin_amdgcn_s_barrier()
; #define PG8_SCHED __builtin_amdgcn_sched_barrier(0)
;     ...
;             const bool last = (t == nt - 2);
;             const char* a1 = cA + (size_t)(t + 1) * kstep;
;             const char* a2 = last ? nA : cA + (size_t)(t + 2) * kstep; const char* b2 = last ? nB : cB + (size_t)(t + 2) * kstep;
;             const char* a3 = a2 + kstep; const char* b3 = b2 + kstep;
;             if (last && has_next) S.a_ready(nxt);
;             if constexpr (SP2) {
;             PG8_LDB(B0, 0, 0); PG8_LDB(B1, 0, 1); PG8_SCHED; PG8_LDA(At, 0, 0); PG8_STAGE(PG8_SA(1, 1), a1 + hstepA, voffA);
;             PG8_WAIT_V(8); PG8_WAIT_L(0); PG8_BAR; PG8_MMA(0, 0, At, B0); PG8_MMA(0, 1, At, B1); PG8_BAR; PG8_SCHED;
;             PG8_LDA(At, 0, 1); PG8_STAGE(PG8_SB(0, 0), b2, voffB); PG8_STAGE(PG8_SB(0, 1), b2 + hstepB, voffB); PG8_STAGE(PG8_SA(0, 0), a2, voffA);
;             PG8_WAIT_V(8); PG8_WAIT_L(0); PG8_BAR; PG8_MMA(1, 0, At, B0); PG8_MMA(1, 1, At, B1); PG8_BAR; PG8_SCHED;
.LBB0_1153:
	s_add_u32 s34, s26, 0xfff80080
	s_addc_u32 s35, s27, -1
	s_add_i32 s37, 0, 0x10000
	s_cmp_eq_u32 s19, 28
	s_cselect_b32 s57, s6, s35
	s_cselect_b32 s56, s10, s34
	v_add_u32_e32 v34, s37, v155
	s_cselect_b32 s41, s11, s15
	s_cselect_b32 s40, s12, s13
	s_add_i32 s49, 0, 0x14000
	ds_read_b128 v[132:135], v34
	ds_read_b128 v[136:139], v34 offset:1024
	s_waitcnt vmcnt(0)
	ds_read_b128 v[158:161], v34 offset:2048
	ds_read_b128 v[186:189], v34 offset:3072
	v_add_u32_e32 v34, s49, v155
	ds_read_b128 v[190:193], v34
	ds_read_b128 v[194:197], v34 offset:1024
	ds_read_b128 v[198:201], v34 offset:2048
	ds_read_b128 v[202:205], v34 offset:3072
	s_add_i32 m0, s8, 0xc000
	ds_read_b128 v[206:209], v157
	ds_read_b128 v[210:213], v157 offset:1024
	ds_read_b128 v[214:217], v157 offset:2048
	ds_read_b128 v[218:221], v157 offset:3072
	ds_read_b128 v[222:225], v157 offset:4096
	ds_read_b128 v[234:237], v157 offset:5120
	ds_read_b128 v[238:241], v157 offset:6144
	ds_read_b128 v[242:245], v157 offset:7168
	global_load_lds_dwordx4 v150, s[26:27]
	s_add_i32 m0, s8, 0xe000
	s_nop 0
	global_load_lds_dwordx4 v152, s[26:27]
	s_waitcnt vmcnt(8)
	s_waitcnt lgkmcnt(0)
	s_barrier
	s_setprio 1
	v_mfma_f32_16x16x32_bf16 v[128:131], v[132:135], v[206:209], v[128:131]
	v_mfma_f32_16x16x32_bf16 v[124:127], v[158:161], v[206:209], v[124:127]
	v_mfma_f32_16x16x32_bf16 v[112:115], v[132:135], v[214:217], v[112:115]
	v_mfma_f32_16x16x32_bf16 v[108:111], v[158:161], v[214:217], v[108:111]
	v_mfma_f32_16x16x32_bf16 v[96:99], v[132:135], v[222:225], v[96:99]
	v_mfma_f32_16x16x32_bf16 v[92:95], v[158:161], v[222:225], v[92:95]
	v_mfma_f32_16x16x32_bf16 v[80:83], v[132:135], v[238:241], v[80:83]
	v_mfma_f32_16x16x32_bf16 v[76:79], v[158:161], v[238:241], v[76:79]
	v_mfma_f32_16x16x32_bf16 v[128:131], v[136:139], v[210:213], v[128:131]
	v_mfma_f32_16x16x32_bf16 v[124:127], v[186:189], v[210:213], v[124:127]
	v_mfma_f32_16x16x32_bf16 v[112:115], v[136:139], v[218:221], v[112:115]
	v_mfma_f32_16x16x32_bf16 v[108:111], v[186:189], v[218:221], v[108:111]
	v_mfma_f32_16x16x32_bf16 v[96:99], v[136:139], v[234:237], v[96:99]
	v_mfma_f32_16x16x32_bf16 v[92:95], v[186:189], v[234:237], v[92:95]
	v_mfma_f32_16x16x32_bf16 v[80:83], v[136:139], v[242:245], v[80:83]
	v_mfma_f32_16x16x32_bf16 v[76:79], v[186:189], v[242:245], v[76:79]
	v_mfma_f32_16x16x32_bf16 v[120:123], v[190:193], v[206:209], v[120:123]
	v_mfma_f32_16x16x32_bf16 v[116:119], v[198:201], v[206:209], v[116:119]
	v_mfma_f32_16x16x32_bf16 v[104:107], v[190:193], v[214:217], v[104:107]
	v_mfma_f32_16x16x32_bf16 v[100:103], v[198:201], v[214:217], v[100:103]
	v_mfma_f32_16x16x32_bf16 v[88:91], v[190:193], v[222:225], v[88:91]
	v_mfma_f32_16x16x32_bf16 v[84:87], v[198:201], v[222:225], v[84:87]
	v_mfma_f32_16x16x32_bf16 v[72:75], v[190:193], v[238:241], v[72:75]
	v_mfma_f32_16x16x32_bf16 v[68:71], v[198:201], v[238:241], v[68:71]
	v_mfma_f32_16x16x32_bf16 v[120:123], v[194:197], v[210:213], v[120:123]
	v_mfma_f32_16x16x32_bf16 v[116:119], v[202:205], v[210:213], v[116:119]
	v_mfma_f32_16x16x32_bf16 v[104:107], v[194:197], v[218:221], v[104:107]
	v_mfma_f32_16x16x32_bf16 v[100:103], v[202:205], v[218:221], v[100:103]
	v_mfma_f32_16x16x32_bf16 v[88:91], v[194:197], v[234:237], v[88:91]
	v_mfma_f32_16x16x32_bf16 v[84:87], v[202:205], v[234:237], v[84:87]
	v_mfma_f32_16x16x32_bf16 v[72:75], v[194:197], v[242:245], v[72:75]
	v_mfma_f32_16x16x32_bf16 v[68:71], v[202:205], v[242:245], v[68:71]
	s_setprio 0
	s_barrier
	s_add_i32 s34, s37, s7
	s_mov_b32 m0, s34
	ds_read_b128 v[206:209], v157 offset:16384
	ds_read_b128 v[210:213], v157 offset:17408
	ds_read_b128 v[214:217], v157 offset:18432
	ds_read_b128 v[218:221], v157 offset:19456
	ds_read_b128 v[222:225], v157 offset:20480
	ds_read_b128 v[234:237], v157 offset:21504
	ds_read_b128 v[238:241], v157 offset:22528
	ds_read_b128 v[242:245], v157 offset:23552
	global_load_lds_dwordx4 v142, s[40:41]
	s_add_i32 m0, s34, 0x2000
	s_add_u32 s34, s40, 0x80000
	v_lshl_add_u64 v[226:227], s[40:41], 0, v[146:147]
	s_addc_u32 s35, s41, 0
	s_add_i32 s37, s49, s7
	global_load_lds_dwordx4 v146, s[40:41]
	s_mov_b32 m0, s37
	v_lshl_add_u64 v[248:249], s[56:57], 0, v[144:145]
	global_load_lds_dwordx4 v142, s[34:35]
	s_add_i32 m0, s37, 0x2000
	s_nop 0
	global_load_lds_dwordx4 v146, s[34:35]
	v_lshl_add_u64 v[246:247], s[56:57], 0, v[140:141]
	s_mov_b32 m0, s8
	s_nop 0
	global_load_lds_dwordx4 v140, s[56:57]
	s_mov_b32 m0, s9
	s_nop 0
	global_load_lds_dwordx4 v144, s[56:57]
	s_waitcnt vmcnt(8)
	s_waitcnt lgkmcnt(0)
	s_barrier
; #define PG8_STAGE(bufoff, gbase, voff) do { _Pragma("unroll") for (int _i = 0; _i < 2; ++_i) \
;         __builtin_amdgcn_global_load_lds((const unsigned*)((const char*)(gbase) + (voff)[_i]), (PG8_LAS unsigned*)(lds + (bufoff) + ldsw + _i * 8192), 16, 0, 0); } while (0)
; #define PG8_LDA(dst, b, h) do { _Pragma("unroll") for (int m = 0; m < 4; ++m) _Pragma("unroll") for (int k = 0; k < 2; ++k) dst[m][k] = *(const PG8_LAS bf16x8*)(lds + PG8_SA(b, h) + aoff + m * 2048 + k * 1024); } while (0)
; #define PG8_LDB(dst, b, h) do { _Pragma("unroll") for (int n = 0; n < 2; ++n) _Pragma("unroll") for (int k = 0; k < 2; ++k) dst[n][k] = *(const PG8_LAS bf16x8*)(lds + PG8_SB(b, h) + boff + n * 2048 + k * 1024); } while (0)
; #define PG8_WAIT_V(n) asm volatile("s_waitcnt vmcnt(" #n ")" ::: "memory")
; #define PG8_WAIT_L(n) asm volatile("s_waitcnt lgkmcnt(" #n ")" ::: "memory")
; #define PG8_BAR __builtin_amdgcn_s_barrier()
; #define PG8_SCHED __builtin_amdgcn_sched_barrier(0)
;     ...
;             PG8_LDA(At, 0, 1); PG8_STAGE(PG8_SB(0, 0), b2, voffB); PG8_STAGE(PG8_SB(0, 1), b2 + hstepB, voffB); PG8_STAGE(PG8_SA(0, 0), a2, voffA);
;             PG8_WAIT_V(8); PG8_WAIT_L(0); PG8_BAR; PG8_MMA(1, 0, At, B0); PG8_MMA(1, 1, At, B1); PG8_BAR; PG8_SCHED;
;             PG8_LDB(B0, 1, 0); PG8_LDB(B1, 1, 1); PG8_SCHED; PG8_LDA(At, 1, 0); PG8_STAGE(PG8_SA(0, 1), a2 + hstepA, voffA);
;             PG8_WAIT_V(8); PG8_WAIT_L(0); PG8_BAR; PG8_MMA(0, 0, At, B0); PG8_MMA(0, 1, At, B1); PG8_BAR; PG8_SCHED;
;             PG8_LDA(At, 1, 1); PG8_STAGE(PG8_SB(1, 0), b3, voffB); PG8_STAGE(PG8_SB(1, 1), b3 + hstepB, voffB); PG8_STAGE(PG8_SA(1, 0), a3, voffA);
	s_setprio 1
	v_mfma_f32_16x16x32_bf16 v[64:67], v[132:135], v[206:209], v[64:67]
	v_mfma_f32_16x16x32_bf16 v[60:63], v[158:161], v[206:209], v[60:63]
	v_mfma_f32_16x16x32_bf16 v[48:51], v[132:135], v[214:217], v[48:51]
	v_mfma_f32_16x16x32_bf16 v[44:47], v[158:161], v[214:217], v[44:47]
	v_mfma_f32_16x16x32_bf16 v[30:33], v[132:135], v[222:225], v[30:33]
	v_mfma_f32_16x16x32_bf16 v[26:29], v[158:161], v[222:225], v[26:29]
	v_mfma_f32_16x16x32_bf16 v[14:17], v[132:135], v[238:241], v[14:17]
	v_mfma_f32_16x16x32_bf16 v[10:13], v[158:161], v[238:241], v[10:13]
	v_mfma_f32_16x16x32_bf16 v[64:67], v[136:139], v[210:213], v[64:67]
	v_mfma_f32_16x16x32_bf16 v[60:63], v[186:189], v[210:213], v[60:63]
	v_mfma_f32_16x16x32_bf16 v[48:51], v[136:139], v[218:221], v[48:51]
	v_mfma_f32_16x16x32_bf16 v[44:47], v[186:189], v[218:221], v[44:47]
	v_mfma_f32_16x16x32_bf16 v[30:33], v[136:139], v[234:237], v[30:33]
	v_mfma_f32_16x16x32_bf16 v[26:29], v[186:189], v[234:237], v[26:29]
	v_mfma_f32_16x16x32_bf16 v[14:17], v[136:139], v[242:245], v[14:17]
	v_mfma_f32_16x16x32_bf16 v[10:13], v[186:189], v[242:245], v[10:13]
	v_mfma_f32_16x16x32_bf16 v[56:59], v[190:193], v[206:209], v[56:59]
	v_mfma_f32_16x16x32_bf16 v[52:55], v[198:201], v[206:209], v[52:55]
	v_mfma_f32_16x16x32_bf16 v[40:43], v[190:193], v[214:217], v[40:43]
	v_mfma_f32_16x16x32_bf16 v[36:39], v[198:201], v[214:217], v[36:39]
	v_mfma_f32_16x16x32_bf16 v[22:25], v[190:193], v[222:225], v[22:25]
	v_mfma_f32_16x16x32_bf16 v[18:21], v[198:201], v[222:225], v[18:21]
	v_mfma_f32_16x16x32_bf16 v[6:9], v[190:193], v[238:241], v[6:9]
	v_mfma_f32_16x16x32_bf16 v[2:5], v[198:201], v[238:241], v[2:5]
	v_mfma_f32_16x16x32_bf16 v[56:59], v[194:197], v[210:213], v[56:59]
	v_mfma_f32_16x16x32_bf16 v[52:55], v[202:205], v[210:213], v[52:55]
	v_mfma_f32_16x16x32_bf16 v[40:43], v[194:197], v[218:221], v[40:43]
	v_mfma_f32_16x16x32_bf16 v[36:39], v[202:205], v[218:221], v[36:39]
	v_mfma_f32_16x16x32_bf16 v[22:25], v[194:197], v[234:237], v[22:25]
	v_mfma_f32_16x16x32_bf16 v[18:21], v[202:205], v[234:237], v[18:21]
	v_mfma_f32_16x16x32_bf16 v[6:9], v[194:197], v[242:245], v[6:9]
	v_mfma_f32_16x16x32_bf16 v[2:5], v[202:205], v[242:245], v[2:5]
	s_setprio 0
	s_barrier
	s_add_i32 s37, 0, 0x18000
	v_add_u32_e32 v34, s37, v155
	s_add_i32 s49, 0, 0x1c000
	ds_read_b128 v[132:135], v34
	ds_read_b128 v[136:139], v34 offset:1024
	ds_read_b128 v[158:161], v34 offset:2048
	ds_read_b128 v[186:189], v34 offset:3072
	v_add_u32_e32 v34, s49, v155
	ds_read_b128 v[190:193], v34
	ds_read_b128 v[194:197], v34 offset:1024
	ds_read_b128 v[198:201], v34 offset:2048
	ds_read_b128 v[202:205], v34 offset:3072
	s_add_u32 s34, s56, 0x80000
	s_addc_u32 s35, s57, 0
	s_mov_b32 m0, s58
	ds_read_b128 v[206:209], v157 offset:32768
	ds_read_b128 v[210:213], v157 offset:33792
	ds_read_b128 v[214:217], v157 offset:34816
	ds_read_b128 v[218:221], v157 offset:35840
	ds_read_b128 v[222:225], v157 offset:36864
	ds_read_b128 v[234:237], v157 offset:37888
	ds_read_b128 v[238:241], v157 offset:38912
	ds_read_b128 v[242:245], v157 offset:39936
	global_load_lds_dwordx4 v140, s[34:35]
	v_lshl_add_u64 v[250:251], s[34:35], 0, v[144:145]
	s_mov_b32 m0, s59
	s_nop 0
	global_load_lds_dwordx4 v144, s[34:35]
	s_waitcnt vmcnt(8)
	s_waitcnt lgkmcnt(0)
	s_barrier
	s_setprio 1
	v_mfma_f32_16x16x32_bf16 v[128:131], v[132:135], v[206:209], v[128:131]
	v_mfma_f32_16x16x32_bf16 v[124:127], v[158:161], v[206:209], v[124:127]
	v_mfma_f32_16x16x32_bf16 v[112:115], v[132:135], v[214:217], v[112:115]
	v_mfma_f32_16x16x32_bf16 v[108:111], v[158:161], v[214:217], v[108:111]
	v_mfma_f32_16x16x32_bf16 v[96:99], v[132:135], v[222:225], v[96:99]
	v_mfma_f32_16x16x32_bf16 v[92:95], v[158:161], v[222:225], v[92:95]
	v_mfma_f32_16x16x32_bf16 v[80:83], v[132:135], v[238:241], v[80:83]
	v_mfma_f32_16x16x32_bf16 v[76:79], v[158:161], v[238:241], v[76:79]
	v_mfma_f32_16x16x32_bf16 v[128:131], v[136:139], v[210:213], v[128:131]
	v_mfma_f32_16x16x32_bf16 v[124:127], v[186:189], v[210:213], v[124:127]
	v_mfma_f32_16x16x32_bf16 v[112:115], v[136:139], v[218:221], v[112:115]
	v_mfma_f32_16x16x32_bf16 v[108:111], v[186:189], v[218:221], v[108:111]
	v_mfma_f32_16x16x32_bf16 v[96:99], v[136:139], v[234:237], v[96:99]
	v_mfma_f32_16x16x32_bf16 v[92:95], v[186:189], v[234:237], v[92:95]
	v_mfma_f32_16x16x32_bf16 v[80:83], v[136:139], v[242:245], v[80:83]
	v_mfma_f32_16x16x32_bf16 v[76:79], v[186:189], v[242:245], v[76:79]
	v_mfma_f32_16x16x32_bf16 v[120:123], v[190:193], v[206:209], v[120:123]
	v_mfma_f32_16x16x32_bf16 v[116:119], v[198:201], v[206:209], v[116:119]
	v_mfma_f32_16x16x32_bf16 v[104:107], v[190:193], v[214:217], v[104:107]
	v_mfma_f32_16x16x32_bf16 v[100:103], v[198:201], v[214:217], v[100:103]
	v_mfma_f32_16x16x32_bf16 v[88:91], v[190:193], v[222:225], v[88:91]
	v_mfma_f32_16x16x32_bf16 v[84:87], v[198:201], v[222:225], v[84:87]
	v_mfma_f32_16x16x32_bf16 v[72:75], v[190:193], v[238:241], v[72:75]
	v_mfma_f32_16x16x32_bf16 v[68:71], v[198:201], v[238:241], v[68:71]
	v_mfma_f32_16x16x32_bf16 v[120:123], v[194:197], v[210:213], v[120:123]
	v_mfma_f32_16x16x32_bf16 v[116:119], v[202:205], v[210:213], v[116:119]
	v_mfma_f32_16x16x32_bf16 v[104:107], v[194:197], v[218:221], v[104:107]
	v_mfma_f32_16x16x32_bf16 v[100:103], v[202:205], v[218:221], v[100:103]
	v_mfma_f32_16x16x32_bf16 v[88:91], v[194:197], v[234:237], v[88:91]
	v_mfma_f32_16x16x32_bf16 v[84:87], v[202:205], v[234:237], v[84:87]
	v_mfma_f32_16x16x32_bf16 v[72:75], v[194:197], v[242:245], v[72:75]
	v_mfma_f32_16x16x32_bf16 v[68:71], v[202:205], v[242:245], v[68:71]
	s_setprio 0
	s_barrier
; #define PG8_STAGE(bufoff, gbase, voff) do { _Pragma("unroll") for (int _i = 0; _i < 2; ++_i) \
;         __builtin_amdgcn_global_load_lds((const unsigned*)((const char*)(gbase) + (voff)[_i]), (PG8_LAS unsigned*)(lds + (bufoff) + ldsw + _i * 8192), 16, 0, 0); } while (0)
; #define PG8_LDA(dst, b, h) do { _Pragma("unroll") for (int m = 0; m < 4; ++m) _Pragma("unroll") for (int k = 0; k < 2; ++k) dst[m][k] = *(const PG8_LAS bf16x8*)(lds + PG8_SA(b, h) + aoff + m * 2048 + k * 1024); } while (0)
; #define PG8_WAIT_V(n) asm volatile("s_waitcnt vmcnt(" #n ")" ::: "memory")
; #define PG8_WAIT_L(n) asm volatile("s_waitcnt lgkmcnt(" #n ")" ::: "memory")
; #define PG8_BAR __builtin_amdgcn_s_barrier()
; #define PG8_SCHED __builtin_amdgcn_sched_barrier(0)
;     ...
;         for (int t = 0; t < nt; t += 2) {
;     ...
;             PG8_LDA(At, 1, 1); PG8_STAGE(PG8_SB(1, 0), b3, voffB); PG8_STAGE(PG8_SB(1, 1), b3 + hstepB, voffB); PG8_STAGE(PG8_SA(1, 0), a3, voffA);
;             PG8_WAIT_V(8); PG8_WAIT_L(0); PG8_BAR; PG8_MMA(1, 0, At, B0); PG8_MMA(1, 1, At, B1); PG8_BAR; PG8_SCHED;
	s_add_i32 s34, s37, s7
	s_mov_b32 m0, s34
	ds_read_b128 v[206:209], v157 offset:49152
	ds_read_b128 v[210:213], v157 offset:50176
	ds_read_b128 v[214:217], v157 offset:51200
	ds_read_b128 v[218:221], v157 offset:52224
	ds_read_b128 v[222:225], v157 offset:53248
	ds_read_b128 v[234:237], v157 offset:54272
	ds_read_b128 v[238:241], v157 offset:55296
	ds_read_b128 v[242:245], v157 offset:56320
	s_add_u32 s98, s40, 0x80
	s_addc_u32 s99, s41, 0
	global_load_lds_dwordx4 v142, s[98:99]
	s_add_i32 m0, s34, 0x2000
	s_add_u32 s34, s40, 0x80080
	s_addc_u32 s35, s41, 0
	s_add_i32 s37, s49, s7
	s_add_u32 s98, s40, 0x80
	s_addc_u32 s99, s41, 0
	global_load_lds_dwordx4 v146, s[98:99]
	s_mov_b32 m0, s37
	s_nop 0
	global_load_lds_dwordx4 v142, s[34:35]
	s_add_i32 m0, s37, 0x2000
	s_nop 0
	global_load_lds_dwordx4 v146, s[34:35]
	s_mov_b32 m0, s66
	s_nop 0
	s_add_u32 s98, s56, 0x80
	s_addc_u32 s99, s57, 0
	global_load_lds_dwordx4 v140, s[98:99]
	v_lshl_add_u64 v[162:163], v[248:249], 0, s[22:23]
	s_mov_b32 m0, s67
	s_nop 0
	s_add_u32 s98, s56, 0x80
	s_addc_u32 s99, s57, 0
	global_load_lds_dwordx4 v144, s[98:99]
	s_waitcnt vmcnt(8)
	s_waitcnt lgkmcnt(0)
	s_barrier
	s_setprio 1
	v_mfma_f32_16x16x32_bf16 v[64:67], v[132:135], v[206:209], v[64:67]
	v_mfma_f32_16x16x32_bf16 v[60:63], v[158:161], v[206:209], v[60:63]
	v_mfma_f32_16x16x32_bf16 v[48:51], v[132:135], v[214:217], v[48:51]
	v_mfma_f32_16x16x32_bf16 v[44:47], v[158:161], v[214:217], v[44:47]
	v_mfma_f32_16x16x32_bf16 v[30:33], v[132:135], v[222:225], v[30:33]
	v_mfma_f32_16x16x32_bf16 v[26:29], v[158:161], v[222:225], v[26:29]
	v_mfma_f32_16x16x32_bf16 v[14:17], v[132:135], v[238:241], v[14:17]
	v_mfma_f32_16x16x32_bf16 v[10:13], v[158:161], v[238:241], v[10:13]
	v_mfma_f32_16x16x32_bf16 v[64:67], v[136:139], v[210:213], v[64:67]
	v_mfma_f32_16x16x32_bf16 v[60:63], v[186:189], v[210:213], v[60:63]
	v_mfma_f32_16x16x32_bf16 v[48:51], v[136:139], v[218:221], v[48:51]
	v_mfma_f32_16x16x32_bf16 v[44:47], v[186:189], v[218:221], v[44:47]
	v_mfma_f32_16x16x32_bf16 v[30:33], v[136:139], v[234:237], v[30:33]
	v_mfma_f32_16x16x32_bf16 v[26:29], v[186:189], v[234:237], v[26:29]
	v_mfma_f32_16x16x32_bf16 v[14:17], v[136:139], v[242:245], v[14:17]
	v_mfma_f32_16x16x32_bf16 v[10:13], v[186:189], v[242:245], v[10:13]
	v_mfma_f32_16x16x32_bf16 v[56:59], v[190:193], v[206:209], v[56:59]
	v_mfma_f32_16x16x32_bf16 v[52:55], v[198:201], v[206:209], v[52:55]
	v_mfma_f32_16x16x32_bf16 v[40:43], v[190:193], v[214:217], v[40:43]
	v_mfma_f32_16x16x32_bf16 v[36:39], v[198:201], v[214:217], v[36:39]
	v_mfma_f32_16x16x32_bf16 v[22:25], v[190:193], v[222:225], v[22:25]
	v_mfma_f32_16x16x32_bf16 v[18:21], v[198:201], v[222:225], v[18:21]
	v_mfma_f32_16x16x32_bf16 v[6:9], v[190:193], v[238:241], v[6:9]
	v_mfma_f32_16x16x32_bf16 v[2:5], v[198:201], v[238:241], v[2:5]
	v_mfma_f32_16x16x32_bf16 v[56:59], v[194:197], v[210:213], v[56:59]
	v_mfma_f32_16x16x32_bf16 v[52:55], v[202:205], v[210:213], v[52:55]
	v_mfma_f32_16x16x32_bf16 v[40:43], v[194:197], v[218:221], v[40:43]
	v_mfma_f32_16x16x32_bf16 v[36:39], v[202:205], v[218:221], v[36:39]
	v_mfma_f32_16x16x32_bf16 v[22:25], v[194:197], v[234:237], v[22:25]
	v_mfma_f32_16x16x32_bf16 v[18:21], v[202:205], v[234:237], v[18:21]
	v_mfma_f32_16x16x32_bf16 v[6:9], v[194:197], v[242:245], v[6:9]
	v_mfma_f32_16x16x32_bf16 v[2:5], v[202:205], v[242:245], v[2:5]
	s_setprio 0
	s_barrier
	s_add_i32 s19, s19, 2
	s_add_u32 s26, s26, 0x100
	s_addc_u32 s27, s27, 0
	s_add_u32 s13, s13, 0x100
	s_addc_u32 s15, s15, 0
	s_cmp_gt_u32 s19, 29
	s_cbranch_scc0 .LBB0_1153
	s_and_b64 vcc, exec, s[46:47]
	s_cbranch_vccz .LBB0_1156
	s_barrier

; #define PG8_STAGE(bufoff, gbase, voff) do { _Pragma("unroll") for (int _i = 0; _i < 2; ++_i) \
;         __builtin_amdgcn_global_load_lds((const unsigned*)((const char*)(gbase) + (voff)[_i]), (PG8_LAS unsigned*)(lds + (bufoff) + ldsw + _i * 8192), 16, 0, 0); } while (0)
; #define PG8_LDA(dst, b, h) do { _Pragma("unroll") for (int m = 0; m < 4; ++m) _Pragma("unroll") for (int k = 0; k < 2; ++k) dst[m][k] = *(const PG8_LAS bf16x8*)(lds + PG8_SA(b, h) + aoff + m * 2048 + k * 1024); } while (0)
; #define PG8_LDB(dst, b, h) do { _Pragma("unroll") for (int n = 0; n < 2; ++n) _Pragma("unroll") for (int k = 0; k < 2; ++k) dst[n][k] = *(const PG8_LAS bf16x8*)(lds + PG8_SB(b, h) + boff + n * 2048 + k * 1024); } while (0)
; #define PG8_WAIT_V(n) asm volatile("s_waitcnt vmcnt(" #n ")" ::: "memory")
; #define PG8_WAIT_L(n) asm volatile("s_waitcnt lgkmcnt(" #n ")" ::: "memory")
; #define PG8_BAR __builtin_amdgcn_s_barrier()
; #define PG8_SCHED __builtin_amdgcn_sched_barrier(0)
;     ...
;             const bool last = (t == nt - 2);
;             const char* a1 = cA + (size_t)(t + 1) * kstep;
;             const char* a2 = last ? nA : cA + (size_t)(t + 2) * kstep; const char* b2 = last ? nB : cB + (size_t)(t + 2) * kstep;
;             const char* a3 = a2 + kstep; const char* b3 = b2 + kstep;
;             if (last && has_next) S.a_ready(nxt);
;             if constexpr (SP2) {
;             PG8_LDB(B0, 0, 0); PG8_LDB(B1, 0, 1); PG8_SCHED; PG8_LDA(At, 0, 0); PG8_STAGE(PG8_SA(1, 1), a1 + hstepA, voffA);
;             PG8_WAIT_V(8); PG8_WAIT_L(0); PG8_BAR; PG8_MMA(0, 0, At, B0); PG8_MMA(0, 1, At, B1); PG8_BAR; PG8_SCHED;
;             PG8_LDA(At, 0, 1); PG8_STAGE(PG8_SB(0, 0), b2, voffB); PG8_STAGE(PG8_SB(0, 1), b2 + hstepB, voffB); PG8_STAGE(PG8_SA(0, 0), a2, voffA);
;             PG8_WAIT_V(8); PG8_WAIT_L(0); PG8_BAR; PG8_MMA(1, 0, At, B0); PG8_MMA(1, 1, At, B1); PG8_BAR; PG8_SCHED;
.LBB0_1503:
	s_add_i32 s70, s58, 2
	s_add_u32 s71, s40, 0xfffc0080
	s_addc_u32 s59, s41, -1
	s_add_i32 s76, 0, 0x10000
	s_cmp_eq_u32 s63, s58
	s_cselect_b32 s59, s51, s59
	s_cselect_b32 s58, s68, s71
	s_cselect_b32 s75, s53, s61
	s_cselect_b32 s74, s52, s60
	s_add_i32 s71, 0, 0x14000
	v_add_u32_e32 v128, s76, v187
	v_add_u32_e32 v189, s71, v187
	ds_read_b128 v[108:111], v128
	ds_read_b128 v[112:115], v128 offset:1024
	ds_read_b128 v[124:127], v128 offset:2048
	ds_read_b128 v[128:131], v128 offset:3072
	ds_read_b128 v[160:163], v189
	ds_read_b128 v[190:193], v189 offset:1024
	ds_read_b128 v[194:197], v189 offset:2048
	ds_read_b128 v[198:201], v189 offset:3072
	s_add_i32 m0, s13, 0xc000
	ds_read_b128 v[202:205], v188
	ds_read_b128 v[206:209], v188 offset:1024
	ds_read_b128 v[210:213], v188 offset:2048
	ds_read_b128 v[214:217], v188 offset:3072
	ds_read_b128 v[218:221], v188 offset:4096
	ds_read_b128 v[222:225], v188 offset:5120
	ds_read_b128 v[234:237], v188 offset:6144
	ds_read_b128 v[238:241], v188 offset:7168
	global_load_lds_dwordx4 v156, s[40:41]
	s_add_i32 m0, s13, 0xe000
	s_nop 0
	global_load_lds_dwordx4 v158, s[40:41]
	s_waitcnt vmcnt(8)
	s_waitcnt lgkmcnt(0)
	s_barrier
	s_setprio 1
	v_mfma_f32_16x16x32_bf16 v[144:147], v[108:111], v[202:205], v[144:147]
	v_mfma_f32_16x16x32_bf16 v[140:143], v[124:127], v[202:205], v[140:143]
	v_mfma_f32_16x16x32_bf16 v[120:123], v[108:111], v[210:213], v[120:123]
	v_mfma_f32_16x16x32_bf16 v[116:119], v[124:127], v[210:213], v[116:119]
	v_mfma_f32_16x16x32_bf16 v[96:99], v[108:111], v[218:221], v[96:99]
	v_mfma_f32_16x16x32_bf16 v[92:95], v[124:127], v[218:221], v[92:95]
	v_mfma_f32_16x16x32_bf16 v[80:83], v[108:111], v[234:237], v[80:83]
	v_mfma_f32_16x16x32_bf16 v[76:79], v[124:127], v[234:237], v[76:79]
	v_mfma_f32_16x16x32_bf16 v[144:147], v[112:115], v[206:209], v[144:147]
	v_mfma_f32_16x16x32_bf16 v[140:143], v[128:131], v[206:209], v[140:143]
	v_mfma_f32_16x16x32_bf16 v[120:123], v[112:115], v[214:217], v[120:123]
	v_mfma_f32_16x16x32_bf16 v[116:119], v[128:131], v[214:217], v[116:119]
	v_mfma_f32_16x16x32_bf16 v[96:99], v[112:115], v[222:225], v[96:99]
	v_mfma_f32_16x16x32_bf16 v[92:95], v[128:131], v[222:225], v[92:95]
	v_mfma_f32_16x16x32_bf16 v[80:83], v[112:115], v[238:241], v[80:83]
	v_mfma_f32_16x16x32_bf16 v[76:79], v[128:131], v[238:241], v[76:79]
	v_mfma_f32_16x16x32_bf16 v[136:139], v[160:163], v[202:205], v[136:139]
	v_mfma_f32_16x16x32_bf16 v[132:135], v[194:197], v[202:205], v[132:135]
	v_mfma_f32_16x16x32_bf16 v[104:107], v[160:163], v[210:213], v[104:107]
	v_mfma_f32_16x16x32_bf16 v[100:103], v[194:197], v[210:213], v[100:103]
	v_mfma_f32_16x16x32_bf16 v[88:91], v[160:163], v[218:221], v[88:91]
	v_mfma_f32_16x16x32_bf16 v[84:87], v[194:197], v[218:221], v[84:87]
	v_mfma_f32_16x16x32_bf16 v[72:75], v[160:163], v[234:237], v[72:75]
	v_mfma_f32_16x16x32_bf16 v[68:71], v[194:197], v[234:237], v[68:71]
	v_mfma_f32_16x16x32_bf16 v[136:139], v[190:193], v[206:209], v[136:139]
	v_mfma_f32_16x16x32_bf16 v[132:135], v[198:201], v[206:209], v[132:135]
	v_mfma_f32_16x16x32_bf16 v[104:107], v[190:193], v[214:217], v[104:107]
	v_mfma_f32_16x16x32_bf16 v[100:103], v[198:201], v[214:217], v[100:103]
	v_mfma_f32_16x16x32_bf16 v[88:91], v[190:193], v[222:225], v[88:91]
	v_mfma_f32_16x16x32_bf16 v[84:87], v[198:201], v[222:225], v[84:87]
	v_mfma_f32_16x16x32_bf16 v[72:75], v[190:193], v[238:241], v[72:75]
	v_mfma_f32_16x16x32_bf16 v[68:71], v[198:201], v[238:241], v[68:71]
	s_setprio 0
	s_barrier
	s_add_i32 s76, s76, s12
	v_lshl_add_u64 v[226:227], s[74:75], 0, v[34:35]
	s_mov_b32 m0, s76
	ds_read_b128 v[202:205], v188 offset:16384
	ds_read_b128 v[206:209], v188 offset:17408
	ds_read_b128 v[210:213], v188 offset:18432
	ds_read_b128 v[214:217], v188 offset:19456
	ds_read_b128 v[218:221], v188 offset:20480
	ds_read_b128 v[222:225], v188 offset:21504
	ds_read_b128 v[234:237], v188 offset:22528
	ds_read_b128 v[238:241], v188 offset:23552
	global_load_lds_dwordx4 v34, s[74:75]
	s_add_i32 m0, s76, 0x2000
	v_lshl_add_u64 v[242:243], s[74:75], 0, v[152:153]
	s_add_u32 s74, s74, s28
	s_addc_u32 s75, s75, s29
	s_add_i32 s71, s71, s12
	global_load_lds_dwordx4 v[242:243], off
	v_lshl_add_u64 v[244:245], s[74:75], 0, v[34:35]
	s_mov_b32 m0, s71
	v_lshl_add_u64 v[246:247], s[74:75], 0, v[152:153]
	global_load_lds_dwordx4 v34, s[74:75]
	s_add_i32 m0, s71, 0x2000
	v_lshl_add_u64 v[248:249], s[58:59], 0, v[148:149]
	global_load_lds_dwordx4 v152, s[74:75]
	s_mov_b32 m0, s13
	v_lshl_add_u64 v[250:251], s[58:59], 0, v[150:151]
	global_load_lds_dwordx4 v148, s[58:59]
	s_mov_b32 m0, s15
	s_nop 0
	global_load_lds_dwordx4 v150, s[58:59]
	s_waitcnt vmcnt(8)
	s_waitcnt lgkmcnt(0)
	s_barrier
; #define PG8_STAGE(bufoff, gbase, voff) do { _Pragma("unroll") for (int _i = 0; _i < 2; ++_i) \
;         __builtin_amdgcn_global_load_lds((const unsigned*)((const char*)(gbase) + (voff)[_i]), (PG8_LAS unsigned*)(lds + (bufoff) + ldsw + _i * 8192), 16, 0, 0); } while (0)
; #define PG8_LDA(dst, b, h) do { _Pragma("unroll") for (int m = 0; m < 4; ++m) _Pragma("unroll") for (int k = 0; k < 2; ++k) dst[m][k] = *(const PG8_LAS bf16x8*)(lds + PG8_SA(b, h) + aoff + m * 2048 + k * 1024); } while (0)
; #define PG8_LDB(dst, b, h) do { _Pragma("unroll") for (int n = 0; n < 2; ++n) _Pragma("unroll") for (int k = 0; k < 2; ++k) dst[n][k] = *(const PG8_LAS bf16x8*)(lds + PG8_SB(b, h) + boff + n * 2048 + k * 1024); } while (0)
; #define PG8_WAIT_V(n) asm volatile("s_waitcnt vmcnt(" #n ")" ::: "memory")
; #define PG8_WAIT_L(n) asm volatile("s_waitcnt lgkmcnt(" #n ")" ::: "memory")
; #define PG8_BAR __builtin_amdgcn_s_barrier()
; #define PG8_SCHED __builtin_amdgcn_sched_barrier(0)
;     ...
;             PG8_WAIT_V(8); PG8_WAIT_L(0); PG8_BAR; PG8_MMA(1, 0, At, B0); PG8_MMA(1, 1, At, B1); PG8_BAR; PG8_SCHED;
;             PG8_LDB(B0, 1, 0); PG8_LDB(B1, 1, 1); PG8_SCHED; PG8_LDA(At, 1, 0); PG8_STAGE(PG8_SA(0, 1), a2 + hstepA, voffA);
;             PG8_WAIT_V(8); PG8_WAIT_L(0); PG8_BAR; PG8_MMA(0, 0, At, B0); PG8_MMA(0, 1, At, B1); PG8_BAR; PG8_SCHED;
	s_setprio 1
	v_mfma_f32_16x16x32_bf16 v[64:67], v[108:111], v[202:205], v[64:67]
	v_mfma_f32_16x16x32_bf16 v[60:63], v[124:127], v[202:205], v[60:63]
	v_mfma_f32_16x16x32_bf16 v[48:51], v[108:111], v[210:213], v[48:51]
	v_mfma_f32_16x16x32_bf16 v[44:47], v[124:127], v[210:213], v[44:47]
	v_mfma_f32_16x16x32_bf16 v[30:33], v[108:111], v[218:221], v[30:33]
	v_mfma_f32_16x16x32_bf16 v[26:29], v[124:127], v[218:221], v[26:29]
	v_mfma_f32_16x16x32_bf16 v[14:17], v[108:111], v[234:237], v[14:17]
	v_mfma_f32_16x16x32_bf16 v[10:13], v[124:127], v[234:237], v[10:13]
	v_mfma_f32_16x16x32_bf16 v[64:67], v[112:115], v[206:209], v[64:67]
	v_mfma_f32_16x16x32_bf16 v[60:63], v[128:131], v[206:209], v[60:63]
	v_mfma_f32_16x16x32_bf16 v[48:51], v[112:115], v[214:217], v[48:51]
	v_mfma_f32_16x16x32_bf16 v[44:47], v[128:131], v[214:217], v[44:47]
	v_mfma_f32_16x16x32_bf16 v[30:33], v[112:115], v[222:225], v[30:33]
	v_mfma_f32_16x16x32_bf16 v[26:29], v[128:131], v[222:225], v[26:29]
	v_mfma_f32_16x16x32_bf16 v[14:17], v[112:115], v[238:241], v[14:17]
	v_mfma_f32_16x16x32_bf16 v[10:13], v[128:131], v[238:241], v[10:13]
	v_mfma_f32_16x16x32_bf16 v[56:59], v[160:163], v[202:205], v[56:59]
	v_mfma_f32_16x16x32_bf16 v[52:55], v[194:197], v[202:205], v[52:55]
	v_mfma_f32_16x16x32_bf16 v[40:43], v[160:163], v[210:213], v[40:43]
	v_mfma_f32_16x16x32_bf16 v[36:39], v[194:197], v[210:213], v[36:39]
	v_mfma_f32_16x16x32_bf16 v[22:25], v[160:163], v[218:221], v[22:25]
	v_mfma_f32_16x16x32_bf16 v[18:21], v[194:197], v[218:221], v[18:21]
	v_mfma_f32_16x16x32_bf16 v[6:9], v[160:163], v[234:237], v[6:9]
	v_mfma_f32_16x16x32_bf16 v[2:5], v[194:197], v[234:237], v[2:5]
	v_mfma_f32_16x16x32_bf16 v[56:59], v[190:193], v[206:209], v[56:59]
	v_mfma_f32_16x16x32_bf16 v[52:55], v[198:201], v[206:209], v[52:55]
	v_mfma_f32_16x16x32_bf16 v[40:43], v[190:193], v[214:217], v[40:43]
	v_mfma_f32_16x16x32_bf16 v[36:39], v[198:201], v[214:217], v[36:39]
	v_mfma_f32_16x16x32_bf16 v[22:25], v[190:193], v[222:225], v[22:25]
	v_mfma_f32_16x16x32_bf16 v[18:21], v[198:201], v[222:225], v[18:21]
	v_mfma_f32_16x16x32_bf16 v[6:9], v[190:193], v[238:241], v[6:9]
	v_mfma_f32_16x16x32_bf16 v[2:5], v[198:201], v[238:241], v[2:5]
	s_setprio 0
	s_barrier
	s_add_i32 s71, 0, 0x18000
	s_add_i32 s74, 0, 0x1c000
	v_add_u32_e32 v128, s71, v187
	v_add_u32_e32 v189, s74, v187
	ds_read_b128 v[108:111], v128
	ds_read_b128 v[112:115], v128 offset:1024
	ds_read_b128 v[124:127], v128 offset:2048
	ds_read_b128 v[128:131], v128 offset:3072
	ds_read_b128 v[160:163], v189
	ds_read_b128 v[190:193], v189 offset:1024
	ds_read_b128 v[194:197], v189 offset:2048
	ds_read_b128 v[198:201], v189 offset:3072
	s_add_u32 s58, s58, 0x40000
	s_addc_u32 s59, s59, 0
	s_mov_b32 m0, s21
	ds_read_b128 v[202:205], v188 offset:32768
	ds_read_b128 v[206:209], v188 offset:33792
	ds_read_b128 v[210:213], v188 offset:34816
	ds_read_b128 v[214:217], v188 offset:35840
	ds_read_b128 v[218:221], v188 offset:36864
	ds_read_b128 v[222:225], v188 offset:37888
	ds_read_b128 v[234:237], v188 offset:38912
	ds_read_b128 v[238:241], v188 offset:39936
	global_load_lds_dwordx4 v148, s[58:59]
	v_lshl_add_u64 v[252:253], s[58:59], 0, v[150:151]
	s_mov_b32 m0, s34
	s_nop 0
	global_load_lds_dwordx4 v150, s[58:59]
	s_waitcnt vmcnt(8)
	s_waitcnt lgkmcnt(0)
	s_barrier
	s_setprio 1
	v_mfma_f32_16x16x32_bf16 v[144:147], v[108:111], v[202:205], v[144:147]
	v_mfma_f32_16x16x32_bf16 v[140:143], v[124:127], v[202:205], v[140:143]
	v_mfma_f32_16x16x32_bf16 v[120:123], v[108:111], v[210:213], v[120:123]
	v_mfma_f32_16x16x32_bf16 v[116:119], v[124:127], v[210:213], v[116:119]
	v_mfma_f32_16x16x32_bf16 v[96:99], v[108:111], v[218:221], v[96:99]
	v_mfma_f32_16x16x32_bf16 v[92:95], v[124:127], v[218:221], v[92:95]
	v_mfma_f32_16x16x32_bf16 v[80:83], v[108:111], v[234:237], v[80:83]
	v_mfma_f32_16x16x32_bf16 v[76:79], v[124:127], v[234:237], v[76:79]
	v_mfma_f32_16x16x32_bf16 v[144:147], v[112:115], v[206:209], v[144:147]
	v_mfma_f32_16x16x32_bf16 v[140:143], v[128:131], v[206:209], v[140:143]
	v_mfma_f32_16x16x32_bf16 v[120:123], v[112:115], v[214:217], v[120:123]
	v_mfma_f32_16x16x32_bf16 v[116:119], v[128:131], v[214:217], v[116:119]
	v_mfma_f32_16x16x32_bf16 v[96:99], v[112:115], v[222:225], v[96:99]
	v_mfma_f32_16x16x32_bf16 v[92:95], v[128:131], v[222:225], v[92:95]
	v_mfma_f32_16x16x32_bf16 v[80:83], v[112:115], v[238:241], v[80:83]
	v_mfma_f32_16x16x32_bf16 v[76:79], v[128:131], v[238:241], v[76:79]
	v_mfma_f32_16x16x32_bf16 v[136:139], v[160:163], v[202:205], v[136:139]
	v_mfma_f32_16x16x32_bf16 v[132:135], v[194:197], v[202:205], v[132:135]
	v_mfma_f32_16x16x32_bf16 v[104:107], v[160:163], v[210:213], v[104:107]
	v_mfma_f32_16x16x32_bf16 v[100:103], v[194:197], v[210:213], v[100:103]
	v_mfma_f32_16x16x32_bf16 v[88:91], v[160:163], v[218:221], v[88:91]
	v_mfma_f32_16x16x32_bf16 v[84:87], v[194:197], v[218:221], v[84:87]
	v_mfma_f32_16x16x32_bf16 v[72:75], v[160:163], v[234:237], v[72:75]
	v_mfma_f32_16x16x32_bf16 v[68:71], v[194:197], v[234:237], v[68:71]
	v_mfma_f32_16x16x32_bf16 v[136:139], v[190:193], v[206:209], v[136:139]
	v_mfma_f32_16x16x32_bf16 v[132:135], v[198:201], v[206:209], v[132:135]
	v_mfma_f32_16x16x32_bf16 v[104:107], v[190:193], v[214:217], v[104:107]
	v_mfma_f32_16x16x32_bf16 v[100:103], v[198:201], v[214:217], v[100:103]
	v_mfma_f32_16x16x32_bf16 v[88:91], v[190:193], v[222:225], v[88:91]
	v_mfma_f32_16x16x32_bf16 v[84:87], v[198:201], v[222:225], v[84:87]
	v_mfma_f32_16x16x32_bf16 v[72:75], v[190:193], v[238:241], v[72:75]
	v_mfma_f32_16x16x32_bf16 v[68:71], v[198:201], v[238:241], v[68:71]
	s_setprio 0
	s_barrier
; #define PG8_STAGE(bufoff, gbase, voff) do { _Pragma("unroll") for (int _i = 0; _i < 2; ++_i) \
;         __builtin_amdgcn_global_load_lds((const unsigned*)((const char*)(gbase) + (voff)[_i]), (PG8_LAS unsigned*)(lds + (bufoff) + ldsw + _i * 8192), 16, 0, 0); } while (0)
; #define PG8_LDA(dst, b, h) do { _Pragma("unroll") for (int m = 0; m < 4; ++m) _Pragma("unroll") for (int k = 0; k < 2; ++k) dst[m][k] = *(const PG8_LAS bf16x8*)(lds + PG8_SA(b, h) + aoff + m * 2048 + k * 1024); } while (0)
; #define PG8_WAIT_V(n) asm volatile("s_waitcnt vmcnt(" #n ")" ::: "memory")
; #define PG8_WAIT_L(n) asm volatile("s_waitcnt lgkmcnt(" #n ")" ::: "memory")
; #define PG8_BAR __builtin_amdgcn_s_barrier()
; #define PG8_SCHED __builtin_amdgcn_sched_barrier(0)
;     ...
;             PG8_LDA(At, 1, 1); PG8_STAGE(PG8_SB(1, 0), b3, voffB); PG8_STAGE(PG8_SB(1, 1), b3 + hstepB, voffB); PG8_STAGE(PG8_SA(1, 0), a3, voffA);
;             PG8_WAIT_V(8); PG8_WAIT_L(0); PG8_BAR; PG8_MMA(1, 0, At, B0); PG8_MMA(1, 1, At, B1); PG8_BAR; PG8_SCHED;
	s_add_i32 s58, s71, s12
	v_lshl_add_u64 v[226:227], v[226:227], 0, s[22:23]
	s_mov_b32 m0, s58
	ds_read_b128 v[202:205], v188 offset:49152
	ds_read_b128 v[206:209], v188 offset:50176
	ds_read_b128 v[210:213], v188 offset:51200
	ds_read_b128 v[214:217], v188 offset:52224
	ds_read_b128 v[218:221], v188 offset:53248
	ds_read_b128 v[222:225], v188 offset:54272
	ds_read_b128 v[234:237], v188 offset:55296
	ds_read_b128 v[238:241], v188 offset:56320
	global_load_lds_dwordx4 v[226:227], off
	v_lshl_add_u64 v[226:227], v[242:243], 0, s[22:23]
	s_add_i32 m0, s58, 0x2000
	s_add_i32 s58, s74, s12
	global_load_lds_dwordx4 v[226:227], off
	v_lshl_add_u64 v[226:227], v[244:245], 0, s[22:23]
	s_mov_b32 m0, s58
	s_nop 0
	global_load_lds_dwordx4 v[226:227], off
	v_lshl_add_u64 v[226:227], v[246:247], 0, s[22:23]
	s_add_i32 m0, s58, 0x2000
	s_nop 0
	global_load_lds_dwordx4 v[226:227], off
	v_lshl_add_u64 v[226:227], v[248:249], 0, s[22:23]
	s_mov_b32 m0, s57
	s_nop 0
	global_load_lds_dwordx4 v[226:227], off
	v_lshl_add_u64 v[226:227], v[250:251], 0, s[22:23]
	s_mov_b32 m0, s62
	s_nop 0
	global_load_lds_dwordx4 v[226:227], off
	s_waitcnt vmcnt(8)
	s_waitcnt lgkmcnt(0)
	s_barrier
	s_setprio 1
	v_mfma_f32_16x16x32_bf16 v[64:67], v[108:111], v[202:205], v[64:67]
	v_mfma_f32_16x16x32_bf16 v[60:63], v[124:127], v[202:205], v[60:63]
	v_mfma_f32_16x16x32_bf16 v[48:51], v[108:111], v[210:213], v[48:51]
	v_mfma_f32_16x16x32_bf16 v[44:47], v[124:127], v[210:213], v[44:47]
	v_mfma_f32_16x16x32_bf16 v[30:33], v[108:111], v[218:221], v[30:33]
	v_mfma_f32_16x16x32_bf16 v[26:29], v[124:127], v[218:221], v[26:29]
	v_mfma_f32_16x16x32_bf16 v[14:17], v[108:111], v[234:237], v[14:17]
	v_mfma_f32_16x16x32_bf16 v[10:13], v[124:127], v[234:237], v[10:13]
	v_mfma_f32_16x16x32_bf16 v[64:67], v[112:115], v[206:209], v[64:67]
	v_mfma_f32_16x16x32_bf16 v[60:63], v[128:131], v[206:209], v[60:63]
	v_mfma_f32_16x16x32_bf16 v[48:51], v[112:115], v[214:217], v[48:51]
	v_mfma_f32_16x16x32_bf16 v[44:47], v[128:131], v[214:217], v[44:47]
	v_mfma_f32_16x16x32_bf16 v[30:33], v[112:115], v[222:225], v[30:33]
	v_mfma_f32_16x16x32_bf16 v[26:29], v[128:131], v[222:225], v[26:29]
	v_mfma_f32_16x16x32_bf16 v[14:17], v[112:115], v[238:241], v[14:17]
	v_mfma_f32_16x16x32_bf16 v[10:13], v[128:131], v[238:241], v[10:13]
	v_mfma_f32_16x16x32_bf16 v[56:59], v[160:163], v[202:205], v[56:59]
	v_mfma_f32_16x16x32_bf16 v[52:55], v[194:197], v[202:205], v[52:55]
	v_mfma_f32_16x16x32_bf16 v[40:43], v[160:163], v[210:213], v[40:43]
	v_mfma_f32_16x16x32_bf16 v[36:39], v[194:197], v[210:213], v[36:39]
	v_mfma_f32_16x16x32_bf16 v[22:25], v[160:163], v[218:221], v[22:25]
	v_mfma_f32_16x16x32_bf16 v[18:21], v[194:197], v[218:221], v[18:21]
	v_mfma_f32_16x16x32_bf16 v[6:9], v[160:163], v[234:237], v[6:9]
	v_mfma_f32_16x16x32_bf16 v[2:5], v[194:197], v[234:237], v[2:5]
	v_mfma_f32_16x16x32_bf16 v[56:59], v[190:193], v[206:209], v[56:59]
	v_mfma_f32_16x16x32_bf16 v[52:55], v[198:201], v[206:209], v[52:55]
	v_mfma_f32_16x16x32_bf16 v[40:43], v[190:193], v[214:217], v[40:43]
	v_mfma_f32_16x16x32_bf16 v[36:39], v[198:201], v[214:217], v[36:39]
	v_mfma_f32_16x16x32_bf16 v[22:25], v[190:193], v[222:225], v[22:25]
	v_mfma_f32_16x16x32_bf16 v[18:21], v[198:201], v[222:225], v[18:21]
	v_mfma_f32_16x16x32_bf16 v[6:9], v[190:193], v[238:241], v[6:9]
	v_mfma_f32_16x16x32_bf16 v[2:5], v[198:201], v[238:241], v[2:5]
	s_setprio 0
	s_barrier
	s_add_u32 s40, s40, 0x100
	s_addc_u32 s41, s41, 0
	s_add_u32 s60, s60, 0x100
	s_addc_u32 s61, s61, 0
	s_cmp_ge_i32 s70, s35
	s_mov_b32 s58, s70
	s_cbranch_scc0 .LBB0_1503
	s_movk_i32 s71, 0x6ff

; #define PG8_STAGE(bufoff, gbase, voff) do { _Pragma("unroll") for (int _i = 0; _i < 2; ++_i) \
;         __builtin_amdgcn_global_load_lds((const unsigned*)((const char*)(gbase) + (voff)[_i]), (PG8_LAS unsigned*)(lds + (bufoff) + ldsw + _i * 8192), 16, 0, 0); } while (0)
; #define PG8_LDA(dst, b, h) do { _Pragma("unroll") for (int m = 0; m < 4; ++m) _Pragma("unroll") for (int k = 0; k < 2; ++k) dst[m][k] = *(const PG8_LAS bf16x8*)(lds + PG8_SA(b, h) + aoff + m * 2048 + k * 1024); } while (0)
; #define PG8_LDB(dst, b, h) do { _Pragma("unroll") for (int n = 0; n < 2; ++n) _Pragma("unroll") for (int k = 0; k < 2; ++k) dst[n][k] = *(const PG8_LAS bf16x8*)(lds + PG8_SB(b, h) + boff + n * 2048 + k * 1024); } while (0)
; #define PG8_WAIT_V(n) asm volatile("s_waitcnt vmcnt(" #n ")" ::: "memory")
; #define PG8_WAIT_L(n) asm volatile("s_waitcnt lgkmcnt(" #n ")" ::: "memory")
; #define PG8_BAR __builtin_amdgcn_s_barrier()
; #define PG8_SCHED __builtin_amdgcn_sched_barrier(0)
;     ...
;             const bool last = (t == nt - 2);
;             const char* a1 = cA + (size_t)(t + 1) * kstep;
;             const char* a2 = last ? nA : cA + (size_t)(t + 2) * kstep; const char* b2 = last ? nB : cB + (size_t)(t + 2) * kstep;
;             const char* a3 = a2 + kstep; const char* b3 = b2 + kstep;
;             if (last && has_next) S.a_ready(nxt);
;             if constexpr (SP2) {
;             PG8_LDB(B0, 0, 0); PG8_LDB(B1, 0, 1); PG8_SCHED; PG8_LDA(At, 0, 0); PG8_STAGE(PG8_SA(1, 1), a1 + hstepA, voffA);
;             PG8_WAIT_V(8); PG8_WAIT_L(0); PG8_BAR; PG8_MMA(0, 0, At, B0); PG8_MMA(0, 1, At, B1); PG8_BAR; PG8_SCHED;
;             PG8_LDA(At, 0, 1); PG8_STAGE(PG8_SB(0, 0), b2, voffB); PG8_STAGE(PG8_SB(0, 1), b2 + hstepB, voffB); PG8_STAGE(PG8_SA(0, 0), a2, voffA);
;             PG8_WAIT_V(8); PG8_WAIT_L(0); PG8_BAR; PG8_MMA(1, 0, At, B0); PG8_MMA(1, 1, At, B1); PG8_BAR; PG8_SCHED;
.LBB0_2023:
	s_add_u32 s35, s40, 0xfffc0080
	s_addc_u32 s37, s41, -1
	s_add_i32 s43, 0, 0x10000
	s_cmp_eq_u32 s34, 12
	s_cselect_b32 s57, s49, s37
	s_cselect_b32 s56, s48, s35
	s_cselect_b32 s55, s51, s24
	s_cselect_b32 s54, s50, s15
	s_add_i32 s35, 0, 0x14000
	v_add_u32_e32 v154, s43, v235
	v_add_u32_e32 v162, s35, v235
	ds_read_b128 v[142:145], v154
	ds_read_b128 v[146:149], v154 offset:1024
	ds_read_b128 v[150:153], v154 offset:2048
	ds_read_b128 v[154:157], v154 offset:3072
	ds_read_b128 v[158:161], v162
	ds_read_b128 v[186:189], v162 offset:1024
	ds_read_b128 v[190:193], v162 offset:2048
	ds_read_b128 v[194:197], v162 offset:3072
	s_add_i32 m0, s53, 0xc000
	ds_read_b128 v[198:201], v237
	ds_read_b128 v[202:205], v237 offset:1024
	ds_read_b128 v[206:209], v237 offset:2048
	ds_read_b128 v[210:213], v237 offset:3072
	ds_read_b128 v[214:217], v237 offset:4096
	ds_read_b128 v[218:221], v237 offset:5120
	ds_read_b128 v[222:225], v237 offset:6144
	ds_read_b128 v[238:241], v237 offset:7168
	global_load_lds_dwordx4 v138, s[40:41]
	s_add_i32 m0, s53, 0xe000
	s_nop 0
	global_load_lds_dwordx4 v140, s[40:41]
	s_waitcnt vmcnt(8)
	s_waitcnt lgkmcnt(0)
	s_barrier
	s_setprio 1
	v_mfma_f32_16x16x32_bf16 v[128:131], v[142:145], v[198:201], v[128:131]
	v_mfma_f32_16x16x32_bf16 v[124:127], v[150:153], v[198:201], v[124:127]
	v_mfma_f32_16x16x32_bf16 v[120:123], v[142:145], v[206:209], v[120:123]
	v_mfma_f32_16x16x32_bf16 v[116:119], v[150:153], v[206:209], v[116:119]
	v_mfma_f32_16x16x32_bf16 v[112:115], v[142:145], v[214:217], v[112:115]
	v_mfma_f32_16x16x32_bf16 v[108:111], v[150:153], v[214:217], v[108:111]
	v_mfma_f32_16x16x32_bf16 v[104:107], v[142:145], v[222:225], v[104:107]
	v_mfma_f32_16x16x32_bf16 v[100:103], v[150:153], v[222:225], v[100:103]
	v_mfma_f32_16x16x32_bf16 v[128:131], v[146:149], v[202:205], v[128:131]
	v_mfma_f32_16x16x32_bf16 v[124:127], v[154:157], v[202:205], v[124:127]
	v_mfma_f32_16x16x32_bf16 v[120:123], v[146:149], v[210:213], v[120:123]
	v_mfma_f32_16x16x32_bf16 v[116:119], v[154:157], v[210:213], v[116:119]
	v_mfma_f32_16x16x32_bf16 v[112:115], v[146:149], v[218:221], v[112:115]
	v_mfma_f32_16x16x32_bf16 v[108:111], v[154:157], v[218:221], v[108:111]
	v_mfma_f32_16x16x32_bf16 v[104:107], v[146:149], v[238:241], v[104:107]
	v_mfma_f32_16x16x32_bf16 v[100:103], v[154:157], v[238:241], v[100:103]
	v_mfma_f32_16x16x32_bf16 v[96:99], v[158:161], v[198:201], v[96:99]
	v_mfma_f32_16x16x32_bf16 v[92:95], v[190:193], v[198:201], v[92:95]
	v_mfma_f32_16x16x32_bf16 v[88:91], v[158:161], v[206:209], v[88:91]
	v_mfma_f32_16x16x32_bf16 v[84:87], v[190:193], v[206:209], v[84:87]
	v_mfma_f32_16x16x32_bf16 v[80:83], v[158:161], v[214:217], v[80:83]
	v_mfma_f32_16x16x32_bf16 v[76:79], v[190:193], v[214:217], v[76:79]
	v_mfma_f32_16x16x32_bf16 v[72:75], v[158:161], v[222:225], v[72:75]
	v_mfma_f32_16x16x32_bf16 v[68:71], v[190:193], v[222:225], v[68:71]
	v_mfma_f32_16x16x32_bf16 v[96:99], v[186:189], v[202:205], v[96:99]
	v_mfma_f32_16x16x32_bf16 v[92:95], v[194:197], v[202:205], v[92:95]
	v_mfma_f32_16x16x32_bf16 v[88:91], v[186:189], v[210:213], v[88:91]
	v_mfma_f32_16x16x32_bf16 v[84:87], v[194:197], v[210:213], v[84:87]
	v_mfma_f32_16x16x32_bf16 v[80:83], v[186:189], v[218:221], v[80:83]
	v_mfma_f32_16x16x32_bf16 v[76:79], v[194:197], v[218:221], v[76:79]
	v_mfma_f32_16x16x32_bf16 v[72:75], v[186:189], v[238:241], v[72:75]
	v_mfma_f32_16x16x32_bf16 v[68:71], v[194:197], v[238:241], v[68:71]
	s_setprio 0
	s_barrier
	s_add_i32 s37, s43, s21
	s_mov_b32 m0, s37
	ds_read_b128 v[198:201], v237 offset:16384
	ds_read_b128 v[202:205], v237 offset:17408
	ds_read_b128 v[206:209], v237 offset:18432
	ds_read_b128 v[210:213], v237 offset:19456
	ds_read_b128 v[214:217], v237 offset:20480
	ds_read_b128 v[218:221], v237 offset:21504
	ds_read_b128 v[222:225], v237 offset:22528
	ds_read_b128 v[238:241], v237 offset:23552
	global_load_lds_dwordx4 v34, s[54:55]
	s_add_i32 m0, s37, 0x2000
	s_add_u32 s66, s54, 0x40000
	s_addc_u32 s67, s55, 0
	s_add_i32 s35, s35, s21
	global_load_lds_dwordx4 v136, s[54:55]
	s_mov_b32 m0, s35
	v_lshl_add_u64 v[244:245], s[56:57], 0, v[134:135]
	global_load_lds_dwordx4 v34, s[66:67]
	s_add_i32 m0, s35, 0x2000
	s_nop 0
	global_load_lds_dwordx4 v136, s[66:67]
	v_lshl_add_u64 v[242:243], s[56:57], 0, v[132:133]
	s_mov_b32 m0, s53
	s_nop 0
	global_load_lds_dwordx4 v132, s[56:57]
	s_mov_b32 m0, s58
	s_nop 0
	global_load_lds_dwordx4 v134, s[56:57]
	s_waitcnt vmcnt(8)
	s_waitcnt lgkmcnt(0)
	s_barrier
	s_setprio 1
	v_mfma_f32_16x16x32_bf16 v[64:67], v[142:145], v[198:201], v[64:67]
	v_mfma_f32_16x16x32_bf16 v[60:63], v[150:153], v[198:201], v[60:63]
	v_mfma_f32_16x16x32_bf16 v[56:59], v[142:145], v[206:209], v[56:59]
	v_mfma_f32_16x16x32_bf16 v[52:55], v[150:153], v[206:209], v[52:55]
	v_mfma_f32_16x16x32_bf16 v[48:51], v[142:145], v[214:217], v[48:51]
	v_mfma_f32_16x16x32_bf16 v[44:47], v[150:153], v[214:217], v[44:47]
	v_mfma_f32_16x16x32_bf16 v[40:43], v[142:145], v[222:225], v[40:43]
	v_mfma_f32_16x16x32_bf16 v[36:39], v[150:153], v[222:225], v[36:39]
	v_mfma_f32_16x16x32_bf16 v[64:67], v[146:149], v[202:205], v[64:67]
	v_mfma_f32_16x16x32_bf16 v[60:63], v[154:157], v[202:205], v[60:63]
	v_mfma_f32_16x16x32_bf16 v[56:59], v[146:149], v[210:213], v[56:59]
	v_mfma_f32_16x16x32_bf16 v[52:55], v[154:157], v[210:213], v[52:55]
	v_mfma_f32_16x16x32_bf16 v[48:51], v[146:149], v[218:221], v[48:51]
	v_mfma_f32_16x16x32_bf16 v[44:47], v[154:157], v[218:221], v[44:47]
	v_mfma_f32_16x16x32_bf16 v[40:43], v[146:149], v[238:241], v[40:43]
	v_mfma_f32_16x16x32_bf16 v[36:39], v[154:157], v[238:241], v[36:39]
	v_mfma_f32_16x16x32_bf16 v[30:33], v[158:161], v[198:201], v[30:33]
	v_mfma_f32_16x16x32_bf16 v[26:29], v[190:193], v[198:201], v[26:29]
	v_mfma_f32_16x16x32_bf16 v[22:25], v[158:161], v[206:209], v[22:25]
	v_mfma_f32_16x16x32_bf16 v[18:21], v[190:193], v[206:209], v[18:21]
	v_mfma_f32_16x16x32_bf16 v[14:17], v[158:161], v[214:217], v[14:17]
	v_mfma_f32_16x16x32_bf16 v[10:13], v[190:193], v[214:217], v[10:13]
	v_mfma_f32_16x16x32_bf16 v[6:9], v[158:161], v[222:225], v[6:9]
	v_mfma_f32_16x16x32_bf16 v[2:5], v[190:193], v[222:225], v[2:5]
	v_mfma_f32_16x16x32_bf16 v[30:33], v[186:189], v[202:205], v[30:33]
	v_mfma_f32_16x16x32_bf16 v[26:29], v[194:197], v[202:205], v[26:29]
	v_mfma_f32_16x16x32_bf16 v[22:25], v[186:189], v[210:213], v[22:25]
	v_mfma_f32_16x16x32_bf16 v[18:21], v[194:197], v[210:213], v[18:21]
	v_mfma_f32_16x16x32_bf16 v[14:17], v[186:189], v[218:221], v[14:17]
	v_mfma_f32_16x16x32_bf16 v[10:13], v[194:197], v[218:221], v[10:13]
	v_mfma_f32_16x16x32_bf16 v[6:9], v[186:189], v[238:241], v[6:9]
	v_mfma_f32_16x16x32_bf16 v[2:5], v[194:197], v[238:241], v[2:5]
	s_setprio 0
	s_barrier
; #define PG8_STAGE(bufoff, gbase, voff) do { _Pragma("unroll") for (int _i = 0; _i < 2; ++_i) \
;         __builtin_amdgcn_global_load_lds((const unsigned*)((const char*)(gbase) + (voff)[_i]), (PG8_LAS unsigned*)(lds + (bufoff) + ldsw + _i * 8192), 16, 0, 0); } while (0)
; #define PG8_LDA(dst, b, h) do { _Pragma("unroll") for (int m = 0; m < 4; ++m) _Pragma("unroll") for (int k = 0; k < 2; ++k) dst[m][k] = *(const PG8_LAS bf16x8*)(lds + PG8_SA(b, h) + aoff + m * 2048 + k * 1024); } while (0)
; #define PG8_LDB(dst, b, h) do { _Pragma("unroll") for (int n = 0; n < 2; ++n) _Pragma("unroll") for (int k = 0; k < 2; ++k) dst[n][k] = *(const PG8_LAS bf16x8*)(lds + PG8_SB(b, h) + boff + n * 2048 + k * 1024); } while (0)
; #define PG8_WAIT_V(n) asm volatile("s_waitcnt vmcnt(" #n ")" ::: "memory")
; #define PG8_WAIT_L(n) asm volatile("s_waitcnt lgkmcnt(" #n ")" ::: "memory")
; #define PG8_BAR __builtin_amdgcn_s_barrier()
; #define PG8_SCHED __builtin_amdgcn_sched_barrier(0)
;     ...
;             PG8_LDB(B0, 1, 0); PG8_LDB(B1, 1, 1); PG8_SCHED; PG8_LDA(At, 1, 0); PG8_STAGE(PG8_SA(0, 1), a2 + hstepA, voffA);
;             PG8_WAIT_V(8); PG8_WAIT_L(0); PG8_BAR; PG8_MMA(0, 0, At, B0); PG8_MMA(0, 1, At, B1); PG8_BAR; PG8_SCHED;
;             PG8_LDA(At, 1, 1); PG8_STAGE(PG8_SB(1, 0), b3, voffB); PG8_STAGE(PG8_SB(1, 1), b3 + hstepB, voffB); PG8_STAGE(PG8_SA(1, 0), a3, voffA);
;             PG8_WAIT_V(8); PG8_WAIT_L(0); PG8_BAR; PG8_MMA(1, 0, At, B0); PG8_MMA(1, 1, At, B1); PG8_BAR; PG8_SCHED;
	s_add_i32 s35, 0, 0x18000
	s_add_i32 s37, 0, 0x1c000
	v_add_u32_e32 v154, s35, v235
	v_add_u32_e32 v194, s37, v235
	ds_read_b128 v[142:145], v154
	ds_read_b128 v[146:149], v154 offset:1024
	ds_read_b128 v[150:153], v154 offset:2048
	ds_read_b128 v[154:157], v154 offset:3072
	ds_read_b128 v[158:161], v194
	ds_read_b128 v[186:189], v194 offset:1024
	ds_read_b128 v[190:193], v194 offset:2048
	ds_read_b128 v[194:197], v194 offset:3072
	s_add_u32 s56, s56, 0x40000
	s_addc_u32 s57, s57, 0
	s_mov_b32 m0, s59
	ds_read_b128 v[198:201], v237 offset:32768
	ds_read_b128 v[202:205], v237 offset:33792
	ds_read_b128 v[206:209], v237 offset:34816
	ds_read_b128 v[210:213], v237 offset:35840
	ds_read_b128 v[214:217], v237 offset:36864
	ds_read_b128 v[218:221], v237 offset:37888
	ds_read_b128 v[222:225], v237 offset:38912
	ds_read_b128 v[238:241], v237 offset:39936
	global_load_lds_dwordx4 v132, s[56:57]
	v_lshl_add_u64 v[246:247], s[56:57], 0, v[134:135]
	s_mov_b32 m0, s60
	s_nop 0
	global_load_lds_dwordx4 v134, s[56:57]
	s_waitcnt vmcnt(8)
	s_waitcnt lgkmcnt(0)
	s_barrier
	s_setprio 1
	v_mfma_f32_16x16x32_bf16 v[128:131], v[142:145], v[198:201], v[128:131]
	v_mfma_f32_16x16x32_bf16 v[124:127], v[150:153], v[198:201], v[124:127]
	v_mfma_f32_16x16x32_bf16 v[120:123], v[142:145], v[206:209], v[120:123]
	v_mfma_f32_16x16x32_bf16 v[116:119], v[150:153], v[206:209], v[116:119]
	v_mfma_f32_16x16x32_bf16 v[112:115], v[142:145], v[214:217], v[112:115]
	v_mfma_f32_16x16x32_bf16 v[108:111], v[150:153], v[214:217], v[108:111]
	v_mfma_f32_16x16x32_bf16 v[104:107], v[142:145], v[222:225], v[104:107]
	v_mfma_f32_16x16x32_bf16 v[100:103], v[150:153], v[222:225], v[100:103]
	v_mfma_f32_16x16x32_bf16 v[128:131], v[146:149], v[202:205], v[128:131]
	v_mfma_f32_16x16x32_bf16 v[124:127], v[154:157], v[202:205], v[124:127]
	v_mfma_f32_16x16x32_bf16 v[120:123], v[146:149], v[210:213], v[120:123]
	v_mfma_f32_16x16x32_bf16 v[116:119], v[154:157], v[210:213], v[116:119]
	v_mfma_f32_16x16x32_bf16 v[112:115], v[146:149], v[218:221], v[112:115]
	v_mfma_f32_16x16x32_bf16 v[108:111], v[154:157], v[218:221], v[108:111]
	v_mfma_f32_16x16x32_bf16 v[104:107], v[146:149], v[238:241], v[104:107]
	v_mfma_f32_16x16x32_bf16 v[100:103], v[154:157], v[238:241], v[100:103]
	v_mfma_f32_16x16x32_bf16 v[96:99], v[158:161], v[198:201], v[96:99]
	v_mfma_f32_16x16x32_bf16 v[92:95], v[190:193], v[198:201], v[92:95]
	v_mfma_f32_16x16x32_bf16 v[88:91], v[158:161], v[206:209], v[88:91]
	v_mfma_f32_16x16x32_bf16 v[84:87], v[190:193], v[206:209], v[84:87]
	v_mfma_f32_16x16x32_bf16 v[80:83], v[158:161], v[214:217], v[80:83]
	v_mfma_f32_16x16x32_bf16 v[76:79], v[190:193], v[214:217], v[76:79]
	v_mfma_f32_16x16x32_bf16 v[72:75], v[158:161], v[222:225], v[72:75]
	v_mfma_f32_16x16x32_bf16 v[68:71], v[190:193], v[222:225], v[68:71]
	v_mfma_f32_16x16x32_bf16 v[96:99], v[186:189], v[202:205], v[96:99]
	v_mfma_f32_16x16x32_bf16 v[92:95], v[194:197], v[202:205], v[92:95]
	v_mfma_f32_16x16x32_bf16 v[88:91], v[186:189], v[210:213], v[88:91]
	v_mfma_f32_16x16x32_bf16 v[84:87], v[194:197], v[210:213], v[84:87]
	v_mfma_f32_16x16x32_bf16 v[80:83], v[186:189], v[218:221], v[80:83]
	v_mfma_f32_16x16x32_bf16 v[76:79], v[194:197], v[218:221], v[76:79]
	v_mfma_f32_16x16x32_bf16 v[72:75], v[186:189], v[238:241], v[72:75]
	v_mfma_f32_16x16x32_bf16 v[68:71], v[194:197], v[238:241], v[68:71]
	s_setprio 0
	s_barrier
	s_add_i32 s35, s35, s21
	s_mov_b32 m0, s35
	ds_read_b128 v[198:201], v237 offset:49152
	ds_read_b128 v[202:205], v237 offset:50176
	ds_read_b128 v[206:209], v237 offset:51200
	ds_read_b128 v[210:213], v237 offset:52224
	ds_read_b128 v[214:217], v237 offset:53248
	ds_read_b128 v[218:221], v237 offset:54272
	ds_read_b128 v[222:225], v237 offset:55296
	ds_read_b128 v[238:241], v237 offset:56320
	s_add_u32 s98, s54, 0x80
	s_addc_u32 s99, s55, 0
	global_load_lds_dwordx4 v34, s[98:99]
	s_add_i32 m0, s35, 0x2000
	s_add_u32 s54, s54, 0x40080
	s_addc_u32 s55, s55, 0
	s_add_i32 s35, s37, s21
	s_add_u32 s98, s54, 0xfffc0000
	s_addc_u32 s99, s55, -1
	global_load_lds_dwordx4 v136, s[98:99]
	s_mov_b32 m0, s35
	s_nop 0
	global_load_lds_dwordx4 v34, s[54:55]
	s_add_i32 m0, s35, 0x2000
	s_nop 0
	global_load_lds_dwordx4 v136, s[54:55]
	s_mov_b32 m0, s61
	s_nop 0
	s_add_u32 s98, s56, 0xfffc0080
	s_addc_u32 s99, s57, -1
	global_load_lds_dwordx4 v132, s[98:99]
	v_lshl_add_u64 v[162:163], v[244:245], 0, s[22:23]
	s_mov_b32 m0, s62
	s_nop 0
	s_add_u32 s98, s56, 0xfffc0080
	s_addc_u32 s99, s57, -1
	global_load_lds_dwordx4 v134, s[98:99]
	s_waitcnt vmcnt(8)
	s_waitcnt lgkmcnt(0)
	s_barrier
	s_setprio 1
	v_mfma_f32_16x16x32_bf16 v[64:67], v[142:145], v[198:201], v[64:67]
	v_mfma_f32_16x16x32_bf16 v[60:63], v[150:153], v[198:201], v[60:63]
	v_mfma_f32_16x16x32_bf16 v[56:59], v[142:145], v[206:209], v[56:59]
	v_mfma_f32_16x16x32_bf16 v[52:55], v[150:153], v[206:209], v[52:55]
	v_mfma_f32_16x16x32_bf16 v[48:51], v[142:145], v[214:217], v[48:51]
	v_mfma_f32_16x16x32_bf16 v[44:47], v[150:153], v[214:217], v[44:47]
	v_mfma_f32_16x16x32_bf16 v[40:43], v[142:145], v[222:225], v[40:43]
	v_mfma_f32_16x16x32_bf16 v[36:39], v[150:153], v[222:225], v[36:39]
	v_mfma_f32_16x16x32_bf16 v[64:67], v[146:149], v[202:205], v[64:67]
	v_mfma_f32_16x16x32_bf16 v[60:63], v[154:157], v[202:205], v[60:63]
	v_mfma_f32_16x16x32_bf16 v[56:59], v[146:149], v[210:213], v[56:59]
	v_mfma_f32_16x16x32_bf16 v[52:55], v[154:157], v[210:213], v[52:55]
	v_mfma_f32_16x16x32_bf16 v[48:51], v[146:149], v[218:221], v[48:51]
	v_mfma_f32_16x16x32_bf16 v[44:47], v[154:157], v[218:221], v[44:47]
	v_mfma_f32_16x16x32_bf16 v[40:43], v[146:149], v[238:241], v[40:43]
	v_mfma_f32_16x16x32_bf16 v[36:39], v[154:157], v[238:241], v[36:39]
	v_mfma_f32_16x16x32_bf16 v[30:33], v[158:161], v[198:201], v[30:33]
	v_mfma_f32_16x16x32_bf16 v[26:29], v[190:193], v[198:201], v[26:29]
	v_mfma_f32_16x16x32_bf16 v[22:25], v[158:161], v[206:209], v[22:25]
	v_mfma_f32_16x16x32_bf16 v[18:21], v[190:193], v[206:209], v[18:21]
	v_mfma_f32_16x16x32_bf16 v[14:17], v[158:161], v[214:217], v[14:17]
	v_mfma_f32_16x16x32_bf16 v[10:13], v[190:193], v[214:217], v[10:13]
	v_mfma_f32_16x16x32_bf16 v[6:9], v[158:161], v[222:225], v[6:9]
	v_mfma_f32_16x16x32_bf16 v[2:5], v[190:193], v[222:225], v[2:5]
	v_mfma_f32_16x16x32_bf16 v[30:33], v[186:189], v[202:205], v[30:33]
	v_mfma_f32_16x16x32_bf16 v[26:29], v[194:197], v[202:205], v[26:29]
	v_mfma_f32_16x16x32_bf16 v[22:25], v[186:189], v[210:213], v[22:25]
	v_mfma_f32_16x16x32_bf16 v[18:21], v[194:197], v[210:213], v[18:21]
	v_mfma_f32_16x16x32_bf16 v[14:17], v[186:189], v[218:221], v[14:17]
	v_mfma_f32_16x16x32_bf16 v[10:13], v[194:197], v[218:221], v[10:13]
	v_mfma_f32_16x16x32_bf16 v[6:9], v[186:189], v[238:241], v[6:9]
	v_mfma_f32_16x16x32_bf16 v[2:5], v[194:197], v[238:241], v[2:5]
	s_setprio 0
	s_barrier
	s_add_i32 s34, s34, 2
	s_add_u32 s40, s40, 0x100
	s_addc_u32 s41, s41, 0
	s_add_u32 s15, s15, 0x100
	s_addc_u32 s24, s24, 0
	s_cmp_gt_u32 s34, 13
	s_cbranch_scc0 .LBB0_2023
	s_and_b64 vcc, exec, s[30:31]
	s_cbranch_vccz .LBB0_2026
	s_barrier

; #define PG8_STAGE(bufoff, gbase, voff) do { _Pragma("unroll") for (int _i = 0; _i < 2; ++_i) \
;         __builtin_amdgcn_global_load_lds((const unsigned*)((const char*)(gbase) + (voff)[_i]), (PG8_LAS unsigned*)(lds + (bufoff) + ldsw + _i * 8192), 16, 0, 0); } while (0)
; #define PG8_LDA(dst, b, h) do { _Pragma("unroll") for (int m = 0; m < 4; ++m) _Pragma("unroll") for (int k = 0; k < 2; ++k) dst[m][k] = *(const PG8_LAS bf16x8*)(lds + PG8_SA(b, h) + aoff + m * 2048 + k * 1024); } while (0)
; #define PG8_LDB(dst, b, h) do { _Pragma("unroll") for (int n = 0; n < 2; ++n) _Pragma("unroll") for (int k = 0; k < 2; ++k) dst[n][k] = *(const PG8_LAS bf16x8*)(lds + PG8_SB(b, h) + boff + n * 2048 + k * 1024); } while (0)
; #define PG8_WAIT_V(n) asm volatile("s_waitcnt vmcnt(" #n ")" ::: "memory")
; #define PG8_WAIT_L(n) asm volatile("s_waitcnt lgkmcnt(" #n ")" ::: "memory")
; #define PG8_BAR __builtin_amdgcn_s_barrier()
; #define PG8_SCHED __builtin_amdgcn_sched_barrier(0)
;     ...
;             const bool last = (t == nt - 2);
;             const char* a1 = cA + (size_t)(t + 1) * kstep;
;             const char* a2 = last ? nA : cA + (size_t)(t + 2) * kstep; const char* b2 = last ? nB : cB + (size_t)(t + 2) * kstep;
;             const char* a3 = a2 + kstep; const char* b3 = b2 + kstep;
;             if (last && has_next) S.a_ready(nxt);
;             if constexpr (SP2) {
;             PG8_LDB(B0, 0, 0); PG8_LDB(B1, 0, 1); PG8_SCHED; PG8_LDA(At, 0, 0); PG8_STAGE(PG8_SA(1, 1), a1 + hstepA, voffA);
;             PG8_WAIT_V(8); PG8_WAIT_L(0); PG8_BAR; PG8_MMA(0, 0, At, B0); PG8_MMA(0, 1, At, B1); PG8_BAR; PG8_SCHED;
;             PG8_LDA(At, 0, 1); PG8_STAGE(PG8_SB(0, 0), b2, voffB); PG8_STAGE(PG8_SB(0, 1), b2 + hstepB, voffB); PG8_STAGE(PG8_SA(0, 0), a2, voffA);
;             PG8_WAIT_V(8); PG8_WAIT_L(0); PG8_BAR; PG8_MMA(1, 0, At, B0); PG8_MMA(1, 1, At, B1); PG8_BAR; PG8_SCHED;
.LBB0_2138:
	s_add_u32 s48, s46, 0xfff80080
	s_addc_u32 s49, s47, -1
	s_add_i32 s61, 0, 0x10000
	s_cmp_eq_u32 s60, 28
	s_cselect_b32 s51, s41, s49
	s_cselect_b32 s50, s56, s48
	s_cselect_b32 s49, s37, s59
	s_cselect_b32 s48, s57, s58
	s_add_i32 s64, 0, 0x14000
	v_add_u32_e32 v158, s61, v143
	v_add_u32_e32 v162, s64, v143
	ds_read_b128 v[146:149], v158
	ds_read_b128 v[150:153], v158 offset:1024
	ds_read_b128 v[154:157], v158 offset:2048
	ds_read_b128 v[158:161], v158 offset:3072
	ds_read_b128 v[186:189], v162
	ds_read_b128 v[190:193], v162 offset:1024
	ds_read_b128 v[194:197], v162 offset:2048
	ds_read_b128 v[198:201], v162 offset:3072
	s_add_i32 m0, s21, 0xc000
	ds_read_b128 v[202:205], v145
	ds_read_b128 v[206:209], v145 offset:1024
	ds_read_b128 v[210:213], v145 offset:2048
	ds_read_b128 v[214:217], v145 offset:3072
	ds_read_b128 v[218:221], v145 offset:4096
	ds_read_b128 v[222:225], v145 offset:5120
	ds_read_b128 v[234:237], v145 offset:6144
	ds_read_b128 v[238:241], v145 offset:7168
	global_load_lds_dwordx4 v138, s[46:47]
	s_add_i32 m0, s21, 0xe000
	s_nop 0
	global_load_lds_dwordx4 v140, s[46:47]
	s_waitcnt vmcnt(8)
	s_waitcnt lgkmcnt(0)
	s_barrier
	s_setprio 1
	v_mfma_f32_16x16x32_bf16 v[128:131], v[146:149], v[202:205], v[128:131]
	v_mfma_f32_16x16x32_bf16 v[124:127], v[154:157], v[202:205], v[124:127]
	v_mfma_f32_16x16x32_bf16 v[120:123], v[146:149], v[210:213], v[120:123]
	v_mfma_f32_16x16x32_bf16 v[116:119], v[154:157], v[210:213], v[116:119]
	v_mfma_f32_16x16x32_bf16 v[104:107], v[146:149], v[218:221], v[104:107]
	v_mfma_f32_16x16x32_bf16 v[100:103], v[154:157], v[218:221], v[100:103]
	v_mfma_f32_16x16x32_bf16 v[88:91], v[146:149], v[234:237], v[88:91]
	v_mfma_f32_16x16x32_bf16 v[84:87], v[154:157], v[234:237], v[84:87]
	v_mfma_f32_16x16x32_bf16 v[128:131], v[150:153], v[206:209], v[128:131]
	v_mfma_f32_16x16x32_bf16 v[124:127], v[158:161], v[206:209], v[124:127]
	v_mfma_f32_16x16x32_bf16 v[120:123], v[150:153], v[214:217], v[120:123]
	v_mfma_f32_16x16x32_bf16 v[116:119], v[158:161], v[214:217], v[116:119]
	v_mfma_f32_16x16x32_bf16 v[104:107], v[150:153], v[222:225], v[104:107]
	v_mfma_f32_16x16x32_bf16 v[100:103], v[158:161], v[222:225], v[100:103]
	v_mfma_f32_16x16x32_bf16 v[88:91], v[150:153], v[238:241], v[88:91]
	v_mfma_f32_16x16x32_bf16 v[84:87], v[158:161], v[238:241], v[84:87]
	v_mfma_f32_16x16x32_bf16 v[112:115], v[186:189], v[202:205], v[112:115]
	v_mfma_f32_16x16x32_bf16 v[108:111], v[194:197], v[202:205], v[108:111]
	v_mfma_f32_16x16x32_bf16 v[96:99], v[186:189], v[210:213], v[96:99]
	v_mfma_f32_16x16x32_bf16 v[92:95], v[194:197], v[210:213], v[92:95]
	v_mfma_f32_16x16x32_bf16 v[80:83], v[186:189], v[218:221], v[80:83]
	v_mfma_f32_16x16x32_bf16 v[76:79], v[194:197], v[218:221], v[76:79]
	v_mfma_f32_16x16x32_bf16 v[72:75], v[186:189], v[234:237], v[72:75]
	v_mfma_f32_16x16x32_bf16 v[68:71], v[194:197], v[234:237], v[68:71]
	v_mfma_f32_16x16x32_bf16 v[112:115], v[190:193], v[206:209], v[112:115]
	v_mfma_f32_16x16x32_bf16 v[108:111], v[198:201], v[206:209], v[108:111]
	v_mfma_f32_16x16x32_bf16 v[96:99], v[190:193], v[214:217], v[96:99]
	v_mfma_f32_16x16x32_bf16 v[92:95], v[198:201], v[214:217], v[92:95]
	v_mfma_f32_16x16x32_bf16 v[80:83], v[190:193], v[222:225], v[80:83]
	v_mfma_f32_16x16x32_bf16 v[76:79], v[198:201], v[222:225], v[76:79]
	v_mfma_f32_16x16x32_bf16 v[72:75], v[190:193], v[238:241], v[72:75]
	v_mfma_f32_16x16x32_bf16 v[68:71], v[198:201], v[238:241], v[68:71]
	s_setprio 0
	s_barrier
	s_add_i32 s61, s61, s15
	s_mov_b32 m0, s61
	ds_read_b128 v[202:205], v145 offset:16384
	ds_read_b128 v[206:209], v145 offset:17408
	ds_read_b128 v[210:213], v145 offset:18432
	ds_read_b128 v[214:217], v145 offset:19456
	ds_read_b128 v[218:221], v145 offset:20480
	ds_read_b128 v[222:225], v145 offset:21504
	ds_read_b128 v[234:237], v145 offset:22528
	ds_read_b128 v[238:241], v145 offset:23552
	global_load_lds_dwordx4 v34, s[48:49]
	s_add_i32 m0, s61, 0x2000
	s_add_u32 s62, s48, 0x80000
	v_lshl_add_u64 v[226:227], s[48:49], 0, v[136:137]
	s_addc_u32 s63, s49, 0
	s_add_i32 s61, s64, s15
	global_load_lds_dwordx4 v136, s[48:49]
	s_mov_b32 m0, s61
	v_lshl_add_u64 v[244:245], s[50:51], 0, v[134:135]
	global_load_lds_dwordx4 v34, s[62:63]
	s_add_i32 m0, s61, 0x2000
	s_nop 0
	global_load_lds_dwordx4 v136, s[62:63]
	v_lshl_add_u64 v[242:243], s[50:51], 0, v[132:133]
	s_mov_b32 m0, s21
	s_nop 0
	global_load_lds_dwordx4 v132, s[50:51]
	s_mov_b32 m0, s34
	s_nop 0
	global_load_lds_dwordx4 v134, s[50:51]
	s_waitcnt vmcnt(8)
	s_waitcnt lgkmcnt(0)
	s_barrier
; #define PG8_STAGE(bufoff, gbase, voff) do { _Pragma("unroll") for (int _i = 0; _i < 2; ++_i) \
;         __builtin_amdgcn_global_load_lds((const unsigned*)((const char*)(gbase) + (voff)[_i]), (PG8_LAS unsigned*)(lds + (bufoff) + ldsw + _i * 8192), 16, 0, 0); } while (0)
; #define PG8_LDA(dst, b, h) do { _Pragma("unroll") for (int m = 0; m < 4; ++m) _Pragma("unroll") for (int k = 0; k < 2; ++k) dst[m][k] = *(const PG8_LAS bf16x8*)(lds + PG8_SA(b, h) + aoff + m * 2048 + k * 1024); } while (0)
; #define PG8_LDB(dst, b, h) do { _Pragma("unroll") for (int n = 0; n < 2; ++n) _Pragma("unroll") for (int k = 0; k < 2; ++k) dst[n][k] = *(const PG8_LAS bf16x8*)(lds + PG8_SB(b, h) + boff + n * 2048 + k * 1024); } while (0)
; #define PG8_WAIT_V(n) asm volatile("s_waitcnt vmcnt(" #n ")" ::: "memory")
; #define PG8_WAIT_L(n) asm volatile("s_waitcnt lgkmcnt(" #n ")" ::: "memory")
; #define PG8_BAR __builtin_amdgcn_s_barrier()
; #define PG8_SCHED __builtin_amdgcn_sched_barrier(0)
;     ...
;             PG8_WAIT_V(8); PG8_WAIT_L(0); PG8_BAR; PG8_MMA(1, 0, At, B0); PG8_MMA(1, 1, At, B1); PG8_BAR; PG8_SCHED;
;             PG8_LDB(B0, 1, 0); PG8_LDB(B1, 1, 1); PG8_SCHED; PG8_LDA(At, 1, 0); PG8_STAGE(PG8_SA(0, 1), a2 + hstepA, voffA);
;             PG8_WAIT_V(8); PG8_WAIT_L(0); PG8_BAR; PG8_MMA(0, 0, At, B0); PG8_MMA(0, 1, At, B1); PG8_BAR; PG8_SCHED;
	s_setprio 1
	v_mfma_f32_16x16x32_bf16 v[64:67], v[146:149], v[202:205], v[64:67]
	v_mfma_f32_16x16x32_bf16 v[60:63], v[154:157], v[202:205], v[60:63]
	v_mfma_f32_16x16x32_bf16 v[56:59], v[146:149], v[210:213], v[56:59]
	v_mfma_f32_16x16x32_bf16 v[52:55], v[154:157], v[210:213], v[52:55]
	v_mfma_f32_16x16x32_bf16 v[40:43], v[146:149], v[218:221], v[40:43]
	v_mfma_f32_16x16x32_bf16 v[36:39], v[154:157], v[218:221], v[36:39]
	v_mfma_f32_16x16x32_bf16 v[22:25], v[146:149], v[234:237], v[22:25]
	v_mfma_f32_16x16x32_bf16 v[18:21], v[154:157], v[234:237], v[18:21]
	v_mfma_f32_16x16x32_bf16 v[64:67], v[150:153], v[206:209], v[64:67]
	v_mfma_f32_16x16x32_bf16 v[60:63], v[158:161], v[206:209], v[60:63]
	v_mfma_f32_16x16x32_bf16 v[56:59], v[150:153], v[214:217], v[56:59]
	v_mfma_f32_16x16x32_bf16 v[52:55], v[158:161], v[214:217], v[52:55]
	v_mfma_f32_16x16x32_bf16 v[40:43], v[150:153], v[222:225], v[40:43]
	v_mfma_f32_16x16x32_bf16 v[36:39], v[158:161], v[222:225], v[36:39]
	v_mfma_f32_16x16x32_bf16 v[22:25], v[150:153], v[238:241], v[22:25]
	v_mfma_f32_16x16x32_bf16 v[18:21], v[158:161], v[238:241], v[18:21]
	v_mfma_f32_16x16x32_bf16 v[48:51], v[186:189], v[202:205], v[48:51]
	v_mfma_f32_16x16x32_bf16 v[44:47], v[194:197], v[202:205], v[44:47]
	v_mfma_f32_16x16x32_bf16 v[30:33], v[186:189], v[210:213], v[30:33]
	v_mfma_f32_16x16x32_bf16 v[26:29], v[194:197], v[210:213], v[26:29]
	v_mfma_f32_16x16x32_bf16 v[14:17], v[186:189], v[218:221], v[14:17]
	v_mfma_f32_16x16x32_bf16 v[10:13], v[194:197], v[218:221], v[10:13]
	v_mfma_f32_16x16x32_bf16 v[6:9], v[186:189], v[234:237], v[6:9]
	v_mfma_f32_16x16x32_bf16 v[2:5], v[194:197], v[234:237], v[2:5]
	v_mfma_f32_16x16x32_bf16 v[48:51], v[190:193], v[206:209], v[48:51]
	v_mfma_f32_16x16x32_bf16 v[44:47], v[198:201], v[206:209], v[44:47]
	v_mfma_f32_16x16x32_bf16 v[30:33], v[190:193], v[214:217], v[30:33]
	v_mfma_f32_16x16x32_bf16 v[26:29], v[198:201], v[214:217], v[26:29]
	v_mfma_f32_16x16x32_bf16 v[14:17], v[190:193], v[222:225], v[14:17]
	v_mfma_f32_16x16x32_bf16 v[10:13], v[198:201], v[222:225], v[10:13]
	v_mfma_f32_16x16x32_bf16 v[6:9], v[190:193], v[238:241], v[6:9]
	v_mfma_f32_16x16x32_bf16 v[2:5], v[198:201], v[238:241], v[2:5]
	s_setprio 0
	s_barrier
	s_add_i32 s61, 0, 0x18000
	s_add_i32 s62, 0, 0x1c000
	v_add_u32_e32 v158, s61, v143
	v_add_u32_e32 v198, s62, v143
	ds_read_b128 v[146:149], v158
	ds_read_b128 v[150:153], v158 offset:1024
	ds_read_b128 v[154:157], v158 offset:2048
	ds_read_b128 v[158:161], v158 offset:3072
	ds_read_b128 v[186:189], v198
	ds_read_b128 v[190:193], v198 offset:1024
	ds_read_b128 v[194:197], v198 offset:2048
	ds_read_b128 v[198:201], v198 offset:3072
	s_add_u32 s50, s50, 0x80000
	s_addc_u32 s51, s51, 0
	s_mov_b32 m0, s35
	ds_read_b128 v[202:205], v145 offset:32768
	ds_read_b128 v[206:209], v145 offset:33792
	ds_read_b128 v[210:213], v145 offset:34816
	ds_read_b128 v[214:217], v145 offset:35840
	ds_read_b128 v[218:221], v145 offset:36864
	ds_read_b128 v[222:225], v145 offset:37888
	ds_read_b128 v[234:237], v145 offset:38912
	ds_read_b128 v[238:241], v145 offset:39936
	global_load_lds_dwordx4 v132, s[50:51]
	v_lshl_add_u64 v[246:247], s[50:51], 0, v[134:135]
	s_mov_b32 m0, s52
	s_nop 0
	global_load_lds_dwordx4 v134, s[50:51]
	s_waitcnt vmcnt(8)
	s_waitcnt lgkmcnt(0)
	s_barrier
	s_setprio 1
	v_mfma_f32_16x16x32_bf16 v[128:131], v[146:149], v[202:205], v[128:131]
	v_mfma_f32_16x16x32_bf16 v[124:127], v[154:157], v[202:205], v[124:127]
	v_mfma_f32_16x16x32_bf16 v[120:123], v[146:149], v[210:213], v[120:123]
	v_mfma_f32_16x16x32_bf16 v[116:119], v[154:157], v[210:213], v[116:119]
	v_mfma_f32_16x16x32_bf16 v[104:107], v[146:149], v[218:221], v[104:107]
	v_mfma_f32_16x16x32_bf16 v[100:103], v[154:157], v[218:221], v[100:103]
	v_mfma_f32_16x16x32_bf16 v[88:91], v[146:149], v[234:237], v[88:91]
	v_mfma_f32_16x16x32_bf16 v[84:87], v[154:157], v[234:237], v[84:87]
	v_mfma_f32_16x16x32_bf16 v[128:131], v[150:153], v[206:209], v[128:131]
	v_mfma_f32_16x16x32_bf16 v[124:127], v[158:161], v[206:209], v[124:127]
	v_mfma_f32_16x16x32_bf16 v[120:123], v[150:153], v[214:217], v[120:123]
	v_mfma_f32_16x16x32_bf16 v[116:119], v[158:161], v[214:217], v[116:119]
	v_mfma_f32_16x16x32_bf16 v[104:107], v[150:153], v[222:225], v[104:107]
	v_mfma_f32_16x16x32_bf16 v[100:103], v[158:161], v[222:225], v[100:103]
	v_mfma_f32_16x16x32_bf16 v[88:91], v[150:153], v[238:241], v[88:91]
	v_mfma_f32_16x16x32_bf16 v[84:87], v[158:161], v[238:241], v[84:87]
	v_mfma_f32_16x16x32_bf16 v[112:115], v[186:189], v[202:205], v[112:115]
	v_mfma_f32_16x16x32_bf16 v[108:111], v[194:197], v[202:205], v[108:111]
	v_mfma_f32_16x16x32_bf16 v[96:99], v[186:189], v[210:213], v[96:99]
	v_mfma_f32_16x16x32_bf16 v[92:95], v[194:197], v[210:213], v[92:95]
	v_mfma_f32_16x16x32_bf16 v[80:83], v[186:189], v[218:221], v[80:83]
	v_mfma_f32_16x16x32_bf16 v[76:79], v[194:197], v[218:221], v[76:79]
	v_mfma_f32_16x16x32_bf16 v[72:75], v[186:189], v[234:237], v[72:75]
	v_mfma_f32_16x16x32_bf16 v[68:71], v[194:197], v[234:237], v[68:71]
	v_mfma_f32_16x16x32_bf16 v[112:115], v[190:193], v[206:209], v[112:115]
	v_mfma_f32_16x16x32_bf16 v[108:111], v[198:201], v[206:209], v[108:111]
	v_mfma_f32_16x16x32_bf16 v[96:99], v[190:193], v[214:217], v[96:99]
	v_mfma_f32_16x16x32_bf16 v[92:95], v[198:201], v[214:217], v[92:95]
	v_mfma_f32_16x16x32_bf16 v[80:83], v[190:193], v[222:225], v[80:83]
	v_mfma_f32_16x16x32_bf16 v[76:79], v[198:201], v[222:225], v[76:79]
	v_mfma_f32_16x16x32_bf16 v[72:75], v[190:193], v[238:241], v[72:75]
	v_mfma_f32_16x16x32_bf16 v[68:71], v[198:201], v[238:241], v[68:71]
	s_setprio 0
	s_barrier
; #define PG8_STAGE(bufoff, gbase, voff) do { _Pragma("unroll") for (int _i = 0; _i < 2; ++_i) \
;         __builtin_amdgcn_global_load_lds((const unsigned*)((const char*)(gbase) + (voff)[_i]), (PG8_LAS unsigned*)(lds + (bufoff) + ldsw + _i * 8192), 16, 0, 0); } while (0)
; #define PG8_LDA(dst, b, h) do { _Pragma("unroll") for (int m = 0; m < 4; ++m) _Pragma("unroll") for (int k = 0; k < 2; ++k) dst[m][k] = *(const PG8_LAS bf16x8*)(lds + PG8_SA(b, h) + aoff + m * 2048 + k * 1024); } while (0)
; #define PG8_WAIT_V(n) asm volatile("s_waitcnt vmcnt(" #n ")" ::: "memory")
; #define PG8_WAIT_L(n) asm volatile("s_waitcnt lgkmcnt(" #n ")" ::: "memory")
; #define PG8_BAR __builtin_amdgcn_s_barrier()
; #define PG8_SCHED __builtin_amdgcn_sched_barrier(0)
;     ...
;             PG8_LDA(At, 1, 1); PG8_STAGE(PG8_SB(1, 0), b3, voffB); PG8_STAGE(PG8_SB(1, 1), b3 + hstepB, voffB); PG8_STAGE(PG8_SA(1, 0), a3, voffA);
;             PG8_WAIT_V(8); PG8_WAIT_L(0); PG8_BAR; PG8_MMA(1, 0, At, B0); PG8_MMA(1, 1, At, B1); PG8_BAR; PG8_SCHED;
	s_add_i32 s50, s61, s15
	s_mov_b32 m0, s50
	ds_read_b128 v[202:205], v145 offset:49152
	ds_read_b128 v[206:209], v145 offset:50176
	ds_read_b128 v[210:213], v145 offset:51200
	ds_read_b128 v[214:217], v145 offset:52224
	ds_read_b128 v[218:221], v145 offset:53248
	ds_read_b128 v[222:225], v145 offset:54272
	ds_read_b128 v[234:237], v145 offset:55296
	ds_read_b128 v[238:241], v145 offset:56320
	s_add_u32 s98, s48, 0x80
	s_addc_u32 s99, s49, 0
	global_load_lds_dwordx4 v34, s[98:99]
	s_add_i32 m0, s50, 0x2000
	s_add_u32 s48, s48, 0x80080
	s_addc_u32 s49, s49, 0
	s_add_i32 s50, s62, s15
	s_add_u32 s98, s48, 0xfff80000
	s_addc_u32 s99, s49, -1
	global_load_lds_dwordx4 v136, s[98:99]
	s_mov_b32 m0, s50
	s_nop 0
	global_load_lds_dwordx4 v34, s[48:49]
	s_add_i32 m0, s50, 0x2000
	s_nop 0
	global_load_lds_dwordx4 v136, s[48:49]
	v_lshl_add_u64 v[162:163], v[242:243], 0, s[22:23]
	s_mov_b32 m0, s24
	s_nop 0
	global_load_lds_dwordx4 v[162:163], off
	v_lshl_add_u64 v[162:163], v[244:245], 0, s[22:23]
	s_mov_b32 m0, s53
	s_nop 0
	global_load_lds_dwordx4 v[162:163], off
	s_waitcnt vmcnt(8)
	s_waitcnt lgkmcnt(0)
	s_barrier
	s_setprio 1
	v_mfma_f32_16x16x32_bf16 v[64:67], v[146:149], v[202:205], v[64:67]
	v_mfma_f32_16x16x32_bf16 v[60:63], v[154:157], v[202:205], v[60:63]
	v_mfma_f32_16x16x32_bf16 v[56:59], v[146:149], v[210:213], v[56:59]
	v_mfma_f32_16x16x32_bf16 v[52:55], v[154:157], v[210:213], v[52:55]
	v_mfma_f32_16x16x32_bf16 v[40:43], v[146:149], v[218:221], v[40:43]
	v_mfma_f32_16x16x32_bf16 v[36:39], v[154:157], v[218:221], v[36:39]
	v_mfma_f32_16x16x32_bf16 v[22:25], v[146:149], v[234:237], v[22:25]
	v_mfma_f32_16x16x32_bf16 v[18:21], v[154:157], v[234:237], v[18:21]
	v_mfma_f32_16x16x32_bf16 v[64:67], v[150:153], v[206:209], v[64:67]
	v_mfma_f32_16x16x32_bf16 v[60:63], v[158:161], v[206:209], v[60:63]
	v_mfma_f32_16x16x32_bf16 v[56:59], v[150:153], v[214:217], v[56:59]
	v_mfma_f32_16x16x32_bf16 v[52:55], v[158:161], v[214:217], v[52:55]
	v_mfma_f32_16x16x32_bf16 v[40:43], v[150:153], v[222:225], v[40:43]
	v_mfma_f32_16x16x32_bf16 v[36:39], v[158:161], v[222:225], v[36:39]
	v_mfma_f32_16x16x32_bf16 v[22:25], v[150:153], v[238:241], v[22:25]
	v_mfma_f32_16x16x32_bf16 v[18:21], v[158:161], v[238:241], v[18:21]
	v_mfma_f32_16x16x32_bf16 v[48:51], v[186:189], v[202:205], v[48:51]
	v_mfma_f32_16x16x32_bf16 v[44:47], v[194:197], v[202:205], v[44:47]
	v_mfma_f32_16x16x32_bf16 v[30:33], v[186:189], v[210:213], v[30:33]
	v_mfma_f32_16x16x32_bf16 v[26:29], v[194:197], v[210:213], v[26:29]
	v_mfma_f32_16x16x32_bf16 v[14:17], v[186:189], v[218:221], v[14:17]
	v_mfma_f32_16x16x32_bf16 v[10:13], v[194:197], v[218:221], v[10:13]
	v_mfma_f32_16x16x32_bf16 v[6:9], v[186:189], v[234:237], v[6:9]
	v_mfma_f32_16x16x32_bf16 v[2:5], v[194:197], v[234:237], v[2:5]
	v_mfma_f32_16x16x32_bf16 v[48:51], v[190:193], v[206:209], v[48:51]
	v_mfma_f32_16x16x32_bf16 v[44:47], v[198:201], v[206:209], v[44:47]
	v_mfma_f32_16x16x32_bf16 v[30:33], v[190:193], v[214:217], v[30:33]
	v_mfma_f32_16x16x32_bf16 v[26:29], v[198:201], v[214:217], v[26:29]
	v_mfma_f32_16x16x32_bf16 v[14:17], v[190:193], v[222:225], v[14:17]
	v_mfma_f32_16x16x32_bf16 v[10:13], v[198:201], v[222:225], v[10:13]
	v_mfma_f32_16x16x32_bf16 v[6:9], v[190:193], v[238:241], v[6:9]
	v_mfma_f32_16x16x32_bf16 v[2:5], v[198:201], v[238:241], v[2:5]
	s_setprio 0
	s_barrier
	s_add_i32 s60, s60, 2
	s_add_u32 s46, s46, 0x100
	s_addc_u32 s47, s47, 0
	s_add_u32 s58, s58, 0x100
	s_addc_u32 s59, s59, 0
	s_cmp_gt_u32 s60, 29
	s_cbranch_scc0 .LBB0_2138
	s_and_b64 vcc, exec, s[28:29]
	s_cbranch_vccz .LBB0_2141
	s_barrier
